# GEMM K-loops: the s_setprio 0/1 flip between the two 16-MFMA groups of each cluster removed (A/B of the compiler's per-cluster flips)
# speedup vs baseline: 1.0034x; 1.0034x over previous
; #define PG8_STAGE(bufoff, gbase, voff) do { _Pragma("unroll") for (int _i = 0; _i < 2; ++_i) \
;         __builtin_amdgcn_global_load_lds((const unsigned*)((const char*)(gbase) + (voff)[_i]), (PG8_LAS unsigned*)(lds + (bufoff) + ldsw + _i * 8192), 16, 0, 0); } while (0)
; #define PG8_LDA(dst, b, h) do { _Pragma("unroll") for (int m = 0; m < 4; ++m) _Pragma("unroll") for (int k = 0; k < 2; ++k) dst[m][k] = *(const PG8_LAS bf16x8*)(lds + PG8_SA(b, h) + aoff + m * 2048 + k * 1024); } while (0)
; #define PG8_LDB(dst, b, h) do { _Pragma("unroll") for (int n = 0; n < 2; ++n) _Pragma("unroll") for (int k = 0; k < 2; ++k) dst[n][k] = *(const PG8_LAS bf16x8*)(lds + PG8_SB(b, h) + boff + n * 2048 + k * 1024); } while (0)
; #define PG8_MMA(ai, bj, At, Bt) do { __builtin_amdgcn_s_setprio(1); _Pragma("unroll") for (int m = 0; m < 4; ++m) _Pragma("unroll") for (int n = 0; n < 2; ++n) _Pragma("unroll") for (int k = 0; k < 2; ++k) \
;         acc[ai][bj][m][n] = __builtin_amdgcn_mfma_f32_16x16x32_bf16(Bt[n][k], At[m][k], acc[ai][bj][m][n], 0, 0, 0); __builtin_amdgcn_s_setprio(0); } while (0)
; #define PG8_BAR __builtin_amdgcn_s_barrier()
; template <class Epi, class Sched, bool ALIGN_EPI = false, bool SP2 = false>
; __device__ __forceinline__ void gemm_phase(PG8_LAS unsigned char* lds, const Gemm g, const Sched& S, const Epi& E) {
;     ...
;         const bool has_next = S.next(ui + 1, nxt);
;         const char* nA = has_next ? (const char*)g.A + (size_t)nxt.pm * tstep : cA; const char* nB = has_next ? (const char*)g.Bt + (size_t)nxt.pn * tstep : cB;
;         for (int t = 0; t < nt; t += 2) {
;             const bool last = (t == nt - 2);
;             const char* a1 = cA + (size_t)(t + 1) * kstep;
;             const char* a2 = last ? nA : cA + (size_t)(t + 2) * kstep; const char* b2 = last ? nB : cB + (size_t)(t + 2) * kstep;
;             const char* a3 = a2 + kstep; const char* b3 = b2 + kstep;
;             if (last && has_next) S.a_ready(nxt);
;             if constexpr (SP2) {
;             PG8_LDB(B0, 0, 0); PG8_LDB(B1, 0, 1); PG8_SCHED; PG8_LDA(At, 0, 0); PG8_STAGE(PG8_SA(1, 1), a1 + hstep, voffA);
;             PG8_WAIT_V(8); PG8_WAIT_L(0); PG8_BAR; PG8_MMA(0, 0, At, B0); PG8_MMA(0, 1, At, B1); PG8_BAR; PG8_SCHED;
;             PG8_LDA(At, 0, 1); PG8_STAGE(PG8_SB(0, 0), b2, voffB); PG8_STAGE(PG8_SB(0, 1), b2 + hstep, voffB); PG8_STAGE(PG8_SA(0, 0), a2, voffA);
.LBB0_188:
	ds_read_b128 v[144:147], v154
	ds_read_b128 v[158:161], v154 offset:1024
	ds_read_b128 v[162:165], v154 offset:2048
	ds_read_b128 v[166:169], v154 offset:3072
	ds_read_b128 v[170:173], v155
	ds_read_b128 v[174:177], v155 offset:1024
	ds_read_b128 v[178:181], v155 offset:2048
	ds_read_b128 v[186:189], v155 offset:3072
	s_add_u32 s44, s36, 0xfffc0080
	s_addc_u32 s45, s37, -1
	s_cmp_eq_u32 s91, 12
	s_cselect_b32 s47, s27, s45
	s_cselect_b32 s46, s87, s44
	s_cselect_b32 s45, s25, s90
	s_cselect_b32 s44, s88, s89
	v_lshl_add_u64 v[182:183], s[36:37], 0, v[136:137]
	s_add_i32 m0, s69, 0xc000
	ds_read_b128 v[190:193], v156
	ds_read_b128 v[194:197], v156 offset:1024
	ds_read_b128 v[198:201], v156 offset:2048
	ds_read_b128 v[202:205], v156 offset:3072
	ds_read_b128 v[206:209], v156 offset:4096
	ds_read_b128 v[210:213], v156 offset:5120
	ds_read_b128 v[214:217], v156 offset:6144
	ds_read_b128 v[218:221], v156 offset:7168
	global_load_lds_dwordx4 v[182:183], off
	v_lshl_add_u64 v[182:183], s[36:37], 0, v[138:139]
	s_add_i32 m0, s69, 0xe000
	s_nop 0
	global_load_lds_dwordx4 v[182:183], off
	s_waitcnt vmcnt(8)
	s_waitcnt lgkmcnt(0)
	s_barrier
	s_setprio 1
	s_waitcnt lgkmcnt(0)
	v_mfma_f32_16x16x32_bf16 v[124:127], v[144:147], v[190:193], v[124:127]
	v_mfma_f32_16x16x32_bf16 v[120:123], v[162:165], v[190:193], v[120:123]
	v_mfma_f32_16x16x32_bf16 v[108:111], v[144:147], v[198:201], v[108:111]
	v_mfma_f32_16x16x32_bf16 v[104:107], v[162:165], v[198:201], v[104:107]
	v_mfma_f32_16x16x32_bf16 v[92:95], v[144:147], v[206:209], v[92:95]
	v_mfma_f32_16x16x32_bf16 v[88:91], v[162:165], v[206:209], v[88:91]
	v_mfma_f32_16x16x32_bf16 v[76:79], v[144:147], v[214:217], v[76:79]
	v_mfma_f32_16x16x32_bf16 v[72:75], v[162:165], v[214:217], v[72:75]
	v_mfma_f32_16x16x32_bf16 v[124:127], v[158:161], v[194:197], v[124:127]
	v_mfma_f32_16x16x32_bf16 v[120:123], v[166:169], v[194:197], v[120:123]
	v_mfma_f32_16x16x32_bf16 v[108:111], v[158:161], v[202:205], v[108:111]
	v_mfma_f32_16x16x32_bf16 v[104:107], v[166:169], v[202:205], v[104:107]
	v_mfma_f32_16x16x32_bf16 v[92:95], v[158:161], v[210:213], v[92:95]
	v_mfma_f32_16x16x32_bf16 v[88:91], v[166:169], v[210:213], v[88:91]
	v_mfma_f32_16x16x32_bf16 v[76:79], v[158:161], v[218:221], v[76:79]
	v_mfma_f32_16x16x32_bf16 v[72:75], v[166:169], v[218:221], v[72:75]
	v_mfma_f32_16x16x32_bf16 v[116:119], v[170:173], v[190:193], v[116:119]
	v_mfma_f32_16x16x32_bf16 v[112:115], v[178:181], v[190:193], v[112:115]
	v_mfma_f32_16x16x32_bf16 v[100:103], v[170:173], v[198:201], v[100:103]
	v_mfma_f32_16x16x32_bf16 v[96:99], v[178:181], v[198:201], v[96:99]
	v_mfma_f32_16x16x32_bf16 v[84:87], v[170:173], v[206:209], v[84:87]
	v_mfma_f32_16x16x32_bf16 v[80:83], v[178:181], v[206:209], v[80:83]
	v_mfma_f32_16x16x32_bf16 v[68:71], v[170:173], v[214:217], v[68:71]
	v_mfma_f32_16x16x32_bf16 v[64:67], v[178:181], v[214:217], v[64:67]
	v_mfma_f32_16x16x32_bf16 v[116:119], v[174:177], v[194:197], v[116:119]
	v_mfma_f32_16x16x32_bf16 v[112:115], v[186:189], v[194:197], v[112:115]
	v_mfma_f32_16x16x32_bf16 v[100:103], v[174:177], v[202:205], v[100:103]
	v_mfma_f32_16x16x32_bf16 v[96:99], v[186:189], v[202:205], v[96:99]
	v_mfma_f32_16x16x32_bf16 v[84:87], v[174:177], v[210:213], v[84:87]
	v_mfma_f32_16x16x32_bf16 v[80:83], v[186:189], v[210:213], v[80:83]
	v_mfma_f32_16x16x32_bf16 v[68:71], v[174:177], v[218:221], v[68:71]
	v_mfma_f32_16x16x32_bf16 v[64:67], v[186:189], v[218:221], v[64:67]
	s_setprio 0
	s_barrier
	s_add_i32 s92, s82, s50
	v_lshl_add_u64 v[182:183], s[44:45], 0, v[132:133]
	s_mov_b32 m0, s92
	ds_read_b128 v[190:193], v156 offset:16384
	ds_read_b128 v[194:197], v156 offset:17408
	ds_read_b128 v[198:201], v156 offset:18432
	ds_read_b128 v[202:205], v156 offset:19456
	ds_read_b128 v[206:209], v156 offset:20480
	ds_read_b128 v[210:213], v156 offset:21504
	ds_read_b128 v[214:217], v156 offset:22528
	ds_read_b128 v[218:221], v156 offset:23552
	global_load_lds_dwordx4 v[182:183], off
	s_add_i32 m0, s92, 0x2000
	s_add_u32 s92, s44, 0x40000
	v_lshl_add_u64 v[222:223], s[44:45], 0, v[128:129]
	s_addc_u32 s93, s45, 0
	s_add_i32 s94, s83, s50
	global_load_lds_dwordx4 v[222:223], off
	v_lshl_add_u64 v[224:225], s[92:93], 0, v[132:133]
	s_mov_b32 m0, s94
	v_lshl_add_u64 v[226:227], s[46:47], 0, v[130:131]
	global_load_lds_dwordx4 v[224:225], off
	v_lshl_add_u64 v[224:225], s[92:93], 0, v[128:129]
	s_add_i32 m0, s94, 0x2000
	s_nop 0
	global_load_lds_dwordx4 v[224:225], off
	v_lshl_add_u64 v[224:225], s[46:47], 0, v[134:135]
	s_mov_b32 m0, s69
	s_nop 0
	global_load_lds_dwordx4 v[224:225], off
	s_mov_b32 m0, s70
	s_nop 0
	global_load_lds_dwordx4 v[226:227], off
	s_waitcnt vmcnt(8)
	s_waitcnt lgkmcnt(0)
	s_barrier
; #define PG8_STAGE(bufoff, gbase, voff) do { _Pragma("unroll") for (int _i = 0; _i < 2; ++_i) \
;         __builtin_amdgcn_global_load_lds((const unsigned*)((const char*)(gbase) + (voff)[_i]), (PG8_LAS unsigned*)(lds + (bufoff) + ldsw + _i * 8192), 16, 0, 0); } while (0)
; #define PG8_LDA(dst, b, h) do { _Pragma("unroll") for (int m = 0; m < 4; ++m) _Pragma("unroll") for (int k = 0; k < 2; ++k) dst[m][k] = *(const PG8_LAS bf16x8*)(lds + PG8_SA(b, h) + aoff + m * 2048 + k * 1024); } while (0)
; #define PG8_LDB(dst, b, h) do { _Pragma("unroll") for (int n = 0; n < 2; ++n) _Pragma("unroll") for (int k = 0; k < 2; ++k) dst[n][k] = *(const PG8_LAS bf16x8*)(lds + PG8_SB(b, h) + boff + n * 2048 + k * 1024); } while (0)
; #define PG8_MMA(ai, bj, At, Bt) do { __builtin_amdgcn_s_setprio(1); _Pragma("unroll") for (int m = 0; m < 4; ++m) _Pragma("unroll") for (int n = 0; n < 2; ++n) _Pragma("unroll") for (int k = 0; k < 2; ++k) \
;         acc[ai][bj][m][n] = __builtin_amdgcn_mfma_f32_16x16x32_bf16(Bt[n][k], At[m][k], acc[ai][bj][m][n], 0, 0, 0); __builtin_amdgcn_s_setprio(0); } while (0)
; #define PG8_WAIT_V(n) asm volatile("s_waitcnt vmcnt(" #n ")" ::: "memory")
; #define PG8_WAIT_L(n) asm volatile("s_waitcnt lgkmcnt(" #n ")" ::: "memory")
; #define PG8_BAR __builtin_amdgcn_s_barrier()
; #define PG8_SCHED __builtin_amdgcn_sched_barrier(0)
; template <class Epi, class Sched, bool ALIGN_EPI = false, bool SP2 = false>
; __device__ __forceinline__ void gemm_phase(PG8_LAS unsigned char* lds, const Gemm g, const Sched& S, const Epi& E) {
;     ...
;             PG8_WAIT_V(8); PG8_WAIT_L(0); PG8_BAR; PG8_MMA(1, 0, At, B0); PG8_MMA(1, 1, At, B1); PG8_BAR; PG8_SCHED;
;             PG8_LDB(B0, 1, 0); PG8_LDB(B1, 1, 1); PG8_SCHED; PG8_LDA(At, 1, 0); PG8_STAGE(PG8_SA(0, 1), a2 + hstep, voffA);
;             PG8_WAIT_V(8); PG8_WAIT_L(0); PG8_BAR; PG8_MMA(0, 0, At, B0); PG8_MMA(0, 1, At, B1); PG8_BAR; PG8_SCHED;
	s_setprio 1
	s_waitcnt lgkmcnt(0)
	v_mfma_f32_16x16x32_bf16 v[60:63], v[144:147], v[190:193], v[60:63]
	v_mfma_f32_16x16x32_bf16 v[56:59], v[162:165], v[190:193], v[56:59]
	v_mfma_f32_16x16x32_bf16 v[44:47], v[144:147], v[198:201], v[44:47]
	v_mfma_f32_16x16x32_bf16 v[40:43], v[162:165], v[198:201], v[40:43]
	v_mfma_f32_16x16x32_bf16 v[28:31], v[144:147], v[206:209], v[28:31]
	v_mfma_f32_16x16x32_bf16 v[24:27], v[162:165], v[206:209], v[24:27]
	v_mfma_f32_16x16x32_bf16 v[12:15], v[144:147], v[214:217], v[12:15]
	v_mfma_f32_16x16x32_bf16 v[8:11], v[162:165], v[214:217], v[8:11]
	v_mfma_f32_16x16x32_bf16 v[60:63], v[158:161], v[194:197], v[60:63]
	v_mfma_f32_16x16x32_bf16 v[56:59], v[166:169], v[194:197], v[56:59]
	v_mfma_f32_16x16x32_bf16 v[44:47], v[158:161], v[202:205], v[44:47]
	v_mfma_f32_16x16x32_bf16 v[40:43], v[166:169], v[202:205], v[40:43]
	v_mfma_f32_16x16x32_bf16 v[28:31], v[158:161], v[210:213], v[28:31]
	v_mfma_f32_16x16x32_bf16 v[24:27], v[166:169], v[210:213], v[24:27]
	v_mfma_f32_16x16x32_bf16 v[12:15], v[158:161], v[218:221], v[12:15]
	v_mfma_f32_16x16x32_bf16 v[8:11], v[166:169], v[218:221], v[8:11]
	v_mfma_f32_16x16x32_bf16 v[52:55], v[170:173], v[190:193], v[52:55]
	v_mfma_f32_16x16x32_bf16 v[48:51], v[178:181], v[190:193], v[48:51]
	v_mfma_f32_16x16x32_bf16 v[36:39], v[170:173], v[198:201], v[36:39]
	v_mfma_f32_16x16x32_bf16 v[32:35], v[178:181], v[198:201], v[32:35]
	v_mfma_f32_16x16x32_bf16 v[20:23], v[170:173], v[206:209], v[20:23]
	v_mfma_f32_16x16x32_bf16 v[16:19], v[178:181], v[206:209], v[16:19]
	v_mfma_f32_16x16x32_bf16 v[4:7], v[170:173], v[214:217], v[4:7]
	v_mfma_f32_16x16x32_bf16 v[0:3], v[178:181], v[214:217], v[0:3]
	v_mfma_f32_16x16x32_bf16 v[52:55], v[174:177], v[194:197], v[52:55]
	v_mfma_f32_16x16x32_bf16 v[48:51], v[186:189], v[194:197], v[48:51]
	v_mfma_f32_16x16x32_bf16 v[36:39], v[174:177], v[202:205], v[36:39]
	v_mfma_f32_16x16x32_bf16 v[32:35], v[186:189], v[202:205], v[32:35]
	v_mfma_f32_16x16x32_bf16 v[20:23], v[174:177], v[210:213], v[20:23]
	v_mfma_f32_16x16x32_bf16 v[16:19], v[186:189], v[210:213], v[16:19]
	v_mfma_f32_16x16x32_bf16 v[4:7], v[174:177], v[218:221], v[4:7]
	v_mfma_f32_16x16x32_bf16 v[0:3], v[186:189], v[218:221], v[0:3]
	s_setprio 0
	s_barrier
	s_add_i32 s92, 0, 0x18000
	v_add_u32_e32 v148, s92, v151
	s_add_i32 s93, 0, 0x1c000
	ds_read_b128 v[144:147], v148
	ds_read_b128 v[158:161], v148 offset:1024
	ds_read_b128 v[162:165], v148 offset:2048
	ds_read_b128 v[166:169], v148 offset:3072
	v_add_u32_e32 v148, s93, v151
	ds_read_b128 v[170:173], v148
	ds_read_b128 v[174:177], v148 offset:1024
	ds_read_b128 v[178:181], v148 offset:2048
	ds_read_b128 v[186:189], v148 offset:3072
	s_add_u32 s46, s46, 0x40000
	s_addc_u32 s47, s47, 0
	s_mov_b32 m0, s71
	v_lshl_add_u64 v[228:229], s[46:47], 0, v[134:135]
	ds_read_b128 v[190:193], v156 offset:32768
	ds_read_b128 v[194:197], v156 offset:33792
	ds_read_b128 v[198:201], v156 offset:34816
	ds_read_b128 v[202:205], v156 offset:35840
	ds_read_b128 v[206:209], v156 offset:36864
	ds_read_b128 v[210:213], v156 offset:37888
	ds_read_b128 v[214:217], v156 offset:38912
	ds_read_b128 v[218:221], v156 offset:39936
	global_load_lds_dwordx4 v[228:229], off
	v_lshl_add_u64 v[228:229], s[46:47], 0, v[130:131]
	s_mov_b32 m0, s72
	s_nop 0
	global_load_lds_dwordx4 v[228:229], off
	s_waitcnt vmcnt(8)
	s_waitcnt lgkmcnt(0)
	s_barrier
	s_setprio 1
	s_waitcnt lgkmcnt(0)
	v_mfma_f32_16x16x32_bf16 v[124:127], v[144:147], v[190:193], v[124:127]
	v_mfma_f32_16x16x32_bf16 v[120:123], v[162:165], v[190:193], v[120:123]
	v_mfma_f32_16x16x32_bf16 v[108:111], v[144:147], v[198:201], v[108:111]
	v_mfma_f32_16x16x32_bf16 v[104:107], v[162:165], v[198:201], v[104:107]
	v_mfma_f32_16x16x32_bf16 v[92:95], v[144:147], v[206:209], v[92:95]
	v_mfma_f32_16x16x32_bf16 v[88:91], v[162:165], v[206:209], v[88:91]
	v_mfma_f32_16x16x32_bf16 v[76:79], v[144:147], v[214:217], v[76:79]
	v_mfma_f32_16x16x32_bf16 v[72:75], v[162:165], v[214:217], v[72:75]
	v_mfma_f32_16x16x32_bf16 v[124:127], v[158:161], v[194:197], v[124:127]
	v_mfma_f32_16x16x32_bf16 v[120:123], v[166:169], v[194:197], v[120:123]
	v_mfma_f32_16x16x32_bf16 v[108:111], v[158:161], v[202:205], v[108:111]
	v_mfma_f32_16x16x32_bf16 v[104:107], v[166:169], v[202:205], v[104:107]
	v_mfma_f32_16x16x32_bf16 v[92:95], v[158:161], v[210:213], v[92:95]
	v_mfma_f32_16x16x32_bf16 v[88:91], v[166:169], v[210:213], v[88:91]
	v_mfma_f32_16x16x32_bf16 v[76:79], v[158:161], v[218:221], v[76:79]
	v_mfma_f32_16x16x32_bf16 v[72:75], v[166:169], v[218:221], v[72:75]
	v_mfma_f32_16x16x32_bf16 v[116:119], v[170:173], v[190:193], v[116:119]
	v_mfma_f32_16x16x32_bf16 v[112:115], v[178:181], v[190:193], v[112:115]
	v_mfma_f32_16x16x32_bf16 v[100:103], v[170:173], v[198:201], v[100:103]
	v_mfma_f32_16x16x32_bf16 v[96:99], v[178:181], v[198:201], v[96:99]
	v_mfma_f32_16x16x32_bf16 v[84:87], v[170:173], v[206:209], v[84:87]
	v_mfma_f32_16x16x32_bf16 v[80:83], v[178:181], v[206:209], v[80:83]
	v_mfma_f32_16x16x32_bf16 v[68:71], v[170:173], v[214:217], v[68:71]
	v_mfma_f32_16x16x32_bf16 v[64:67], v[178:181], v[214:217], v[64:67]
	v_mfma_f32_16x16x32_bf16 v[116:119], v[174:177], v[194:197], v[116:119]
	v_mfma_f32_16x16x32_bf16 v[112:115], v[186:189], v[194:197], v[112:115]
	v_mfma_f32_16x16x32_bf16 v[100:103], v[174:177], v[202:205], v[100:103]
	v_mfma_f32_16x16x32_bf16 v[96:99], v[186:189], v[202:205], v[96:99]
	v_mfma_f32_16x16x32_bf16 v[84:87], v[174:177], v[210:213], v[84:87]
	v_mfma_f32_16x16x32_bf16 v[80:83], v[186:189], v[210:213], v[80:83]
	v_mfma_f32_16x16x32_bf16 v[68:71], v[174:177], v[218:221], v[68:71]
	v_mfma_f32_16x16x32_bf16 v[64:67], v[186:189], v[218:221], v[64:67]
	s_setprio 0
	s_barrier
; #define PG8_STAGE(bufoff, gbase, voff) do { _Pragma("unroll") for (int _i = 0; _i < 2; ++_i) \
;         __builtin_amdgcn_global_load_lds((const unsigned*)((const char*)(gbase) + (voff)[_i]), (PG8_LAS unsigned*)(lds + (bufoff) + ldsw + _i * 8192), 16, 0, 0); } while (0)
; #define PG8_LDA(dst, b, h) do { _Pragma("unroll") for (int m = 0; m < 4; ++m) _Pragma("unroll") for (int k = 0; k < 2; ++k) dst[m][k] = *(const PG8_LAS bf16x8*)(lds + PG8_SA(b, h) + aoff + m * 2048 + k * 1024); } while (0)
; #define PG8_MMA(ai, bj, At, Bt) do { __builtin_amdgcn_s_setprio(1); _Pragma("unroll") for (int m = 0; m < 4; ++m) _Pragma("unroll") for (int n = 0; n < 2; ++n) _Pragma("unroll") for (int k = 0; k < 2; ++k) \
;         acc[ai][bj][m][n] = __builtin_amdgcn_mfma_f32_16x16x32_bf16(Bt[n][k], At[m][k], acc[ai][bj][m][n], 0, 0, 0); __builtin_amdgcn_s_setprio(0); } while (0)
; #define PG8_WAIT_V(n) asm volatile("s_waitcnt vmcnt(" #n ")" ::: "memory")
; #define PG8_WAIT_L(n) asm volatile("s_waitcnt lgkmcnt(" #n ")" ::: "memory")
; #define PG8_BAR __builtin_amdgcn_s_barrier()
; #define PG8_SCHED __builtin_amdgcn_sched_barrier(0)
; template <class Epi, class Sched, bool ALIGN_EPI = false, bool SP2 = false>
; __device__ __forceinline__ void gemm_phase(PG8_LAS unsigned char* lds, const Gemm g, const Sched& S, const Epi& E) {
;     ...
;             PG8_LDA(At, 1, 1); PG8_STAGE(PG8_SB(1, 0), b3, voffB); PG8_STAGE(PG8_SB(1, 1), b3 + hstep, voffB); PG8_STAGE(PG8_SA(1, 0), a3, voffA);
;             PG8_WAIT_V(8); PG8_WAIT_L(0); PG8_BAR; PG8_MMA(1, 0, At, B0); PG8_MMA(1, 1, At, B1); PG8_BAR; PG8_SCHED;
;     ...
;         if constexpr (ALIGN_EPI) { if (wr == 0) PG8_BAR; }
	s_add_i32 s46, s92, s50
	v_lshl_add_u64 v[182:183], v[182:183], 0, s[20:21]
	s_mov_b32 m0, s46
	ds_read_b128 v[190:193], v156 offset:49152
	ds_read_b128 v[194:197], v156 offset:50176
	ds_read_b128 v[198:201], v156 offset:51200
	ds_read_b128 v[202:205], v156 offset:52224
	ds_read_b128 v[206:209], v156 offset:53248
	ds_read_b128 v[210:213], v156 offset:54272
	ds_read_b128 v[214:217], v156 offset:55296
	ds_read_b128 v[218:221], v156 offset:56320
	global_load_lds_dwordx4 v[182:183], off
	s_add_i32 m0, s46, 0x2000
	s_add_u32 s44, s44, 0x40080
	v_lshl_add_u64 v[182:183], v[222:223], 0, s[20:21]
	s_addc_u32 s45, s45, 0
	s_add_i32 s46, s93, s50
	global_load_lds_dwordx4 v[182:183], off
	v_lshl_add_u64 v[182:183], s[44:45], 0, v[132:133]
	s_mov_b32 m0, s46
	s_nop 0
	global_load_lds_dwordx4 v[182:183], off
	v_lshl_add_u64 v[182:183], s[44:45], 0, v[128:129]
	s_add_i32 m0, s46, 0x2000
	s_nop 0
	global_load_lds_dwordx4 v[182:183], off
	v_lshl_add_u64 v[182:183], v[224:225], 0, s[20:21]
	s_mov_b32 m0, s78
	s_nop 0
	global_load_lds_dwordx4 v[182:183], off
	v_lshl_add_u64 v[182:183], v[226:227], 0, s[20:21]
	s_mov_b32 m0, s79
	s_nop 0
	global_load_lds_dwordx4 v[182:183], off
	s_waitcnt vmcnt(8)
	s_waitcnt lgkmcnt(0)
	s_barrier
	s_setprio 1
	s_waitcnt lgkmcnt(0)
	v_mfma_f32_16x16x32_bf16 v[60:63], v[144:147], v[190:193], v[60:63]
	v_mfma_f32_16x16x32_bf16 v[56:59], v[162:165], v[190:193], v[56:59]
	v_mfma_f32_16x16x32_bf16 v[44:47], v[144:147], v[198:201], v[44:47]
	v_mfma_f32_16x16x32_bf16 v[40:43], v[162:165], v[198:201], v[40:43]
	v_mfma_f32_16x16x32_bf16 v[28:31], v[144:147], v[206:209], v[28:31]
	v_mfma_f32_16x16x32_bf16 v[24:27], v[162:165], v[206:209], v[24:27]
	v_mfma_f32_16x16x32_bf16 v[12:15], v[144:147], v[214:217], v[12:15]
	v_mfma_f32_16x16x32_bf16 v[8:11], v[162:165], v[214:217], v[8:11]
	v_mfma_f32_16x16x32_bf16 v[60:63], v[158:161], v[194:197], v[60:63]
	v_mfma_f32_16x16x32_bf16 v[56:59], v[166:169], v[194:197], v[56:59]
	v_mfma_f32_16x16x32_bf16 v[44:47], v[158:161], v[202:205], v[44:47]
	v_mfma_f32_16x16x32_bf16 v[40:43], v[166:169], v[202:205], v[40:43]
	v_mfma_f32_16x16x32_bf16 v[28:31], v[158:161], v[210:213], v[28:31]
	v_mfma_f32_16x16x32_bf16 v[24:27], v[166:169], v[210:213], v[24:27]
	v_mfma_f32_16x16x32_bf16 v[12:15], v[158:161], v[218:221], v[12:15]
	v_mfma_f32_16x16x32_bf16 v[8:11], v[166:169], v[218:221], v[8:11]
	v_mfma_f32_16x16x32_bf16 v[52:55], v[170:173], v[190:193], v[52:55]
	v_mfma_f32_16x16x32_bf16 v[48:51], v[178:181], v[190:193], v[48:51]
	v_mfma_f32_16x16x32_bf16 v[36:39], v[170:173], v[198:201], v[36:39]
	v_mfma_f32_16x16x32_bf16 v[32:35], v[178:181], v[198:201], v[32:35]
	v_mfma_f32_16x16x32_bf16 v[20:23], v[170:173], v[206:209], v[20:23]
	v_mfma_f32_16x16x32_bf16 v[16:19], v[178:181], v[206:209], v[16:19]
	v_mfma_f32_16x16x32_bf16 v[4:7], v[170:173], v[214:217], v[4:7]
	v_mfma_f32_16x16x32_bf16 v[0:3], v[178:181], v[214:217], v[0:3]
	v_mfma_f32_16x16x32_bf16 v[52:55], v[174:177], v[194:197], v[52:55]
	v_mfma_f32_16x16x32_bf16 v[48:51], v[186:189], v[194:197], v[48:51]
	v_mfma_f32_16x16x32_bf16 v[36:39], v[174:177], v[202:205], v[36:39]
	v_mfma_f32_16x16x32_bf16 v[32:35], v[186:189], v[202:205], v[32:35]
	v_mfma_f32_16x16x32_bf16 v[20:23], v[174:177], v[210:213], v[20:23]
	v_mfma_f32_16x16x32_bf16 v[16:19], v[186:189], v[210:213], v[16:19]
	v_mfma_f32_16x16x32_bf16 v[4:7], v[174:177], v[218:221], v[4:7]
	v_mfma_f32_16x16x32_bf16 v[0:3], v[186:189], v[218:221], v[0:3]
	s_setprio 0
	s_barrier
	s_add_i32 s91, s91, 2
	s_add_u32 s36, s36, 0x100
	s_addc_u32 s37, s37, 0
	s_add_u32 s89, s89, 0x100
	s_addc_u32 s90, s90, 0
	s_cmp_gt_u32 s91, 13
	s_cbranch_scc0 .LBB0_188
	s_and_b64 vcc, exec, s[22:23]
	s_cbranch_vccz .LBB0_191
	s_barrier

; #define PG8_STAGE(bufoff, gbase, voff) do { _Pragma("unroll") for (int _i = 0; _i < 2; ++_i) \
;         __builtin_amdgcn_global_load_lds((const unsigned*)((const char*)(gbase) + (voff)[_i]), (PG8_LAS unsigned*)(lds + (bufoff) + ldsw + _i * 8192), 16, 0, 0); } while (0)
; #define PG8_LDA(dst, b, h) do { _Pragma("unroll") for (int m = 0; m < 4; ++m) _Pragma("unroll") for (int k = 0; k < 2; ++k) dst[m][k] = *(const PG8_LAS bf16x8*)(lds + PG8_SA(b, h) + aoff + m * 2048 + k * 1024); } while (0)
; #define PG8_LDB(dst, b, h) do { _Pragma("unroll") for (int n = 0; n < 2; ++n) _Pragma("unroll") for (int k = 0; k < 2; ++k) dst[n][k] = *(const PG8_LAS bf16x8*)(lds + PG8_SB(b, h) + boff + n * 2048 + k * 1024); } while (0)
; #define PG8_MMA(ai, bj, At, Bt) do { __builtin_amdgcn_s_setprio(1); _Pragma("unroll") for (int m = 0; m < 4; ++m) _Pragma("unroll") for (int n = 0; n < 2; ++n) _Pragma("unroll") for (int k = 0; k < 2; ++k) \
;         acc[ai][bj][m][n] = __builtin_amdgcn_mfma_f32_16x16x32_bf16(Bt[n][k], At[m][k], acc[ai][bj][m][n], 0, 0, 0); __builtin_amdgcn_s_setprio(0); } while (0)
; #define PG8_BAR __builtin_amdgcn_s_barrier()
; template <class Epi, class Sched, bool ALIGN_EPI = false, bool SP2 = false>
; __device__ __forceinline__ void gemm_phase(PG8_LAS unsigned char* lds, const Gemm g, const Sched& S, const Epi& E) {
;     ...
;         const bool has_next = S.next(ui + 1, nxt);
;         const char* nA = has_next ? (const char*)g.A + (size_t)nxt.pm * tstep : cA; const char* nB = has_next ? (const char*)g.Bt + (size_t)nxt.pn * tstep : cB;
;         for (int t = 0; t < nt; t += 2) {
;             const bool last = (t == nt - 2);
;             const char* a1 = cA + (size_t)(t + 1) * kstep;
;             const char* a2 = last ? nA : cA + (size_t)(t + 2) * kstep; const char* b2 = last ? nB : cB + (size_t)(t + 2) * kstep;
;             const char* a3 = a2 + kstep; const char* b3 = b2 + kstep;
;             if (last && has_next) S.a_ready(nxt);
;             if constexpr (SP2) {
;             PG8_LDB(B0, 0, 0); PG8_LDB(B1, 0, 1); PG8_SCHED; PG8_LDA(At, 0, 0); PG8_STAGE(PG8_SA(1, 1), a1 + hstep, voffA);
;             PG8_WAIT_V(8); PG8_WAIT_L(0); PG8_BAR; PG8_MMA(0, 0, At, B0); PG8_MMA(0, 1, At, B1); PG8_BAR; PG8_SCHED;
;             PG8_LDA(At, 0, 1); PG8_STAGE(PG8_SB(0, 0), b2, voffB); PG8_STAGE(PG8_SB(0, 1), b2 + hstep, voffB); PG8_STAGE(PG8_SA(0, 0), a2, voffA);
.LBB0_404:
	ds_read_b128 v[100:103], v223
	ds_read_b128 v[108:111], v223 offset:1024
	ds_read_b128 v[120:123], v223 offset:2048
	ds_read_b128 v[132:135], v223 offset:3072
	ds_read_b128 v[144:147], v224
	ds_read_b128 v[148:151], v224 offset:1024
	ds_read_b128 v[152:155], v224 offset:2048
	ds_read_b128 v[156:159], v224 offset:3072
	s_add_u32 s20, s18, 0xfffb0080
	s_addc_u32 s21, s19, -1
	s_cmp_eq_u32 s58, 16
	s_cselect_b32 s23, s7, s21
	s_cselect_b32 s22, s6, s20
	s_cselect_b32 s21, s9, s51
	s_cselect_b32 s20, s8, s50
	v_lshl_add_u64 v[212:213], s[18:19], 0, v[196:197]
	s_add_i32 m0, s30, 0xc000
	ds_read_b128 v[160:163], v225
	ds_read_b128 v[164:167], v225 offset:1024
	ds_read_b128 v[168:171], v225 offset:2048
	ds_read_b128 v[172:175], v225 offset:3072
	ds_read_b128 v[176:179], v225 offset:4096
	ds_read_b128 v[180:183], v225 offset:5120
	ds_read_b128 v[204:207], v225 offset:6144
	ds_read_b128 v[208:211], v225 offset:7168
	global_load_lds_dwordx4 v[212:213], off
	v_lshl_add_u64 v[212:213], s[18:19], 0, v[198:199]
	s_add_i32 m0, s30, 0xe000
	s_nop 0
	global_load_lds_dwordx4 v[212:213], off
	s_waitcnt vmcnt(8)
	s_waitcnt lgkmcnt(0)
	s_barrier
	s_setprio 1
	s_waitcnt lgkmcnt(0)
	v_mfma_f32_16x16x32_bf16 v[140:143], v[100:103], v[160:163], v[140:143]
	v_mfma_f32_16x16x32_bf16 v[136:139], v[120:123], v[160:163], v[136:139]
	v_mfma_f32_16x16x32_bf16 v[116:119], v[100:103], v[168:171], v[116:119]
	v_mfma_f32_16x16x32_bf16 v[112:115], v[120:123], v[168:171], v[112:115]
	v_mfma_f32_16x16x32_bf16 v[92:95], v[100:103], v[176:179], v[92:95]
	v_mfma_f32_16x16x32_bf16 v[88:91], v[120:123], v[176:179], v[88:91]
	v_mfma_f32_16x16x32_bf16 v[76:79], v[100:103], v[204:207], v[76:79]
	v_mfma_f32_16x16x32_bf16 v[72:75], v[120:123], v[204:207], v[72:75]
	v_mfma_f32_16x16x32_bf16 v[140:143], v[108:111], v[164:167], v[140:143]
	v_mfma_f32_16x16x32_bf16 v[136:139], v[132:135], v[164:167], v[136:139]
	v_mfma_f32_16x16x32_bf16 v[116:119], v[108:111], v[172:175], v[116:119]
	v_mfma_f32_16x16x32_bf16 v[112:115], v[132:135], v[172:175], v[112:115]
	v_mfma_f32_16x16x32_bf16 v[92:95], v[108:111], v[180:183], v[92:95]
	v_mfma_f32_16x16x32_bf16 v[88:91], v[132:135], v[180:183], v[88:91]
	v_mfma_f32_16x16x32_bf16 v[76:79], v[108:111], v[208:211], v[76:79]
	v_mfma_f32_16x16x32_bf16 v[72:75], v[132:135], v[208:211], v[72:75]
	v_mfma_f32_16x16x32_bf16 v[128:131], v[144:147], v[160:163], v[128:131]
	v_mfma_f32_16x16x32_bf16 v[124:127], v[152:155], v[160:163], v[124:127]
	v_mfma_f32_16x16x32_bf16 v[104:107], v[144:147], v[168:171], v[104:107]
	v_mfma_f32_16x16x32_bf16 v[96:99], v[152:155], v[168:171], v[96:99]
	v_mfma_f32_16x16x32_bf16 v[84:87], v[144:147], v[176:179], v[84:87]
	v_mfma_f32_16x16x32_bf16 v[80:83], v[152:155], v[176:179], v[80:83]
	v_mfma_f32_16x16x32_bf16 v[68:71], v[144:147], v[204:207], v[68:71]
	v_mfma_f32_16x16x32_bf16 v[64:67], v[152:155], v[204:207], v[64:67]
	v_mfma_f32_16x16x32_bf16 v[128:131], v[148:151], v[164:167], v[128:131]
	v_mfma_f32_16x16x32_bf16 v[124:127], v[156:159], v[164:167], v[124:127]
	v_mfma_f32_16x16x32_bf16 v[104:107], v[148:151], v[172:175], v[104:107]
	v_mfma_f32_16x16x32_bf16 v[96:99], v[156:159], v[172:175], v[96:99]
	v_mfma_f32_16x16x32_bf16 v[84:87], v[148:151], v[180:183], v[84:87]
	v_mfma_f32_16x16x32_bf16 v[80:83], v[156:159], v[180:183], v[80:83]
	v_mfma_f32_16x16x32_bf16 v[68:71], v[148:151], v[208:211], v[68:71]
	v_mfma_f32_16x16x32_bf16 v[64:67], v[156:159], v[208:211], v[64:67]
	s_setprio 0
	s_barrier
	s_add_i32 s69, s44, s29
	v_lshl_add_u64 v[212:213], s[20:21], 0, v[190:191]
	s_mov_b32 m0, s69
	ds_read_b128 v[160:163], v225 offset:16384
	ds_read_b128 v[164:167], v225 offset:17408
	ds_read_b128 v[168:171], v225 offset:18432
	ds_read_b128 v[172:175], v225 offset:19456
	ds_read_b128 v[176:179], v225 offset:20480
	ds_read_b128 v[180:183], v225 offset:21504
	ds_read_b128 v[204:207], v225 offset:22528
	ds_read_b128 v[208:211], v225 offset:23552
	global_load_lds_dwordx4 v[212:213], off
	s_add_i32 m0, s69, 0x2000
	s_add_u32 s70, s20, 0x50000
	v_lshl_add_u64 v[214:215], s[20:21], 0, v[194:195]
	s_addc_u32 s71, s21, 0
	s_add_i32 s69, s45, s29
	global_load_lds_dwordx4 v[214:215], off
	v_lshl_add_u64 v[216:217], s[70:71], 0, v[190:191]
	s_mov_b32 m0, s69
	v_lshl_add_u64 v[218:219], s[22:23], 0, v[192:193]
	global_load_lds_dwordx4 v[216:217], off
	v_lshl_add_u64 v[216:217], s[70:71], 0, v[194:195]
	s_add_i32 m0, s69, 0x2000
	s_nop 0
	global_load_lds_dwordx4 v[216:217], off
	v_lshl_add_u64 v[216:217], s[22:23], 0, v[188:189]
	s_mov_b32 m0, s30
	s_nop 0
	global_load_lds_dwordx4 v[216:217], off
	s_mov_b32 m0, s31
	s_nop 0
	global_load_lds_dwordx4 v[218:219], off
	s_waitcnt vmcnt(8)
	s_waitcnt lgkmcnt(0)
	s_barrier
; #define PG8_STAGE(bufoff, gbase, voff) do { _Pragma("unroll") for (int _i = 0; _i < 2; ++_i) \
;         __builtin_amdgcn_global_load_lds((const unsigned*)((const char*)(gbase) + (voff)[_i]), (PG8_LAS unsigned*)(lds + (bufoff) + ldsw + _i * 8192), 16, 0, 0); } while (0)
; #define PG8_LDA(dst, b, h) do { _Pragma("unroll") for (int m = 0; m < 4; ++m) _Pragma("unroll") for (int k = 0; k < 2; ++k) dst[m][k] = *(const PG8_LAS bf16x8*)(lds + PG8_SA(b, h) + aoff + m * 2048 + k * 1024); } while (0)
; #define PG8_LDB(dst, b, h) do { _Pragma("unroll") for (int n = 0; n < 2; ++n) _Pragma("unroll") for (int k = 0; k < 2; ++k) dst[n][k] = *(const PG8_LAS bf16x8*)(lds + PG8_SB(b, h) + boff + n * 2048 + k * 1024); } while (0)
; #define PG8_MMA(ai, bj, At, Bt) do { __builtin_amdgcn_s_setprio(1); _Pragma("unroll") for (int m = 0; m < 4; ++m) _Pragma("unroll") for (int n = 0; n < 2; ++n) _Pragma("unroll") for (int k = 0; k < 2; ++k) \
;         acc[ai][bj][m][n] = __builtin_amdgcn_mfma_f32_16x16x32_bf16(Bt[n][k], At[m][k], acc[ai][bj][m][n], 0, 0, 0); __builtin_amdgcn_s_setprio(0); } while (0)
; #define PG8_WAIT_V(n) asm volatile("s_waitcnt vmcnt(" #n ")" ::: "memory")
; #define PG8_WAIT_L(n) asm volatile("s_waitcnt lgkmcnt(" #n ")" ::: "memory")
; #define PG8_BAR __builtin_amdgcn_s_barrier()
; #define PG8_SCHED __builtin_amdgcn_sched_barrier(0)
; template <class Epi, class Sched, bool ALIGN_EPI = false, bool SP2 = false>
; __device__ __forceinline__ void gemm_phase(PG8_LAS unsigned char* lds, const Gemm g, const Sched& S, const Epi& E) {
;     ...
;             PG8_WAIT_V(8); PG8_WAIT_L(0); PG8_BAR; PG8_MMA(1, 0, At, B0); PG8_MMA(1, 1, At, B1); PG8_BAR; PG8_SCHED;
;             PG8_LDB(B0, 1, 0); PG8_LDB(B1, 1, 1); PG8_SCHED; PG8_LDA(At, 1, 0); PG8_STAGE(PG8_SA(0, 1), a2 + hstep, voffA);
;             PG8_WAIT_V(8); PG8_WAIT_L(0); PG8_BAR; PG8_MMA(0, 0, At, B0); PG8_MMA(0, 1, At, B1); PG8_BAR; PG8_SCHED;
	s_setprio 1
	s_waitcnt lgkmcnt(0)
	v_mfma_f32_16x16x32_bf16 v[60:63], v[100:103], v[160:163], v[60:63]
	v_mfma_f32_16x16x32_bf16 v[56:59], v[120:123], v[160:163], v[56:59]
	v_mfma_f32_16x16x32_bf16 v[44:47], v[100:103], v[168:171], v[44:47]
	v_mfma_f32_16x16x32_bf16 v[40:43], v[120:123], v[168:171], v[40:43]
	v_mfma_f32_16x16x32_bf16 v[28:31], v[100:103], v[176:179], v[28:31]
	v_mfma_f32_16x16x32_bf16 v[24:27], v[120:123], v[176:179], v[24:27]
	v_mfma_f32_16x16x32_bf16 v[12:15], v[100:103], v[204:207], v[12:15]
	v_mfma_f32_16x16x32_bf16 v[8:11], v[120:123], v[204:207], v[8:11]
	v_mfma_f32_16x16x32_bf16 v[60:63], v[108:111], v[164:167], v[60:63]
	v_mfma_f32_16x16x32_bf16 v[56:59], v[132:135], v[164:167], v[56:59]
	v_mfma_f32_16x16x32_bf16 v[44:47], v[108:111], v[172:175], v[44:47]
	v_mfma_f32_16x16x32_bf16 v[40:43], v[132:135], v[172:175], v[40:43]
	v_mfma_f32_16x16x32_bf16 v[28:31], v[108:111], v[180:183], v[28:31]
	v_mfma_f32_16x16x32_bf16 v[24:27], v[132:135], v[180:183], v[24:27]
	v_mfma_f32_16x16x32_bf16 v[12:15], v[108:111], v[208:211], v[12:15]
	v_mfma_f32_16x16x32_bf16 v[8:11], v[132:135], v[208:211], v[8:11]
	v_mfma_f32_16x16x32_bf16 v[52:55], v[144:147], v[160:163], v[52:55]
	v_mfma_f32_16x16x32_bf16 v[48:51], v[152:155], v[160:163], v[48:51]
	v_mfma_f32_16x16x32_bf16 v[36:39], v[144:147], v[168:171], v[36:39]
	v_mfma_f32_16x16x32_bf16 v[32:35], v[152:155], v[168:171], v[32:35]
	v_mfma_f32_16x16x32_bf16 v[20:23], v[144:147], v[176:179], v[20:23]
	v_mfma_f32_16x16x32_bf16 v[16:19], v[152:155], v[176:179], v[16:19]
	v_mfma_f32_16x16x32_bf16 v[4:7], v[144:147], v[204:207], v[4:7]
	v_mfma_f32_16x16x32_bf16 v[0:3], v[152:155], v[204:207], v[0:3]
	v_mfma_f32_16x16x32_bf16 v[52:55], v[148:151], v[164:167], v[52:55]
	v_mfma_f32_16x16x32_bf16 v[48:51], v[156:159], v[164:167], v[48:51]
	v_mfma_f32_16x16x32_bf16 v[36:39], v[148:151], v[172:175], v[36:39]
	v_mfma_f32_16x16x32_bf16 v[32:35], v[156:159], v[172:175], v[32:35]
	v_mfma_f32_16x16x32_bf16 v[20:23], v[148:151], v[180:183], v[20:23]
	v_mfma_f32_16x16x32_bf16 v[16:19], v[156:159], v[180:183], v[16:19]
	v_mfma_f32_16x16x32_bf16 v[4:7], v[148:151], v[208:211], v[4:7]
	v_mfma_f32_16x16x32_bf16 v[0:3], v[156:159], v[208:211], v[0:3]
	s_setprio 0
	s_barrier
	s_add_i32 s69, 0, 0x18000
	s_add_i32 s70, 0, 0x1c000
	v_add_u32_e32 v132, s69, v187
	v_add_u32_e32 v156, s70, v187
	ds_read_b128 v[100:103], v132
	ds_read_b128 v[108:111], v132 offset:1024
	ds_read_b128 v[120:123], v132 offset:2048
	ds_read_b128 v[132:135], v132 offset:3072
	ds_read_b128 v[144:147], v156
	ds_read_b128 v[148:151], v156 offset:1024
	ds_read_b128 v[152:155], v156 offset:2048
	ds_read_b128 v[156:159], v156 offset:3072
	s_add_u32 s22, s22, 0x50000
	s_addc_u32 s23, s23, 0
	s_mov_b32 m0, s34
	v_lshl_add_u64 v[220:221], s[22:23], 0, v[188:189]
	ds_read_b128 v[160:163], v225 offset:32768
	ds_read_b128 v[164:167], v225 offset:33792
	ds_read_b128 v[168:171], v225 offset:34816
	ds_read_b128 v[172:175], v225 offset:35840
	ds_read_b128 v[176:179], v225 offset:36864
	ds_read_b128 v[180:183], v225 offset:37888
	ds_read_b128 v[204:207], v225 offset:38912
	ds_read_b128 v[208:211], v225 offset:39936
	global_load_lds_dwordx4 v[220:221], off
	v_lshl_add_u64 v[220:221], s[22:23], 0, v[192:193]
	s_mov_b32 m0, s35
	s_nop 0
	global_load_lds_dwordx4 v[220:221], off
	s_waitcnt vmcnt(8)
	s_waitcnt lgkmcnt(0)
	s_barrier
	s_setprio 1
	s_waitcnt lgkmcnt(0)
	v_mfma_f32_16x16x32_bf16 v[140:143], v[100:103], v[160:163], v[140:143]
	v_mfma_f32_16x16x32_bf16 v[136:139], v[120:123], v[160:163], v[136:139]
	v_mfma_f32_16x16x32_bf16 v[116:119], v[100:103], v[168:171], v[116:119]
	v_mfma_f32_16x16x32_bf16 v[112:115], v[120:123], v[168:171], v[112:115]
	v_mfma_f32_16x16x32_bf16 v[92:95], v[100:103], v[176:179], v[92:95]
	v_mfma_f32_16x16x32_bf16 v[88:91], v[120:123], v[176:179], v[88:91]
	v_mfma_f32_16x16x32_bf16 v[76:79], v[100:103], v[204:207], v[76:79]
	v_mfma_f32_16x16x32_bf16 v[72:75], v[120:123], v[204:207], v[72:75]
	v_mfma_f32_16x16x32_bf16 v[140:143], v[108:111], v[164:167], v[140:143]
	v_mfma_f32_16x16x32_bf16 v[136:139], v[132:135], v[164:167], v[136:139]
	v_mfma_f32_16x16x32_bf16 v[116:119], v[108:111], v[172:175], v[116:119]
	v_mfma_f32_16x16x32_bf16 v[112:115], v[132:135], v[172:175], v[112:115]
	v_mfma_f32_16x16x32_bf16 v[92:95], v[108:111], v[180:183], v[92:95]
	v_mfma_f32_16x16x32_bf16 v[88:91], v[132:135], v[180:183], v[88:91]
	v_mfma_f32_16x16x32_bf16 v[76:79], v[108:111], v[208:211], v[76:79]
	v_mfma_f32_16x16x32_bf16 v[72:75], v[132:135], v[208:211], v[72:75]
	v_mfma_f32_16x16x32_bf16 v[128:131], v[144:147], v[160:163], v[128:131]
	v_mfma_f32_16x16x32_bf16 v[124:127], v[152:155], v[160:163], v[124:127]
	v_mfma_f32_16x16x32_bf16 v[104:107], v[144:147], v[168:171], v[104:107]
	v_mfma_f32_16x16x32_bf16 v[96:99], v[152:155], v[168:171], v[96:99]
	v_mfma_f32_16x16x32_bf16 v[84:87], v[144:147], v[176:179], v[84:87]
	v_mfma_f32_16x16x32_bf16 v[80:83], v[152:155], v[176:179], v[80:83]
	v_mfma_f32_16x16x32_bf16 v[68:71], v[144:147], v[204:207], v[68:71]
	v_mfma_f32_16x16x32_bf16 v[64:67], v[152:155], v[204:207], v[64:67]
	v_mfma_f32_16x16x32_bf16 v[128:131], v[148:151], v[164:167], v[128:131]
	v_mfma_f32_16x16x32_bf16 v[124:127], v[156:159], v[164:167], v[124:127]
	v_mfma_f32_16x16x32_bf16 v[104:107], v[148:151], v[172:175], v[104:107]
	v_mfma_f32_16x16x32_bf16 v[96:99], v[156:159], v[172:175], v[96:99]
	v_mfma_f32_16x16x32_bf16 v[84:87], v[148:151], v[180:183], v[84:87]
	v_mfma_f32_16x16x32_bf16 v[80:83], v[156:159], v[180:183], v[80:83]
	v_mfma_f32_16x16x32_bf16 v[68:71], v[148:151], v[208:211], v[68:71]
	v_mfma_f32_16x16x32_bf16 v[64:67], v[156:159], v[208:211], v[64:67]
	s_setprio 0
	s_barrier
; #define PG8_STAGE(bufoff, gbase, voff) do { _Pragma("unroll") for (int _i = 0; _i < 2; ++_i) \
;         __builtin_amdgcn_global_load_lds((const unsigned*)((const char*)(gbase) + (voff)[_i]), (PG8_LAS unsigned*)(lds + (bufoff) + ldsw + _i * 8192), 16, 0, 0); } while (0)
; #define PG8_LDA(dst, b, h) do { _Pragma("unroll") for (int m = 0; m < 4; ++m) _Pragma("unroll") for (int k = 0; k < 2; ++k) dst[m][k] = *(const PG8_LAS bf16x8*)(lds + PG8_SA(b, h) + aoff + m * 2048 + k * 1024); } while (0)
; #define PG8_MMA(ai, bj, At, Bt) do { __builtin_amdgcn_s_setprio(1); _Pragma("unroll") for (int m = 0; m < 4; ++m) _Pragma("unroll") for (int n = 0; n < 2; ++n) _Pragma("unroll") for (int k = 0; k < 2; ++k) \
;         acc[ai][bj][m][n] = __builtin_amdgcn_mfma_f32_16x16x32_bf16(Bt[n][k], At[m][k], acc[ai][bj][m][n], 0, 0, 0); __builtin_amdgcn_s_setprio(0); } while (0)
; #define PG8_WAIT_V(n) asm volatile("s_waitcnt vmcnt(" #n ")" ::: "memory")
; #define PG8_WAIT_L(n) asm volatile("s_waitcnt lgkmcnt(" #n ")" ::: "memory")
; #define PG8_BAR __builtin_amdgcn_s_barrier()
; #define PG8_SCHED __builtin_amdgcn_sched_barrier(0)
; template <class Epi, class Sched, bool ALIGN_EPI = false, bool SP2 = false>
; __device__ __forceinline__ void gemm_phase(PG8_LAS unsigned char* lds, const Gemm g, const Sched& S, const Epi& E) {
;     ...
;             PG8_LDA(At, 1, 1); PG8_STAGE(PG8_SB(1, 0), b3, voffB); PG8_STAGE(PG8_SB(1, 1), b3 + hstep, voffB); PG8_STAGE(PG8_SA(1, 0), a3, voffA);
;             PG8_WAIT_V(8); PG8_WAIT_L(0); PG8_BAR; PG8_MMA(1, 0, At, B0); PG8_MMA(1, 1, At, B1); PG8_BAR; PG8_SCHED;
	s_add_i32 s22, s69, s29
	v_lshl_add_u64 v[212:213], v[212:213], 0, s[16:17]
	s_mov_b32 m0, s22
	ds_read_b128 v[160:163], v225 offset:49152
	ds_read_b128 v[164:167], v225 offset:50176
	ds_read_b128 v[168:171], v225 offset:51200
	ds_read_b128 v[172:175], v225 offset:52224
	ds_read_b128 v[176:179], v225 offset:53248
	ds_read_b128 v[180:183], v225 offset:54272
	ds_read_b128 v[204:207], v225 offset:55296
	ds_read_b128 v[208:211], v225 offset:56320
	global_load_lds_dwordx4 v[212:213], off
	s_add_i32 m0, s22, 0x2000
	s_add_u32 s20, s20, 0x50080
	v_lshl_add_u64 v[212:213], v[214:215], 0, s[16:17]
	s_addc_u32 s21, s21, 0
	s_add_i32 s22, s70, s29
	global_load_lds_dwordx4 v[212:213], off
	v_lshl_add_u64 v[212:213], s[20:21], 0, v[190:191]
	s_mov_b32 m0, s22
	s_nop 0
	global_load_lds_dwordx4 v[212:213], off
	v_lshl_add_u64 v[212:213], s[20:21], 0, v[194:195]
	s_add_i32 m0, s22, 0x2000
	s_nop 0
	global_load_lds_dwordx4 v[212:213], off
	v_lshl_add_u64 v[212:213], v[216:217], 0, s[16:17]
	s_mov_b32 m0, s37
	s_nop 0
	global_load_lds_dwordx4 v[212:213], off
	v_lshl_add_u64 v[212:213], v[218:219], 0, s[16:17]
	s_mov_b32 m0, s38
	s_nop 0
	global_load_lds_dwordx4 v[212:213], off
	s_waitcnt vmcnt(8)
	s_waitcnt lgkmcnt(0)
	s_barrier
	s_setprio 1
	s_waitcnt lgkmcnt(0)
	v_mfma_f32_16x16x32_bf16 v[60:63], v[100:103], v[160:163], v[60:63]
	v_mfma_f32_16x16x32_bf16 v[56:59], v[120:123], v[160:163], v[56:59]
	v_mfma_f32_16x16x32_bf16 v[44:47], v[100:103], v[168:171], v[44:47]
	v_mfma_f32_16x16x32_bf16 v[40:43], v[120:123], v[168:171], v[40:43]
	v_mfma_f32_16x16x32_bf16 v[28:31], v[100:103], v[176:179], v[28:31]
	v_mfma_f32_16x16x32_bf16 v[24:27], v[120:123], v[176:179], v[24:27]
	v_mfma_f32_16x16x32_bf16 v[12:15], v[100:103], v[204:207], v[12:15]
	v_mfma_f32_16x16x32_bf16 v[8:11], v[120:123], v[204:207], v[8:11]
	v_mfma_f32_16x16x32_bf16 v[60:63], v[108:111], v[164:167], v[60:63]
	v_mfma_f32_16x16x32_bf16 v[56:59], v[132:135], v[164:167], v[56:59]
	v_mfma_f32_16x16x32_bf16 v[44:47], v[108:111], v[172:175], v[44:47]
	v_mfma_f32_16x16x32_bf16 v[40:43], v[132:135], v[172:175], v[40:43]
	v_mfma_f32_16x16x32_bf16 v[28:31], v[108:111], v[180:183], v[28:31]
	v_mfma_f32_16x16x32_bf16 v[24:27], v[132:135], v[180:183], v[24:27]
	v_mfma_f32_16x16x32_bf16 v[12:15], v[108:111], v[208:211], v[12:15]
	v_mfma_f32_16x16x32_bf16 v[8:11], v[132:135], v[208:211], v[8:11]
	v_mfma_f32_16x16x32_bf16 v[52:55], v[144:147], v[160:163], v[52:55]
	v_mfma_f32_16x16x32_bf16 v[48:51], v[152:155], v[160:163], v[48:51]
	v_mfma_f32_16x16x32_bf16 v[36:39], v[144:147], v[168:171], v[36:39]
	v_mfma_f32_16x16x32_bf16 v[32:35], v[152:155], v[168:171], v[32:35]
	v_mfma_f32_16x16x32_bf16 v[20:23], v[144:147], v[176:179], v[20:23]
	v_mfma_f32_16x16x32_bf16 v[16:19], v[152:155], v[176:179], v[16:19]
	v_mfma_f32_16x16x32_bf16 v[4:7], v[144:147], v[204:207], v[4:7]
	v_mfma_f32_16x16x32_bf16 v[0:3], v[152:155], v[204:207], v[0:3]
	v_mfma_f32_16x16x32_bf16 v[52:55], v[148:151], v[164:167], v[52:55]
	v_mfma_f32_16x16x32_bf16 v[48:51], v[156:159], v[164:167], v[48:51]
	v_mfma_f32_16x16x32_bf16 v[36:39], v[148:151], v[172:175], v[36:39]
	v_mfma_f32_16x16x32_bf16 v[32:35], v[156:159], v[172:175], v[32:35]
	v_mfma_f32_16x16x32_bf16 v[20:23], v[148:151], v[180:183], v[20:23]
	v_mfma_f32_16x16x32_bf16 v[16:19], v[156:159], v[180:183], v[16:19]
	v_mfma_f32_16x16x32_bf16 v[4:7], v[148:151], v[208:211], v[4:7]
	v_mfma_f32_16x16x32_bf16 v[0:3], v[156:159], v[208:211], v[0:3]
	s_setprio 0
	s_barrier
	s_add_i32 s58, s58, 2
	s_add_u32 s18, s18, 0x100
	s_addc_u32 s19, s19, 0
	s_add_u32 s50, s50, 0x100
	s_addc_u32 s51, s51, 0
	s_cmp_gt_u32 s58, 17
	s_cbranch_scc0 .LBB0_404
; __device__ __forceinline__ unsigned cvt_pk_bf16(float lo, float hi) { unsigned r; asm volatile("v_cvt_pk_bf16_f32 %0, %1, %2" : "=v"(r) : "v"(lo), "v"(hi)); return r; }
;     __device__ __forceinline__ void operator()(const f32x4 (&acc)[2][2][4][2], const Unit& u, int wr, int wc, int fr, int fq) const {
;         const int row0 = u.pm * BM + wr * 64 + fr, col0 = u.pn * BM + wc * 32 + 8 * fq;
;         u32x4 rb[2][4][2];
; #pragma unroll
;         for (int ai = 0; ai < 2; ++ai)
; #pragma unroll
;             for (int m = 0; m < 4; ++m)
; #pragma unroll
;                 for (int bj = 0; bj < 2; ++bj) rb[ai][m][bj] = *(const u32x4*)(base + (size_t)(row0 + ai * HALF + m * 16) * ldc + col0 + bj * HALF);
;         asm volatile("" ::: "memory");
; #pragma unroll
;         for (int ai = 0; ai < 2; ++ai)
; #pragma unroll
;             for (int m = 0; m < 4; ++m) { const int row = row0 + ai * HALF + m * 16; float s = 0.f;
; #pragma unroll
;                 for (int bj = 0; bj < 2; ++bj) { const u32x4 w = rb[ai][m][bj];
;                     const f32x4 v0 = acc[ai][bj][m][0] + (f32x4){__uint_as_float(w.x << 16), __uint_as_float(w.x & 0xffff0000u), __uint_as_float(w.y << 16), __uint_as_float(w.y & 0xffff0000u)};
;                     const f32x4 v1 = acc[ai][bj][m][1] + (f32x4){__uint_as_float(w.z << 16), __uint_as_float(w.z & 0xffff0000u), __uint_as_float(w.w << 16), __uint_as_float(w.w & 0xffff0000u)};
;                     s += ((v0[0] * v0[0] + v0[1] * v0[1]) + (v0[2] * v0[2] + v0[3] * v0[3])) + ((v1[0] * v1[0] + v1[1] * v1[1]) + (v1[2] * v1[2] + v1[3] * v1[3]));
;                     u32x4 o; o.x = cvt_pk_bf16(v0[0], v0[1]); o.y = cvt_pk_bf16(v0[2], v0[3]); o.z = cvt_pk_bf16(v1[0], v1[1]); o.w = cvt_pk_bf16(v1[2], v1[3]);
;                     *(u32x4*)(outb + (size_t)row * ldc + col0 + bj * HALF) = o; }
	v_lshl_or_b32 v204, s48, 8, v222
	v_lshl_add_u32 v220, s49, 8, v185
	v_ashrrev_i32_e32 v205, 31, v204
	v_lshlrev_b64 v[238:239], 1, v[204:205]
	v_ashrrev_i32_e32 v221, 31, v220
	v_lshl_add_u64 v[100:101], s[12:13], 0, v[238:239]
	v_lshlrev_b64 v[240:241], 11, v[220:221]
	v_lshl_add_u64 v[102:103], v[100:101], 0, v[240:241]
	global_load_dwordx4 v[228:231], v[102:103], off
	global_load_dwordx4 v[234:237], v[102:103], off offset:256
	v_or_b32_e32 v218, 16, v220
	v_or_b32_e32 v216, 32, v220
	v_or_b32_e32 v214, 48, v220
	v_add_u32_e32 v212, 0x80, v220
	v_add_u32_e32 v210, 0x90, v220
	v_add_u32_e32 v208, 0xa0, v220
	v_add_u32_e32 v206, 0xb0, v220
	v_ashrrev_i32_e32 v219, 31, v218
	v_ashrrev_i32_e32 v217, 31, v216
	v_ashrrev_i32_e32 v215, 31, v214
	v_ashrrev_i32_e32 v213, 31, v212
	v_ashrrev_i32_e32 v211, 31, v210
	v_ashrrev_i32_e32 v209, 31, v208
	v_ashrrev_i32_e32 v207, 31, v206
	v_lshlrev_b64 v[102:103], 11, v[218:219]
	v_lshlrev_b64 v[108:109], 11, v[216:217]
	v_lshlrev_b64 v[110:111], 11, v[214:215]
	v_lshlrev_b64 v[120:121], 11, v[212:213]
	v_lshlrev_b64 v[122:123], 11, v[210:211]
	v_lshlrev_b64 v[132:133], 11, v[208:209]
	v_lshlrev_b64 v[134:135], 11, v[206:207]
	v_lshl_add_u64 v[102:103], v[100:101], 0, v[102:103]
	v_lshl_add_u64 v[108:109], v[100:101], 0, v[108:109]
	v_lshl_add_u64 v[110:111], v[100:101], 0, v[110:111]
	v_lshl_add_u64 v[120:121], v[100:101], 0, v[120:121]
	v_lshl_add_u64 v[122:123], v[100:101], 0, v[122:123]
	v_lshl_add_u64 v[242:243], v[100:101], 0, v[132:133]
	v_lshl_add_u64 v[100:101], v[100:101], 0, v[134:135]
	global_load_dwordx4 v[180:183], v[102:103], off
	global_load_dwordx4 v[176:179], v[102:103], off offset:256
	global_load_dwordx4 v[172:175], v[108:109], off
	global_load_dwordx4 v[168:171], v[108:109], off offset:256
	global_load_dwordx4 v[164:167], v[110:111], off
	global_load_dwordx4 v[160:163], v[110:111], off offset:256
	global_load_dwordx4 v[156:159], v[120:121], off
	global_load_dwordx4 v[152:155], v[120:121], off offset:256
	global_load_dwordx4 v[148:151], v[122:123], off
	global_load_dwordx4 v[144:147], v[122:123], off offset:256
	global_load_dwordx4 v[132:135], v[242:243], off
	s_nop 0
	global_load_dwordx4 v[120:123], v[242:243], off offset:256
	global_load_dwordx4 v[108:111], v[100:101], off
	s_nop 0
	global_load_dwordx4 v[100:103], v[100:101], off offset:256
	s_waitcnt vmcnt(0)
	v_lshlrev_b32_e32 v242, 16, v228
	v_and_b32_e32 v243, 0xffff0000, v228
	v_lshlrev_b32_e32 v228, 16, v229
	v_and_b32_e32 v229, 0xffff0000, v229
	v_lshlrev_b32_e32 v244, 16, v230
	v_and_b32_e32 v245, 0xffff0000, v230
	v_lshlrev_b32_e32 v230, 16, v231
	v_and_b32_e32 v231, 0xffff0000, v231
	v_lshlrev_b32_e32 v246, 16, v234
	v_and_b32_e32 v247, 0xffff0000, v234
	v_lshlrev_b32_e32 v234, 16, v235
	v_and_b32_e32 v235, 0xffff0000, v235
	v_pk_add_f32 v[142:143], v[142:143], v[228:229]
	v_pk_add_f32 v[140:141], v[140:141], v[242:243]
	v_pk_add_f32 v[138:139], v[138:139], v[230:231]
	v_pk_add_f32 v[136:137], v[136:137], v[244:245]
	v_pk_add_f32 v[130:131], v[130:131], v[234:235]
	v_mul_f32_e32 v227, v141, v141
	v_mul_f32_e32 v233, v143, v143
	v_mul_f32_e32 v234, v137, v137
	v_mul_f32_e32 v235, v139, v139
	v_lshlrev_b32_e32 v248, 16, v236
	v_and_b32_e32 v249, 0xffff0000, v236
	v_lshlrev_b32_e32 v236, 16, v237
	v_and_b32_e32 v237, 0xffff0000, v237
	v_fmac_f32_e32 v227, v140, v140
	v_fmac_f32_e32 v233, v142, v142
	v_fmac_f32_e32 v234, v136, v136
	v_fmac_f32_e32 v235, v138, v138
	v_pk_add_f32 v[228:229], v[128:129], v[246:247]
	v_pk_add_f32 v[230:231], v[126:127], v[236:237]
	v_cvt_pk_bf16_f32 v126, v140, v141
	v_cvt_pk_bf16_f32 v127, v142, v143
	v_cvt_pk_bf16_f32 v128, v136, v137
	v_add_f32_e32 v136, v227, v233
	v_add_f32_e32 v137, v234, v235
	v_cvt_pk_bf16_f32 v129, v138, v139
	v_add_f32_e32 v138, v136, v137
	v_pk_add_f32 v[136:137], v[124:125], v[248:249]
	v_mul_f32_e32 v124, v229, v229
	v_mul_f32_e32 v125, v131, v131
	v_fmac_f32_e32 v124, v228, v228
	v_fmac_f32_e32 v125, v130, v130
	v_add_f32_e32 v124, v124, v125
	v_mul_f32_e32 v125, v137, v137
	v_mul_f32_e32 v139, v231, v231
	v_fmac_f32_e32 v125, v136, v136
	v_fmac_f32_e32 v139, v230, v230
	v_add_f32_e32 v125, v125, v139
	v_add_f32_e32 v124, v124, v125
	v_add_f32_e32 v125, v138, v124
	v_and_b32_e32 v138, 64, v226
	v_xor_b32_e32 v124, 16, v226
	v_add_u32_e32 v140, 64, v138
	v_cmp_lt_i32_e32 vcc, v124, v140
	v_lshl_add_u64 v[138:139], s[12:13], 0, v[240:241]
	v_lshl_add_u64 v[138:139], v[138:139], 0, v[238:239]
	v_cndmask_b32_e32 v124, v226, v124, vcc
	v_lshlrev_b32_e32 v124, 2, v124
	ds_bpermute_b32 v141, v124, v125
	global_store_dwordx4 v[138:139], v[126:129], off
	s_nop 1
	v_cvt_pk_bf16_f32 v128, v228, v229
	s_waitcnt lgkmcnt(0)
	v_add_f32_e32 v126, v125, v141
	v_xor_b32_e32 v125, 32, v226
	v_cmp_lt_i32_e32 vcc, v125, v140
	v_cvt_pk_bf16_f32 v129, v130, v131
	v_cvt_pk_bf16_f32 v130, v136, v137
	v_cvt_pk_bf16_f32 v131, v230, v231
	global_store_dwordx4 v[138:139], v[128:131], off offset:256
	s_nop 0
	v_cndmask_b32_e32 v125, v226, v125, vcc
	v_lshlrev_b32_e32 v125, 2, v125
	ds_bpermute_b32 v127, v125, v126
	s_and_saveexec_b64 s[18:19], s[2:3]
	s_cbranch_execz .LBB0_407
	v_lshl_add_u64 v[128:129], v[220:221], 2, s[14:15]
	s_waitcnt lgkmcnt(0)
	v_add_f32_e32 v126, v126, v127
	global_atomic_add_f32 v[128:129], v126, off

; #define PG8_STAGE(bufoff, gbase, voff) do { _Pragma("unroll") for (int _i = 0; _i < 2; ++_i) \
;         __builtin_amdgcn_global_load_lds((const unsigned*)((const char*)(gbase) + (voff)[_i]), (PG8_LAS unsigned*)(lds + (bufoff) + ldsw + _i * 8192), 16, 0, 0); } while (0)
; #define PG8_LDA(dst, b, h) do { _Pragma("unroll") for (int m = 0; m < 4; ++m) _Pragma("unroll") for (int k = 0; k < 2; ++k) dst[m][k] = *(const PG8_LAS bf16x8*)(lds + PG8_SA(b, h) + aoff + m * 2048 + k * 1024); } while (0)
; #define PG8_LDB(dst, b, h) do { _Pragma("unroll") for (int n = 0; n < 2; ++n) _Pragma("unroll") for (int k = 0; k < 2; ++k) dst[n][k] = *(const PG8_LAS bf16x8*)(lds + PG8_SB(b, h) + boff + n * 2048 + k * 1024); } while (0)
; #define PG8_MMA(ai, bj, At, Bt) do { __builtin_amdgcn_s_setprio(1); _Pragma("unroll") for (int m = 0; m < 4; ++m) _Pragma("unroll") for (int n = 0; n < 2; ++n) _Pragma("unroll") for (int k = 0; k < 2; ++k) \
;         acc[ai][bj][m][n] = __builtin_amdgcn_mfma_f32_16x16x32_bf16(Bt[n][k], At[m][k], acc[ai][bj][m][n], 0, 0, 0); __builtin_amdgcn_s_setprio(0); } while (0)
; #define PG8_BAR __builtin_amdgcn_s_barrier()
; template <class Epi, class Sched, bool ALIGN_EPI = false, bool SP2 = false>
; __device__ __forceinline__ void gemm_phase(PG8_LAS unsigned char* lds, const Gemm g, const Sched& S, const Epi& E) {
;     ...
;         const bool has_next = S.next(ui + 1, nxt);
;         const char* nA = has_next ? (const char*)g.A + (size_t)nxt.pm * tstep : cA; const char* nB = has_next ? (const char*)g.Bt + (size_t)nxt.pn * tstep : cB;
;         for (int t = 0; t < nt; t += 2) {
;             const bool last = (t == nt - 2);
;             const char* a1 = cA + (size_t)(t + 1) * kstep;
;             const char* a2 = last ? nA : cA + (size_t)(t + 2) * kstep; const char* b2 = last ? nB : cB + (size_t)(t + 2) * kstep;
;             const char* a3 = a2 + kstep; const char* b3 = b2 + kstep;
;             if (last && has_next) S.a_ready(nxt);
;             if constexpr (SP2) {
;             PG8_LDB(B0, 0, 0); PG8_LDB(B1, 0, 1); PG8_SCHED; PG8_LDA(At, 0, 0); PG8_STAGE(PG8_SA(1, 1), a1 + hstep, voffA);
;             PG8_WAIT_V(8); PG8_WAIT_L(0); PG8_BAR; PG8_MMA(0, 0, At, B0); PG8_MMA(0, 1, At, B1); PG8_BAR; PG8_SCHED;
;             PG8_LDA(At, 0, 1); PG8_STAGE(PG8_SB(0, 0), b2, voffB); PG8_STAGE(PG8_SB(0, 1), b2 + hstep, voffB); PG8_STAGE(PG8_SA(0, 0), a2, voffA);
.LBB0_490:
	ds_read_b128 v[144:147], v161
	ds_read_b128 v[168:171], v161 offset:1024
	ds_read_b128 v[172:175], v161 offset:2048
	ds_read_b128 v[176:179], v161 offset:3072
	ds_read_b128 v[180:183], v163
	ds_read_b128 v[188:191], v163 offset:1024
	ds_read_b128 v[192:195], v163 offset:2048
	ds_read_b128 v[196:199], v163 offset:3072
	s_add_u32 s28, s26, 0xfffc0080
	s_addc_u32 s29, s27, -1
	s_cmp_eq_u32 s78, 12
	s_cselect_b32 s31, s5, s29
	s_cselect_b32 s30, s19, s28
	s_cselect_b32 s29, s17, s77
	s_cselect_b32 s28, s25, s76
	v_lshl_add_u64 v[148:149], s[26:27], 0, v[136:137]
	s_add_i32 m0, s39, 0xc000
	ds_read_b128 v[200:203], v164
	ds_read_b128 v[204:207], v164 offset:1024
	ds_read_b128 v[208:211], v164 offset:2048
	ds_read_b128 v[212:215], v164 offset:3072
	ds_read_b128 v[216:219], v164 offset:4096
	ds_read_b128 v[220:223], v164 offset:5120
	ds_read_b128 v[224:227], v164 offset:6144
	ds_read_b128 v[228:231], v164 offset:7168
	global_load_lds_dwordx4 v[148:149], off
	v_lshl_add_u64 v[148:149], s[26:27], 0, v[138:139]
	s_add_i32 m0, s39, 0xe000
	s_nop 0
	global_load_lds_dwordx4 v[148:149], off
	s_waitcnt vmcnt(8)
	s_waitcnt lgkmcnt(0)
	s_barrier
	s_setprio 1
	s_waitcnt lgkmcnt(0)
	v_mfma_f32_16x16x32_bf16 v[124:127], v[144:147], v[200:203], v[124:127]
	v_mfma_f32_16x16x32_bf16 v[120:123], v[172:175], v[200:203], v[120:123]
	v_mfma_f32_16x16x32_bf16 v[108:111], v[144:147], v[208:211], v[108:111]
	v_mfma_f32_16x16x32_bf16 v[104:107], v[172:175], v[208:211], v[104:107]
	v_mfma_f32_16x16x32_bf16 v[92:95], v[144:147], v[216:219], v[92:95]
	v_mfma_f32_16x16x32_bf16 v[88:91], v[172:175], v[216:219], v[88:91]
	v_mfma_f32_16x16x32_bf16 v[76:79], v[144:147], v[224:227], v[76:79]
	v_mfma_f32_16x16x32_bf16 v[72:75], v[172:175], v[224:227], v[72:75]
	v_mfma_f32_16x16x32_bf16 v[124:127], v[168:171], v[204:207], v[124:127]
	v_mfma_f32_16x16x32_bf16 v[120:123], v[176:179], v[204:207], v[120:123]
	v_mfma_f32_16x16x32_bf16 v[108:111], v[168:171], v[212:215], v[108:111]
	v_mfma_f32_16x16x32_bf16 v[104:107], v[176:179], v[212:215], v[104:107]
	v_mfma_f32_16x16x32_bf16 v[92:95], v[168:171], v[220:223], v[92:95]
	v_mfma_f32_16x16x32_bf16 v[88:91], v[176:179], v[220:223], v[88:91]
	v_mfma_f32_16x16x32_bf16 v[76:79], v[168:171], v[228:231], v[76:79]
	v_mfma_f32_16x16x32_bf16 v[72:75], v[176:179], v[228:231], v[72:75]
	v_mfma_f32_16x16x32_bf16 v[116:119], v[180:183], v[200:203], v[116:119]
	v_mfma_f32_16x16x32_bf16 v[112:115], v[192:195], v[200:203], v[112:115]
	v_mfma_f32_16x16x32_bf16 v[100:103], v[180:183], v[208:211], v[100:103]
	v_mfma_f32_16x16x32_bf16 v[96:99], v[192:195], v[208:211], v[96:99]
	v_mfma_f32_16x16x32_bf16 v[84:87], v[180:183], v[216:219], v[84:87]
	v_mfma_f32_16x16x32_bf16 v[80:83], v[192:195], v[216:219], v[80:83]
	v_mfma_f32_16x16x32_bf16 v[68:71], v[180:183], v[224:227], v[68:71]
	v_mfma_f32_16x16x32_bf16 v[64:67], v[192:195], v[224:227], v[64:67]
	v_mfma_f32_16x16x32_bf16 v[116:119], v[188:191], v[204:207], v[116:119]
	v_mfma_f32_16x16x32_bf16 v[112:115], v[196:199], v[204:207], v[112:115]
	v_mfma_f32_16x16x32_bf16 v[100:103], v[188:191], v[212:215], v[100:103]
	v_mfma_f32_16x16x32_bf16 v[96:99], v[196:199], v[212:215], v[96:99]
	v_mfma_f32_16x16x32_bf16 v[84:87], v[188:191], v[220:223], v[84:87]
	v_mfma_f32_16x16x32_bf16 v[80:83], v[196:199], v[220:223], v[80:83]
	v_mfma_f32_16x16x32_bf16 v[68:71], v[188:191], v[228:231], v[68:71]
	v_mfma_f32_16x16x32_bf16 v[64:67], v[196:199], v[228:231], v[64:67]
	s_setprio 0
	s_barrier
	s_add_i32 s79, s74, s38
	v_lshl_add_u64 v[148:149], s[28:29], 0, v[130:131]
	s_mov_b32 m0, s79
	ds_read_b128 v[200:203], v164 offset:16384
	ds_read_b128 v[204:207], v164 offset:17408
	ds_read_b128 v[208:211], v164 offset:18432
	ds_read_b128 v[212:215], v164 offset:19456
	ds_read_b128 v[216:219], v164 offset:20480
	ds_read_b128 v[220:223], v164 offset:21504
	ds_read_b128 v[224:227], v164 offset:22528
	ds_read_b128 v[228:231], v164 offset:23552
	global_load_lds_dwordx4 v[148:149], off
	s_add_i32 m0, s79, 0x2000
	s_add_u32 s80, s28, 0x40000
	v_lshl_add_u64 v[234:235], s[28:29], 0, v[134:135]
	s_addc_u32 s81, s29, 0
	s_add_i32 s79, s75, s38
	global_load_lds_dwordx4 v[234:235], off
	v_lshl_add_u64 v[236:237], s[80:81], 0, v[130:131]
	s_mov_b32 m0, s79
	v_lshl_add_u64 v[238:239], s[30:31], 0, v[132:133]
	global_load_lds_dwordx4 v[236:237], off
	v_lshl_add_u64 v[236:237], s[80:81], 0, v[134:135]
	s_add_i32 m0, s79, 0x2000
	s_nop 0
	global_load_lds_dwordx4 v[236:237], off
	v_lshl_add_u64 v[236:237], s[30:31], 0, v[128:129]
	s_mov_b32 m0, s39
	s_nop 0
	global_load_lds_dwordx4 v[236:237], off
	s_mov_b32 m0, s42
	s_nop 0
	global_load_lds_dwordx4 v[238:239], off
	s_waitcnt vmcnt(8)
	s_waitcnt lgkmcnt(0)
	s_barrier
; #define PG8_STAGE(bufoff, gbase, voff) do { _Pragma("unroll") for (int _i = 0; _i < 2; ++_i) \
;         __builtin_amdgcn_global_load_lds((const unsigned*)((const char*)(gbase) + (voff)[_i]), (PG8_LAS unsigned*)(lds + (bufoff) + ldsw + _i * 8192), 16, 0, 0); } while (0)
; #define PG8_LDA(dst, b, h) do { _Pragma("unroll") for (int m = 0; m < 4; ++m) _Pragma("unroll") for (int k = 0; k < 2; ++k) dst[m][k] = *(const PG8_LAS bf16x8*)(lds + PG8_SA(b, h) + aoff + m * 2048 + k * 1024); } while (0)
; #define PG8_LDB(dst, b, h) do { _Pragma("unroll") for (int n = 0; n < 2; ++n) _Pragma("unroll") for (int k = 0; k < 2; ++k) dst[n][k] = *(const PG8_LAS bf16x8*)(lds + PG8_SB(b, h) + boff + n * 2048 + k * 1024); } while (0)
; #define PG8_MMA(ai, bj, At, Bt) do { __builtin_amdgcn_s_setprio(1); _Pragma("unroll") for (int m = 0; m < 4; ++m) _Pragma("unroll") for (int n = 0; n < 2; ++n) _Pragma("unroll") for (int k = 0; k < 2; ++k) \
;         acc[ai][bj][m][n] = __builtin_amdgcn_mfma_f32_16x16x32_bf16(Bt[n][k], At[m][k], acc[ai][bj][m][n], 0, 0, 0); __builtin_amdgcn_s_setprio(0); } while (0)
; #define PG8_WAIT_V(n) asm volatile("s_waitcnt vmcnt(" #n ")" ::: "memory")
; #define PG8_WAIT_L(n) asm volatile("s_waitcnt lgkmcnt(" #n ")" ::: "memory")
; #define PG8_BAR __builtin_amdgcn_s_barrier()
; #define PG8_SCHED __builtin_amdgcn_sched_barrier(0)
; template <class Epi, class Sched, bool ALIGN_EPI = false, bool SP2 = false>
; __device__ __forceinline__ void gemm_phase(PG8_LAS unsigned char* lds, const Gemm g, const Sched& S, const Epi& E) {
;     ...
;             PG8_WAIT_V(8); PG8_WAIT_L(0); PG8_BAR; PG8_MMA(1, 0, At, B0); PG8_MMA(1, 1, At, B1); PG8_BAR; PG8_SCHED;
;             PG8_LDB(B0, 1, 0); PG8_LDB(B1, 1, 1); PG8_SCHED; PG8_LDA(At, 1, 0); PG8_STAGE(PG8_SA(0, 1), a2 + hstep, voffA);
;             PG8_WAIT_V(8); PG8_WAIT_L(0); PG8_BAR; PG8_MMA(0, 0, At, B0); PG8_MMA(0, 1, At, B1); PG8_BAR; PG8_SCHED;
	s_setprio 1
	s_waitcnt lgkmcnt(0)
	v_mfma_f32_16x16x32_bf16 v[60:63], v[144:147], v[200:203], v[60:63]
	v_mfma_f32_16x16x32_bf16 v[56:59], v[172:175], v[200:203], v[56:59]
	v_mfma_f32_16x16x32_bf16 v[44:47], v[144:147], v[208:211], v[44:47]
	v_mfma_f32_16x16x32_bf16 v[40:43], v[172:175], v[208:211], v[40:43]
	v_mfma_f32_16x16x32_bf16 v[28:31], v[144:147], v[216:219], v[28:31]
	v_mfma_f32_16x16x32_bf16 v[24:27], v[172:175], v[216:219], v[24:27]
	v_mfma_f32_16x16x32_bf16 v[12:15], v[144:147], v[224:227], v[12:15]
	v_mfma_f32_16x16x32_bf16 v[8:11], v[172:175], v[224:227], v[8:11]
	v_mfma_f32_16x16x32_bf16 v[60:63], v[168:171], v[204:207], v[60:63]
	v_mfma_f32_16x16x32_bf16 v[56:59], v[176:179], v[204:207], v[56:59]
	v_mfma_f32_16x16x32_bf16 v[44:47], v[168:171], v[212:215], v[44:47]
	v_mfma_f32_16x16x32_bf16 v[40:43], v[176:179], v[212:215], v[40:43]
	v_mfma_f32_16x16x32_bf16 v[28:31], v[168:171], v[220:223], v[28:31]
	v_mfma_f32_16x16x32_bf16 v[24:27], v[176:179], v[220:223], v[24:27]
	v_mfma_f32_16x16x32_bf16 v[12:15], v[168:171], v[228:231], v[12:15]
	v_mfma_f32_16x16x32_bf16 v[8:11], v[176:179], v[228:231], v[8:11]
	v_mfma_f32_16x16x32_bf16 v[52:55], v[180:183], v[200:203], v[52:55]
	v_mfma_f32_16x16x32_bf16 v[48:51], v[192:195], v[200:203], v[48:51]
	v_mfma_f32_16x16x32_bf16 v[36:39], v[180:183], v[208:211], v[36:39]
	v_mfma_f32_16x16x32_bf16 v[32:35], v[192:195], v[208:211], v[32:35]
	v_mfma_f32_16x16x32_bf16 v[20:23], v[180:183], v[216:219], v[20:23]
	v_mfma_f32_16x16x32_bf16 v[16:19], v[192:195], v[216:219], v[16:19]
	v_mfma_f32_16x16x32_bf16 v[4:7], v[180:183], v[224:227], v[4:7]
	v_mfma_f32_16x16x32_bf16 v[0:3], v[192:195], v[224:227], v[0:3]
	v_mfma_f32_16x16x32_bf16 v[52:55], v[188:191], v[204:207], v[52:55]
	v_mfma_f32_16x16x32_bf16 v[48:51], v[196:199], v[204:207], v[48:51]
	v_mfma_f32_16x16x32_bf16 v[36:39], v[188:191], v[212:215], v[36:39]
	v_mfma_f32_16x16x32_bf16 v[32:35], v[196:199], v[212:215], v[32:35]
	v_mfma_f32_16x16x32_bf16 v[20:23], v[188:191], v[220:223], v[20:23]
	v_mfma_f32_16x16x32_bf16 v[16:19], v[196:199], v[220:223], v[16:19]
	v_mfma_f32_16x16x32_bf16 v[4:7], v[188:191], v[228:231], v[4:7]
	v_mfma_f32_16x16x32_bf16 v[0:3], v[196:199], v[228:231], v[0:3]
	s_setprio 0
	s_barrier
	s_add_i32 s79, 0, 0x18000
	v_add_u32_e32 v167, s79, v157
	s_add_i32 s80, 0, 0x1c000
	ds_read_b128 v[144:147], v167
	ds_read_b128 v[168:171], v167 offset:1024
	ds_read_b128 v[172:175], v167 offset:2048
	ds_read_b128 v[176:179], v167 offset:3072
	v_add_u32_e32 v167, s80, v157
	ds_read_b128 v[180:183], v167
	ds_read_b128 v[188:191], v167 offset:1024
	ds_read_b128 v[192:195], v167 offset:2048
	ds_read_b128 v[196:199], v167 offset:3072
	s_add_u32 s30, s30, 0x40000
	s_addc_u32 s31, s31, 0
	s_mov_b32 m0, s43
	v_lshl_add_u64 v[240:241], s[30:31], 0, v[128:129]
	ds_read_b128 v[200:203], v164 offset:32768
	ds_read_b128 v[204:207], v164 offset:33792
	ds_read_b128 v[208:211], v164 offset:34816
	ds_read_b128 v[212:215], v164 offset:35840
	ds_read_b128 v[216:219], v164 offset:36864
	ds_read_b128 v[220:223], v164 offset:37888
	ds_read_b128 v[224:227], v164 offset:38912
	ds_read_b128 v[228:231], v164 offset:39936
	global_load_lds_dwordx4 v[240:241], off
	v_lshl_add_u64 v[240:241], s[30:31], 0, v[132:133]
	s_mov_b32 m0, s44
	s_nop 0
	global_load_lds_dwordx4 v[240:241], off
	s_waitcnt vmcnt(8)
	s_waitcnt lgkmcnt(0)
	s_barrier
	s_setprio 1
	s_waitcnt lgkmcnt(0)
	v_mfma_f32_16x16x32_bf16 v[124:127], v[144:147], v[200:203], v[124:127]
	v_mfma_f32_16x16x32_bf16 v[120:123], v[172:175], v[200:203], v[120:123]
	v_mfma_f32_16x16x32_bf16 v[108:111], v[144:147], v[208:211], v[108:111]
	v_mfma_f32_16x16x32_bf16 v[104:107], v[172:175], v[208:211], v[104:107]
	v_mfma_f32_16x16x32_bf16 v[92:95], v[144:147], v[216:219], v[92:95]
	v_mfma_f32_16x16x32_bf16 v[88:91], v[172:175], v[216:219], v[88:91]
	v_mfma_f32_16x16x32_bf16 v[76:79], v[144:147], v[224:227], v[76:79]
	v_mfma_f32_16x16x32_bf16 v[72:75], v[172:175], v[224:227], v[72:75]
	v_mfma_f32_16x16x32_bf16 v[124:127], v[168:171], v[204:207], v[124:127]
	v_mfma_f32_16x16x32_bf16 v[120:123], v[176:179], v[204:207], v[120:123]
	v_mfma_f32_16x16x32_bf16 v[108:111], v[168:171], v[212:215], v[108:111]
	v_mfma_f32_16x16x32_bf16 v[104:107], v[176:179], v[212:215], v[104:107]
	v_mfma_f32_16x16x32_bf16 v[92:95], v[168:171], v[220:223], v[92:95]
	v_mfma_f32_16x16x32_bf16 v[88:91], v[176:179], v[220:223], v[88:91]
	v_mfma_f32_16x16x32_bf16 v[76:79], v[168:171], v[228:231], v[76:79]
	v_mfma_f32_16x16x32_bf16 v[72:75], v[176:179], v[228:231], v[72:75]
	v_mfma_f32_16x16x32_bf16 v[116:119], v[180:183], v[200:203], v[116:119]
	v_mfma_f32_16x16x32_bf16 v[112:115], v[192:195], v[200:203], v[112:115]
	v_mfma_f32_16x16x32_bf16 v[100:103], v[180:183], v[208:211], v[100:103]
	v_mfma_f32_16x16x32_bf16 v[96:99], v[192:195], v[208:211], v[96:99]
	v_mfma_f32_16x16x32_bf16 v[84:87], v[180:183], v[216:219], v[84:87]
	v_mfma_f32_16x16x32_bf16 v[80:83], v[192:195], v[216:219], v[80:83]
	v_mfma_f32_16x16x32_bf16 v[68:71], v[180:183], v[224:227], v[68:71]
	v_mfma_f32_16x16x32_bf16 v[64:67], v[192:195], v[224:227], v[64:67]
	v_mfma_f32_16x16x32_bf16 v[116:119], v[188:191], v[204:207], v[116:119]
	v_mfma_f32_16x16x32_bf16 v[112:115], v[196:199], v[204:207], v[112:115]
	v_mfma_f32_16x16x32_bf16 v[100:103], v[188:191], v[212:215], v[100:103]
	v_mfma_f32_16x16x32_bf16 v[96:99], v[196:199], v[212:215], v[96:99]
	v_mfma_f32_16x16x32_bf16 v[84:87], v[188:191], v[220:223], v[84:87]
	v_mfma_f32_16x16x32_bf16 v[80:83], v[196:199], v[220:223], v[80:83]
	v_mfma_f32_16x16x32_bf16 v[68:71], v[188:191], v[228:231], v[68:71]
	v_mfma_f32_16x16x32_bf16 v[64:67], v[196:199], v[228:231], v[64:67]
	s_setprio 0
	s_barrier
; #define PG8_STAGE(bufoff, gbase, voff) do { _Pragma("unroll") for (int _i = 0; _i < 2; ++_i) \
;         __builtin_amdgcn_global_load_lds((const unsigned*)((const char*)(gbase) + (voff)[_i]), (PG8_LAS unsigned*)(lds + (bufoff) + ldsw + _i * 8192), 16, 0, 0); } while (0)
; #define PG8_LDA(dst, b, h) do { _Pragma("unroll") for (int m = 0; m < 4; ++m) _Pragma("unroll") for (int k = 0; k < 2; ++k) dst[m][k] = *(const PG8_LAS bf16x8*)(lds + PG8_SA(b, h) + aoff + m * 2048 + k * 1024); } while (0)
; #define PG8_MMA(ai, bj, At, Bt) do { __builtin_amdgcn_s_setprio(1); _Pragma("unroll") for (int m = 0; m < 4; ++m) _Pragma("unroll") for (int n = 0; n < 2; ++n) _Pragma("unroll") for (int k = 0; k < 2; ++k) \
;         acc[ai][bj][m][n] = __builtin_amdgcn_mfma_f32_16x16x32_bf16(Bt[n][k], At[m][k], acc[ai][bj][m][n], 0, 0, 0); __builtin_amdgcn_s_setprio(0); } while (0)
; #define PG8_WAIT_V(n) asm volatile("s_waitcnt vmcnt(" #n ")" ::: "memory")
; #define PG8_WAIT_L(n) asm volatile("s_waitcnt lgkmcnt(" #n ")" ::: "memory")
; #define PG8_BAR __builtin_amdgcn_s_barrier()
; #define PG8_SCHED __builtin_amdgcn_sched_barrier(0)
; template <class Epi, class Sched, bool ALIGN_EPI = false, bool SP2 = false>
; __device__ __forceinline__ void gemm_phase(PG8_LAS unsigned char* lds, const Gemm g, const Sched& S, const Epi& E) {
;     ...
;             PG8_LDA(At, 1, 1); PG8_STAGE(PG8_SB(1, 0), b3, voffB); PG8_STAGE(PG8_SB(1, 1), b3 + hstep, voffB); PG8_STAGE(PG8_SA(1, 0), a3, voffA);
;             PG8_WAIT_V(8); PG8_WAIT_L(0); PG8_BAR; PG8_MMA(1, 0, At, B0); PG8_MMA(1, 1, At, B1); PG8_BAR; PG8_SCHED;
;     ...
;         if constexpr (ALIGN_EPI) { if (wr == 0) PG8_BAR; }
	s_add_i32 s30, s79, s38
	v_lshl_add_u64 v[148:149], v[148:149], 0, s[12:13]
	s_mov_b32 m0, s30
	ds_read_b128 v[200:203], v164 offset:49152
	ds_read_b128 v[204:207], v164 offset:50176
	ds_read_b128 v[208:211], v164 offset:51200
	ds_read_b128 v[212:215], v164 offset:52224
	ds_read_b128 v[216:219], v164 offset:53248
	ds_read_b128 v[220:223], v164 offset:54272
	ds_read_b128 v[224:227], v164 offset:55296
	ds_read_b128 v[228:231], v164 offset:56320
	global_load_lds_dwordx4 v[148:149], off
	s_add_i32 m0, s30, 0x2000
	s_add_u32 s28, s28, 0x40080
	v_lshl_add_u64 v[148:149], v[234:235], 0, s[12:13]
	s_addc_u32 s29, s29, 0
	s_add_i32 s30, s80, s38
	global_load_lds_dwordx4 v[148:149], off
	v_lshl_add_u64 v[148:149], s[28:29], 0, v[130:131]
	s_mov_b32 m0, s30
	s_nop 0
	global_load_lds_dwordx4 v[148:149], off
	v_lshl_add_u64 v[148:149], s[28:29], 0, v[134:135]
	s_add_i32 m0, s30, 0x2000
	s_nop 0
	global_load_lds_dwordx4 v[148:149], off
	v_lshl_add_u64 v[148:149], v[236:237], 0, s[12:13]
	s_mov_b32 m0, s50
	s_nop 0
	global_load_lds_dwordx4 v[148:149], off
	v_lshl_add_u64 v[148:149], v[238:239], 0, s[12:13]
	s_mov_b32 m0, s51
	s_nop 0
	global_load_lds_dwordx4 v[148:149], off
	s_waitcnt vmcnt(8)
	s_waitcnt lgkmcnt(0)
	s_barrier
	s_setprio 1
	s_waitcnt lgkmcnt(0)
	v_mfma_f32_16x16x32_bf16 v[60:63], v[144:147], v[200:203], v[60:63]
	v_mfma_f32_16x16x32_bf16 v[56:59], v[172:175], v[200:203], v[56:59]
	v_mfma_f32_16x16x32_bf16 v[44:47], v[144:147], v[208:211], v[44:47]
	v_mfma_f32_16x16x32_bf16 v[40:43], v[172:175], v[208:211], v[40:43]
	v_mfma_f32_16x16x32_bf16 v[28:31], v[144:147], v[216:219], v[28:31]
	v_mfma_f32_16x16x32_bf16 v[24:27], v[172:175], v[216:219], v[24:27]
	v_mfma_f32_16x16x32_bf16 v[12:15], v[144:147], v[224:227], v[12:15]
	v_mfma_f32_16x16x32_bf16 v[8:11], v[172:175], v[224:227], v[8:11]
	v_mfma_f32_16x16x32_bf16 v[60:63], v[168:171], v[204:207], v[60:63]
	v_mfma_f32_16x16x32_bf16 v[56:59], v[176:179], v[204:207], v[56:59]
	v_mfma_f32_16x16x32_bf16 v[44:47], v[168:171], v[212:215], v[44:47]
	v_mfma_f32_16x16x32_bf16 v[40:43], v[176:179], v[212:215], v[40:43]
	v_mfma_f32_16x16x32_bf16 v[28:31], v[168:171], v[220:223], v[28:31]
	v_mfma_f32_16x16x32_bf16 v[24:27], v[176:179], v[220:223], v[24:27]
	v_mfma_f32_16x16x32_bf16 v[12:15], v[168:171], v[228:231], v[12:15]
	v_mfma_f32_16x16x32_bf16 v[8:11], v[176:179], v[228:231], v[8:11]
	v_mfma_f32_16x16x32_bf16 v[52:55], v[180:183], v[200:203], v[52:55]
	v_mfma_f32_16x16x32_bf16 v[48:51], v[192:195], v[200:203], v[48:51]
	v_mfma_f32_16x16x32_bf16 v[36:39], v[180:183], v[208:211], v[36:39]
	v_mfma_f32_16x16x32_bf16 v[32:35], v[192:195], v[208:211], v[32:35]
	v_mfma_f32_16x16x32_bf16 v[20:23], v[180:183], v[216:219], v[20:23]
	v_mfma_f32_16x16x32_bf16 v[16:19], v[192:195], v[216:219], v[16:19]
	v_mfma_f32_16x16x32_bf16 v[4:7], v[180:183], v[224:227], v[4:7]
	v_mfma_f32_16x16x32_bf16 v[0:3], v[192:195], v[224:227], v[0:3]
	v_mfma_f32_16x16x32_bf16 v[52:55], v[188:191], v[204:207], v[52:55]
	v_mfma_f32_16x16x32_bf16 v[48:51], v[196:199], v[204:207], v[48:51]
	v_mfma_f32_16x16x32_bf16 v[36:39], v[188:191], v[212:215], v[36:39]
	v_mfma_f32_16x16x32_bf16 v[32:35], v[196:199], v[212:215], v[32:35]
	v_mfma_f32_16x16x32_bf16 v[20:23], v[188:191], v[220:223], v[20:23]
	v_mfma_f32_16x16x32_bf16 v[16:19], v[196:199], v[220:223], v[16:19]
	v_mfma_f32_16x16x32_bf16 v[4:7], v[188:191], v[228:231], v[4:7]
	v_mfma_f32_16x16x32_bf16 v[0:3], v[196:199], v[228:231], v[0:3]
	s_setprio 0
	s_barrier
	s_add_i32 s78, s78, 2
	s_add_u32 s26, s26, 0x100
	s_addc_u32 s27, s27, 0
	s_add_u32 s76, s76, 0x100
	s_addc_u32 s77, s77, 0
	s_cmp_gt_u32 s78, 13
	s_cbranch_scc0 .LBB0_490
	s_and_b64 vcc, exec, s[14:15]
	s_cbranch_vccz .LBB0_493
	s_barrier

; #define PG8_STAGE(bufoff, gbase, voff) do { _Pragma("unroll") for (int _i = 0; _i < 2; ++_i) \
;         __builtin_amdgcn_global_load_lds((const unsigned*)((const char*)(gbase) + (voff)[_i]), (PG8_LAS unsigned*)(lds + (bufoff) + ldsw + _i * 8192), 16, 0, 0); } while (0)
; #define PG8_LDA(dst, b, h) do { _Pragma("unroll") for (int m = 0; m < 4; ++m) _Pragma("unroll") for (int k = 0; k < 2; ++k) dst[m][k] = *(const PG8_LAS bf16x8*)(lds + PG8_SA(b, h) + aoff + m * 2048 + k * 1024); } while (0)
; #define PG8_LDB(dst, b, h) do { _Pragma("unroll") for (int n = 0; n < 2; ++n) _Pragma("unroll") for (int k = 0; k < 2; ++k) dst[n][k] = *(const PG8_LAS bf16x8*)(lds + PG8_SB(b, h) + boff + n * 2048 + k * 1024); } while (0)
; #define PG8_MMA(ai, bj, At, Bt) do { __builtin_amdgcn_s_setprio(1); _Pragma("unroll") for (int m = 0; m < 4; ++m) _Pragma("unroll") for (int n = 0; n < 2; ++n) _Pragma("unroll") for (int k = 0; k < 2; ++k) \
;         acc[ai][bj][m][n] = __builtin_amdgcn_mfma_f32_16x16x32_bf16(Bt[n][k], At[m][k], acc[ai][bj][m][n], 0, 0, 0); __builtin_amdgcn_s_setprio(0); } while (0)
; #define PG8_BAR __builtin_amdgcn_s_barrier()
; template <class Epi, class Sched, bool ALIGN_EPI = false, bool SP2 = false>
; __device__ __forceinline__ void gemm_phase(PG8_LAS unsigned char* lds, const Gemm g, const Sched& S, const Epi& E) {
;     ...
;         const bool has_next = S.next(ui + 1, nxt);
;         const char* nA = has_next ? (const char*)g.A + (size_t)nxt.pm * tstep : cA; const char* nB = has_next ? (const char*)g.Bt + (size_t)nxt.pn * tstep : cB;
;         for (int t = 0; t < nt; t += 2) {
;             const bool last = (t == nt - 2);
;             const char* a1 = cA + (size_t)(t + 1) * kstep;
;             const char* a2 = last ? nA : cA + (size_t)(t + 2) * kstep; const char* b2 = last ? nB : cB + (size_t)(t + 2) * kstep;
;             const char* a3 = a2 + kstep; const char* b3 = b2 + kstep;
;             if (last && has_next) S.a_ready(nxt);
;             if constexpr (SP2) {
;             PG8_LDB(B0, 0, 0); PG8_LDB(B1, 0, 1); PG8_SCHED; PG8_LDA(At, 0, 0); PG8_STAGE(PG8_SA(1, 1), a1 + hstep, voffA);
;             PG8_WAIT_V(8); PG8_WAIT_L(0); PG8_BAR; PG8_MMA(0, 0, At, B0); PG8_MMA(0, 1, At, B1); PG8_BAR; PG8_SCHED;
;             PG8_LDA(At, 0, 1); PG8_STAGE(PG8_SB(0, 0), b2, voffB); PG8_STAGE(PG8_SB(0, 1), b2 + hstep, voffB); PG8_STAGE(PG8_SA(0, 0), a2, voffA);
.LBB0_576:
	ds_read_b128 v[146:149], v167
	ds_read_b128 v[150:153], v167 offset:1024
	ds_read_b128 v[154:157], v167 offset:2048
	ds_read_b128 v[158:161], v167 offset:3072
	ds_read_b128 v[172:175], v168
	ds_read_b128 v[176:179], v168 offset:1024
	ds_read_b128 v[180:183], v168 offset:2048
	ds_read_b128 v[188:191], v168 offset:3072
	s_add_u32 s22, s20, 0xfffc0080
	s_addc_u32 s23, s21, -1
	s_cmp_eq_u32 s70, 12
	s_cselect_b32 s25, s13, s23
	s_cselect_b32 s24, s50, s22
	s_cselect_b32 s23, s11, s69
	s_cselect_b32 s22, s51, s58
	v_lshl_add_u64 v[224:225], s[20:21], 0, v[138:139]
	s_add_i32 m0, s19, 0xc000
	ds_read_b128 v[192:195], v169
	ds_read_b128 v[196:199], v169 offset:1024
	ds_read_b128 v[200:203], v169 offset:2048
	ds_read_b128 v[204:207], v169 offset:3072
	ds_read_b128 v[208:211], v169 offset:4096
	ds_read_b128 v[212:215], v169 offset:5120
	ds_read_b128 v[216:219], v169 offset:6144
	ds_read_b128 v[220:223], v169 offset:7168
	global_load_lds_dwordx4 v[224:225], off
	v_lshl_add_u64 v[224:225], s[20:21], 0, v[140:141]
	s_add_i32 m0, s19, 0xe000
	s_nop 0
	global_load_lds_dwordx4 v[224:225], off
	s_waitcnt vmcnt(8)
	s_waitcnt lgkmcnt(0)
	s_barrier
	s_setprio 1
	s_waitcnt lgkmcnt(0)
	v_mfma_f32_16x16x32_bf16 v[124:127], v[146:149], v[192:195], v[124:127]
	v_mfma_f32_16x16x32_bf16 v[120:123], v[154:157], v[192:195], v[120:123]
	v_mfma_f32_16x16x32_bf16 v[116:119], v[146:149], v[200:203], v[116:119]
	v_mfma_f32_16x16x32_bf16 v[112:115], v[154:157], v[200:203], v[112:115]
	v_mfma_f32_16x16x32_bf16 v[92:95], v[146:149], v[208:211], v[92:95]
	v_mfma_f32_16x16x32_bf16 v[88:91], v[154:157], v[208:211], v[88:91]
	v_mfma_f32_16x16x32_bf16 v[76:79], v[146:149], v[216:219], v[76:79]
	v_mfma_f32_16x16x32_bf16 v[72:75], v[154:157], v[216:219], v[72:75]
	v_mfma_f32_16x16x32_bf16 v[124:127], v[150:153], v[196:199], v[124:127]
	v_mfma_f32_16x16x32_bf16 v[120:123], v[158:161], v[196:199], v[120:123]
	v_mfma_f32_16x16x32_bf16 v[116:119], v[150:153], v[204:207], v[116:119]
	v_mfma_f32_16x16x32_bf16 v[112:115], v[158:161], v[204:207], v[112:115]
	v_mfma_f32_16x16x32_bf16 v[92:95], v[150:153], v[212:215], v[92:95]
	v_mfma_f32_16x16x32_bf16 v[88:91], v[158:161], v[212:215], v[88:91]
	v_mfma_f32_16x16x32_bf16 v[76:79], v[150:153], v[220:223], v[76:79]
	v_mfma_f32_16x16x32_bf16 v[72:75], v[158:161], v[220:223], v[72:75]
	v_mfma_f32_16x16x32_bf16 v[108:111], v[172:175], v[192:195], v[108:111]
	v_mfma_f32_16x16x32_bf16 v[104:107], v[180:183], v[192:195], v[104:107]
	v_mfma_f32_16x16x32_bf16 v[100:103], v[172:175], v[200:203], v[100:103]
	v_mfma_f32_16x16x32_bf16 v[96:99], v[180:183], v[200:203], v[96:99]
	v_mfma_f32_16x16x32_bf16 v[84:87], v[172:175], v[208:211], v[84:87]
	v_mfma_f32_16x16x32_bf16 v[80:83], v[180:183], v[208:211], v[80:83]
	v_mfma_f32_16x16x32_bf16 v[68:71], v[172:175], v[216:219], v[68:71]
	v_mfma_f32_16x16x32_bf16 v[64:67], v[180:183], v[216:219], v[64:67]
	v_mfma_f32_16x16x32_bf16 v[108:111], v[176:179], v[196:199], v[108:111]
	v_mfma_f32_16x16x32_bf16 v[104:107], v[188:191], v[196:199], v[104:107]
	v_mfma_f32_16x16x32_bf16 v[100:103], v[176:179], v[204:207], v[100:103]
	v_mfma_f32_16x16x32_bf16 v[96:99], v[188:191], v[204:207], v[96:99]
	v_mfma_f32_16x16x32_bf16 v[84:87], v[176:179], v[212:215], v[84:87]
	v_mfma_f32_16x16x32_bf16 v[80:83], v[188:191], v[212:215], v[80:83]
	v_mfma_f32_16x16x32_bf16 v[68:71], v[176:179], v[220:223], v[68:71]
	v_mfma_f32_16x16x32_bf16 v[64:67], v[188:191], v[220:223], v[64:67]
	s_setprio 0
	s_barrier
	s_add_i32 s71, s47, s30
	v_lshl_add_u64 v[224:225], s[22:23], 0, v[130:131]
	s_mov_b32 m0, s71
	ds_read_b128 v[192:195], v169 offset:16384
	ds_read_b128 v[196:199], v169 offset:17408
	ds_read_b128 v[200:203], v169 offset:18432
	ds_read_b128 v[204:207], v169 offset:19456
	ds_read_b128 v[208:211], v169 offset:20480
	ds_read_b128 v[212:215], v169 offset:21504
	ds_read_b128 v[216:219], v169 offset:22528
	ds_read_b128 v[220:223], v169 offset:23552
	global_load_lds_dwordx4 v[224:225], off
	s_add_i32 m0, s71, 0x2000
	s_add_u32 s72, s22, 0x40000
	v_lshl_add_u64 v[226:227], s[22:23], 0, v[134:135]
	s_addc_u32 s73, s23, 0
	s_add_i32 s71, s48, s30
	global_load_lds_dwordx4 v[226:227], off
	v_lshl_add_u64 v[228:229], s[72:73], 0, v[130:131]
	s_mov_b32 m0, s71
	v_lshl_add_u64 v[230:231], s[24:25], 0, v[132:133]
	global_load_lds_dwordx4 v[228:229], off
	v_lshl_add_u64 v[228:229], s[72:73], 0, v[134:135]
	s_add_i32 m0, s71, 0x2000
	s_nop 0
	global_load_lds_dwordx4 v[228:229], off
	v_lshl_add_u64 v[228:229], s[24:25], 0, v[128:129]
	s_mov_b32 m0, s19
	s_nop 0
	global_load_lds_dwordx4 v[228:229], off
	s_mov_b32 m0, s31
	s_nop 0
	global_load_lds_dwordx4 v[230:231], off
	s_waitcnt vmcnt(8)
	s_waitcnt lgkmcnt(0)
	s_barrier
; #define PG8_STAGE(bufoff, gbase, voff) do { _Pragma("unroll") for (int _i = 0; _i < 2; ++_i) \
;         __builtin_amdgcn_global_load_lds((const unsigned*)((const char*)(gbase) + (voff)[_i]), (PG8_LAS unsigned*)(lds + (bufoff) + ldsw + _i * 8192), 16, 0, 0); } while (0)
; #define PG8_LDA(dst, b, h) do { _Pragma("unroll") for (int m = 0; m < 4; ++m) _Pragma("unroll") for (int k = 0; k < 2; ++k) dst[m][k] = *(const PG8_LAS bf16x8*)(lds + PG8_SA(b, h) + aoff + m * 2048 + k * 1024); } while (0)
; #define PG8_LDB(dst, b, h) do { _Pragma("unroll") for (int n = 0; n < 2; ++n) _Pragma("unroll") for (int k = 0; k < 2; ++k) dst[n][k] = *(const PG8_LAS bf16x8*)(lds + PG8_SB(b, h) + boff + n * 2048 + k * 1024); } while (0)
; #define PG8_MMA(ai, bj, At, Bt) do { __builtin_amdgcn_s_setprio(1); _Pragma("unroll") for (int m = 0; m < 4; ++m) _Pragma("unroll") for (int n = 0; n < 2; ++n) _Pragma("unroll") for (int k = 0; k < 2; ++k) \
;         acc[ai][bj][m][n] = __builtin_amdgcn_mfma_f32_16x16x32_bf16(Bt[n][k], At[m][k], acc[ai][bj][m][n], 0, 0, 0); __builtin_amdgcn_s_setprio(0); } while (0)
; #define PG8_WAIT_V(n) asm volatile("s_waitcnt vmcnt(" #n ")" ::: "memory")
; #define PG8_WAIT_L(n) asm volatile("s_waitcnt lgkmcnt(" #n ")" ::: "memory")
; #define PG8_BAR __builtin_amdgcn_s_barrier()
; #define PG8_SCHED __builtin_amdgcn_sched_barrier(0)
; template <class Epi, class Sched, bool ALIGN_EPI = false, bool SP2 = false>
; __device__ __forceinline__ void gemm_phase(PG8_LAS unsigned char* lds, const Gemm g, const Sched& S, const Epi& E) {
;     ...
;             PG8_WAIT_V(8); PG8_WAIT_L(0); PG8_BAR; PG8_MMA(1, 0, At, B0); PG8_MMA(1, 1, At, B1); PG8_BAR; PG8_SCHED;
;             PG8_LDB(B0, 1, 0); PG8_LDB(B1, 1, 1); PG8_SCHED; PG8_LDA(At, 1, 0); PG8_STAGE(PG8_SA(0, 1), a2 + hstep, voffA);
;             PG8_WAIT_V(8); PG8_WAIT_L(0); PG8_BAR; PG8_MMA(0, 0, At, B0); PG8_MMA(0, 1, At, B1); PG8_BAR; PG8_SCHED;
	s_setprio 1
	s_waitcnt lgkmcnt(0)
	v_mfma_f32_16x16x32_bf16 v[60:63], v[146:149], v[192:195], v[60:63]
	v_mfma_f32_16x16x32_bf16 v[56:59], v[154:157], v[192:195], v[56:59]
	v_mfma_f32_16x16x32_bf16 v[44:47], v[146:149], v[200:203], v[44:47]
	v_mfma_f32_16x16x32_bf16 v[40:43], v[154:157], v[200:203], v[40:43]
	v_mfma_f32_16x16x32_bf16 v[28:31], v[146:149], v[208:211], v[28:31]
	v_mfma_f32_16x16x32_bf16 v[24:27], v[154:157], v[208:211], v[24:27]
	v_mfma_f32_16x16x32_bf16 v[12:15], v[146:149], v[216:219], v[12:15]
	v_mfma_f32_16x16x32_bf16 v[8:11], v[154:157], v[216:219], v[8:11]
	v_mfma_f32_16x16x32_bf16 v[60:63], v[150:153], v[196:199], v[60:63]
	v_mfma_f32_16x16x32_bf16 v[56:59], v[158:161], v[196:199], v[56:59]
	v_mfma_f32_16x16x32_bf16 v[44:47], v[150:153], v[204:207], v[44:47]
	v_mfma_f32_16x16x32_bf16 v[40:43], v[158:161], v[204:207], v[40:43]
	v_mfma_f32_16x16x32_bf16 v[28:31], v[150:153], v[212:215], v[28:31]
	v_mfma_f32_16x16x32_bf16 v[24:27], v[158:161], v[212:215], v[24:27]
	v_mfma_f32_16x16x32_bf16 v[12:15], v[150:153], v[220:223], v[12:15]
	v_mfma_f32_16x16x32_bf16 v[8:11], v[158:161], v[220:223], v[8:11]
	v_mfma_f32_16x16x32_bf16 v[52:55], v[172:175], v[192:195], v[52:55]
	v_mfma_f32_16x16x32_bf16 v[48:51], v[180:183], v[192:195], v[48:51]
	v_mfma_f32_16x16x32_bf16 v[36:39], v[172:175], v[200:203], v[36:39]
	v_mfma_f32_16x16x32_bf16 v[32:35], v[180:183], v[200:203], v[32:35]
	v_mfma_f32_16x16x32_bf16 v[20:23], v[172:175], v[208:211], v[20:23]
	v_mfma_f32_16x16x32_bf16 v[16:19], v[180:183], v[208:211], v[16:19]
	v_mfma_f32_16x16x32_bf16 v[4:7], v[172:175], v[216:219], v[4:7]
	v_mfma_f32_16x16x32_bf16 v[0:3], v[180:183], v[216:219], v[0:3]
	v_mfma_f32_16x16x32_bf16 v[52:55], v[176:179], v[196:199], v[52:55]
	v_mfma_f32_16x16x32_bf16 v[48:51], v[188:191], v[196:199], v[48:51]
	v_mfma_f32_16x16x32_bf16 v[36:39], v[176:179], v[204:207], v[36:39]
	v_mfma_f32_16x16x32_bf16 v[32:35], v[188:191], v[204:207], v[32:35]
	v_mfma_f32_16x16x32_bf16 v[20:23], v[176:179], v[212:215], v[20:23]
	v_mfma_f32_16x16x32_bf16 v[16:19], v[188:191], v[212:215], v[16:19]
	v_mfma_f32_16x16x32_bf16 v[4:7], v[176:179], v[220:223], v[4:7]
	v_mfma_f32_16x16x32_bf16 v[0:3], v[188:191], v[220:223], v[0:3]
	s_setprio 0
	s_barrier
	s_add_i32 s71, 0, 0x18000
	s_add_i32 s72, 0, 0x1c000
	v_add_u32_e32 v158, s71, v164
	v_add_u32_e32 v171, s72, v164
	ds_read_b128 v[146:149], v158
	ds_read_b128 v[150:153], v158 offset:1024
	ds_read_b128 v[154:157], v158 offset:2048
	ds_read_b128 v[158:161], v158 offset:3072
	ds_read_b128 v[172:175], v171
	ds_read_b128 v[176:179], v171 offset:1024
	ds_read_b128 v[180:183], v171 offset:2048
	ds_read_b128 v[188:191], v171 offset:3072
	s_add_u32 s24, s24, 0x40000
	s_addc_u32 s25, s25, 0
	s_mov_b32 m0, s36
	v_lshl_add_u64 v[234:235], s[24:25], 0, v[128:129]
	ds_read_b128 v[192:195], v169 offset:32768
	ds_read_b128 v[196:199], v169 offset:33792
	ds_read_b128 v[200:203], v169 offset:34816
	ds_read_b128 v[204:207], v169 offset:35840
	ds_read_b128 v[208:211], v169 offset:36864
	ds_read_b128 v[212:215], v169 offset:37888
	ds_read_b128 v[216:219], v169 offset:38912
	ds_read_b128 v[220:223], v169 offset:39936
	global_load_lds_dwordx4 v[234:235], off
	v_lshl_add_u64 v[234:235], s[24:25], 0, v[132:133]
	s_mov_b32 m0, s37
	s_nop 0
	global_load_lds_dwordx4 v[234:235], off
	s_waitcnt vmcnt(8)
	s_waitcnt lgkmcnt(0)
	s_barrier
	s_setprio 1
	s_waitcnt lgkmcnt(0)
	v_mfma_f32_16x16x32_bf16 v[124:127], v[146:149], v[192:195], v[124:127]
	v_mfma_f32_16x16x32_bf16 v[120:123], v[154:157], v[192:195], v[120:123]
	v_mfma_f32_16x16x32_bf16 v[116:119], v[146:149], v[200:203], v[116:119]
	v_mfma_f32_16x16x32_bf16 v[112:115], v[154:157], v[200:203], v[112:115]
	v_mfma_f32_16x16x32_bf16 v[92:95], v[146:149], v[208:211], v[92:95]
	v_mfma_f32_16x16x32_bf16 v[88:91], v[154:157], v[208:211], v[88:91]
	v_mfma_f32_16x16x32_bf16 v[76:79], v[146:149], v[216:219], v[76:79]
	v_mfma_f32_16x16x32_bf16 v[72:75], v[154:157], v[216:219], v[72:75]
	v_mfma_f32_16x16x32_bf16 v[124:127], v[150:153], v[196:199], v[124:127]
	v_mfma_f32_16x16x32_bf16 v[120:123], v[158:161], v[196:199], v[120:123]
	v_mfma_f32_16x16x32_bf16 v[116:119], v[150:153], v[204:207], v[116:119]
	v_mfma_f32_16x16x32_bf16 v[112:115], v[158:161], v[204:207], v[112:115]
	v_mfma_f32_16x16x32_bf16 v[92:95], v[150:153], v[212:215], v[92:95]
	v_mfma_f32_16x16x32_bf16 v[88:91], v[158:161], v[212:215], v[88:91]
	v_mfma_f32_16x16x32_bf16 v[76:79], v[150:153], v[220:223], v[76:79]
	v_mfma_f32_16x16x32_bf16 v[72:75], v[158:161], v[220:223], v[72:75]
	v_mfma_f32_16x16x32_bf16 v[108:111], v[172:175], v[192:195], v[108:111]
	v_mfma_f32_16x16x32_bf16 v[104:107], v[180:183], v[192:195], v[104:107]
	v_mfma_f32_16x16x32_bf16 v[100:103], v[172:175], v[200:203], v[100:103]
	v_mfma_f32_16x16x32_bf16 v[96:99], v[180:183], v[200:203], v[96:99]
	v_mfma_f32_16x16x32_bf16 v[84:87], v[172:175], v[208:211], v[84:87]
	v_mfma_f32_16x16x32_bf16 v[80:83], v[180:183], v[208:211], v[80:83]
	v_mfma_f32_16x16x32_bf16 v[68:71], v[172:175], v[216:219], v[68:71]
	v_mfma_f32_16x16x32_bf16 v[64:67], v[180:183], v[216:219], v[64:67]
	v_mfma_f32_16x16x32_bf16 v[108:111], v[176:179], v[196:199], v[108:111]
	v_mfma_f32_16x16x32_bf16 v[104:107], v[188:191], v[196:199], v[104:107]
	v_mfma_f32_16x16x32_bf16 v[100:103], v[176:179], v[204:207], v[100:103]
	v_mfma_f32_16x16x32_bf16 v[96:99], v[188:191], v[204:207], v[96:99]
	v_mfma_f32_16x16x32_bf16 v[84:87], v[176:179], v[212:215], v[84:87]
	v_mfma_f32_16x16x32_bf16 v[80:83], v[188:191], v[212:215], v[80:83]
	v_mfma_f32_16x16x32_bf16 v[68:71], v[176:179], v[220:223], v[68:71]
	v_mfma_f32_16x16x32_bf16 v[64:67], v[188:191], v[220:223], v[64:67]
	s_setprio 0
	s_barrier
; #define PG8_STAGE(bufoff, gbase, voff) do { _Pragma("unroll") for (int _i = 0; _i < 2; ++_i) \
;         __builtin_amdgcn_global_load_lds((const unsigned*)((const char*)(gbase) + (voff)[_i]), (PG8_LAS unsigned*)(lds + (bufoff) + ldsw + _i * 8192), 16, 0, 0); } while (0)
; #define PG8_LDA(dst, b, h) do { _Pragma("unroll") for (int m = 0; m < 4; ++m) _Pragma("unroll") for (int k = 0; k < 2; ++k) dst[m][k] = *(const PG8_LAS bf16x8*)(lds + PG8_SA(b, h) + aoff + m * 2048 + k * 1024); } while (0)
; #define PG8_WAIT_V(n) asm volatile("s_waitcnt vmcnt(" #n ")" ::: "memory")
; #define PG8_WAIT_L(n) asm volatile("s_waitcnt lgkmcnt(" #n ")" ::: "memory")
; #define PG8_BAR __builtin_amdgcn_s_barrier()
;     __device__ __forceinline__ void operator()(const f32x4 (&acc)[2][2][4][2], const Unit& u, int wr, int wc, int fr, int fq) const {
;         const int row0 = u.pm * BM + wr * 64 + fr, col0 = u.pn * BM + wc * 32 + 8 * fq;
;         f32x4 cs[2][2];
; #pragma unroll
;         for (int bj = 0; bj < 2; ++bj)
; #pragma unroll
;             for (int n = 0; n < 2; ++n) { const f32x4 q = *(const f32x4*)(ssq + col0 + bj * HALF + 4 * n);
; #pragma unroll
;                 for (int e = 0; e < 4; ++e) cs[bj][n][e] = __builtin_amdgcn_rsqf(q[e] * (1.0f / 1024.0f) + 1e-6f); }
; #pragma unroll
;         for (int ai = 0; ai < 2; ++ai)
; #pragma unroll
;             for (int m = 0; m < 4; ++m) { const int row = row0 + ai * HALF + m * 16, h = row >> 6, d = row & 63, dt = d >> 5, r = d & 31;
; #pragma unroll
;                 for (int bj = 0; bj < 2; ++bj) { const int col = col0 + bj * HALF, b = col >> 12, tl = col & 4095, kt = tl >> 5, k0 = tl & 31, s = k0 >> 4, half = (k0 >> 3) & 1, bh = b * 16 + h;
;                     const f32x4 v0 = acc[ai][bj][m][0] * cs[bj][0], v1 = acc[ai][bj][m][1] * cs[bj][1];
;                     bf16_t* p = VF + (((size_t)((((bh * 128 + kt) * 2 + dt) * 2 + s) * 64 + r)) << 3) + 4 * half;
; template <class Epi, class Sched, bool ALIGN_EPI = false, bool SP2 = false>
; __device__ __forceinline__ void gemm_phase(PG8_LAS unsigned char* lds, const Gemm g, const Sched& S, const Epi& E) {
;     ...
;             PG8_LDA(At, 1, 1); PG8_STAGE(PG8_SB(1, 0), b3, voffB); PG8_STAGE(PG8_SB(1, 1), b3 + hstep, voffB); PG8_STAGE(PG8_SA(1, 0), a3, voffA);
;             PG8_WAIT_V(8); PG8_WAIT_L(0); PG8_BAR; PG8_MMA(1, 0, At, B0); PG8_MMA(1, 1, At, B1); PG8_BAR; PG8_SCHED;
	s_add_i32 s24, s71, s30
	v_lshl_add_u64 v[224:225], v[224:225], 0, s[4:5]
	s_mov_b32 m0, s24
	ds_read_b128 v[192:195], v169 offset:49152
	ds_read_b128 v[196:199], v169 offset:50176
	ds_read_b128 v[200:203], v169 offset:51200
	ds_read_b128 v[204:207], v169 offset:52224
	ds_read_b128 v[208:211], v169 offset:53248
	ds_read_b128 v[212:215], v169 offset:54272
	ds_read_b128 v[216:219], v169 offset:55296
	ds_read_b128 v[220:223], v169 offset:56320
	global_load_lds_dwordx4 v[224:225], off
	s_add_i32 m0, s24, 0x2000
	s_add_u32 s22, s22, 0x40080
	v_lshl_add_u64 v[224:225], v[226:227], 0, s[4:5]
	s_addc_u32 s23, s23, 0
	s_add_i32 s24, s72, s30
	global_load_lds_dwordx4 v[224:225], off
	v_lshl_add_u64 v[224:225], s[22:23], 0, v[130:131]
	s_mov_b32 m0, s24
	s_nop 0
	global_load_lds_dwordx4 v[224:225], off
	v_lshl_add_u64 v[224:225], s[22:23], 0, v[134:135]
	s_add_i32 m0, s24, 0x2000
	s_nop 0
	global_load_lds_dwordx4 v[224:225], off
	v_lshl_add_u64 v[224:225], v[228:229], 0, s[4:5]
	s_mov_b32 m0, s43
	s_nop 0
	global_load_lds_dwordx4 v[224:225], off
	v_lshl_add_u64 v[224:225], v[230:231], 0, s[4:5]
	s_mov_b32 m0, s44
	s_nop 0
	global_load_lds_dwordx4 v[224:225], off
	s_waitcnt vmcnt(8)
	s_waitcnt lgkmcnt(0)
	s_barrier
	s_setprio 1
	s_waitcnt lgkmcnt(0)
	v_mfma_f32_16x16x32_bf16 v[60:63], v[146:149], v[192:195], v[60:63]
	v_mfma_f32_16x16x32_bf16 v[56:59], v[154:157], v[192:195], v[56:59]
	v_mfma_f32_16x16x32_bf16 v[44:47], v[146:149], v[200:203], v[44:47]
	v_mfma_f32_16x16x32_bf16 v[40:43], v[154:157], v[200:203], v[40:43]
	v_mfma_f32_16x16x32_bf16 v[28:31], v[146:149], v[208:211], v[28:31]
	v_mfma_f32_16x16x32_bf16 v[24:27], v[154:157], v[208:211], v[24:27]
	v_mfma_f32_16x16x32_bf16 v[12:15], v[146:149], v[216:219], v[12:15]
	v_mfma_f32_16x16x32_bf16 v[8:11], v[154:157], v[216:219], v[8:11]
	v_mfma_f32_16x16x32_bf16 v[60:63], v[150:153], v[196:199], v[60:63]
	v_mfma_f32_16x16x32_bf16 v[56:59], v[158:161], v[196:199], v[56:59]
	v_mfma_f32_16x16x32_bf16 v[44:47], v[150:153], v[204:207], v[44:47]
	v_mfma_f32_16x16x32_bf16 v[40:43], v[158:161], v[204:207], v[40:43]
	v_mfma_f32_16x16x32_bf16 v[28:31], v[150:153], v[212:215], v[28:31]
	v_mfma_f32_16x16x32_bf16 v[24:27], v[158:161], v[212:215], v[24:27]
	v_mfma_f32_16x16x32_bf16 v[12:15], v[150:153], v[220:223], v[12:15]
	v_mfma_f32_16x16x32_bf16 v[8:11], v[158:161], v[220:223], v[8:11]
	v_mfma_f32_16x16x32_bf16 v[52:55], v[172:175], v[192:195], v[52:55]
	v_mfma_f32_16x16x32_bf16 v[48:51], v[180:183], v[192:195], v[48:51]
	v_mfma_f32_16x16x32_bf16 v[36:39], v[172:175], v[200:203], v[36:39]
	v_mfma_f32_16x16x32_bf16 v[32:35], v[180:183], v[200:203], v[32:35]
	v_mfma_f32_16x16x32_bf16 v[20:23], v[172:175], v[208:211], v[20:23]
	v_mfma_f32_16x16x32_bf16 v[16:19], v[180:183], v[208:211], v[16:19]
	v_mfma_f32_16x16x32_bf16 v[4:7], v[172:175], v[216:219], v[4:7]
	v_mfma_f32_16x16x32_bf16 v[0:3], v[180:183], v[216:219], v[0:3]
	v_mfma_f32_16x16x32_bf16 v[52:55], v[176:179], v[196:199], v[52:55]
	v_mfma_f32_16x16x32_bf16 v[48:51], v[188:191], v[196:199], v[48:51]
	v_mfma_f32_16x16x32_bf16 v[36:39], v[176:179], v[204:207], v[36:39]
	v_mfma_f32_16x16x32_bf16 v[32:35], v[188:191], v[204:207], v[32:35]
	v_mfma_f32_16x16x32_bf16 v[20:23], v[176:179], v[212:215], v[20:23]
	v_mfma_f32_16x16x32_bf16 v[16:19], v[188:191], v[212:215], v[16:19]
	v_mfma_f32_16x16x32_bf16 v[4:7], v[176:179], v[220:223], v[4:7]
	v_mfma_f32_16x16x32_bf16 v[0:3], v[188:191], v[220:223], v[0:3]
	s_setprio 0
	s_barrier
	s_add_i32 s70, s70, 2
	s_add_u32 s20, s20, 0x100
	s_addc_u32 s21, s21, 0
	s_add_u32 s58, s58, 0x100
	s_addc_u32 s69, s69, 0
	s_cmp_gt_u32 s70, 13
	s_cbranch_scc0 .LBB0_576
	s_lshl_b32 s11, s49, 8
	s_or_b32 s11, s11, s42
	v_or_b32_e32 v146, s11, v163
	v_ashrrev_i32_e32 v147, 31, v146
	v_lshl_add_u64 v[158:159], v[146:147], 2, s[8:9]
	global_load_dwordx4 v[146:149], v[158:159], off
	global_load_dwordx4 v[150:153], v[158:159], off offset:16
	global_load_dwordx4 v[154:157], v[158:159], off offset:512
	s_nop 0
	global_load_dwordx4 v[158:161], v[158:159], off offset:528
	s_lshl_b32 s20, s18, 8
	s_add_i32 s20, s20, s39
	s_and_b32 s18, s49, 0x7ffff0
	s_lshr_b32 s13, s20, 6
	s_lshr_b32 s11, s11, 3
	s_add_i32 s13, s13, s18
	s_and_b32 s11, s11, 0x1ec
	v_lshl_or_b32 v171, s13, 9, v165
	s_or_b32 s13, s11, 16
	v_or_b32_e32 v172, s11, v171
	v_or_b32_e32 v173, s13, v171
	v_lshlrev_b32_e32 v175, 6, v172
	v_lshlrev_b32_e32 v173, 6, v173
	v_or_b32_e32 v172, v175, v162
	v_or_b32_e32 v174, v173, v162
	v_or_b32_e32 v176, v175, v166
	v_or_b32_e32 v178, v173, v166
	v_ashrrev_i32_e32 v173, 31, v172
	v_ashrrev_i32_e32 v175, 31, v174
	v_lshl_add_u64 v[172:173], v[172:173], 4, v[136:137]
	v_lshl_add_u64 v[174:175], v[174:175], 4, v[136:137]
	v_ashrrev_i32_e32 v177, 31, v176
	v_lshl_add_u64 v[176:177], v[176:177], 4, v[136:137]
	s_addk_i32 s20, 0x80
	s_lshr_b32 s20, s20, 6
	s_add_i32 s20, s20, s18
	s_and_b64 vcc, exec, s[2:3]
	s_mov_b32 s49, s10
	s_mov_b32 s18, s12
	s_mov_b64 s[22:23], s[16:17]
	s_waitcnt vmcnt(0)
; __device__ __forceinline__ unsigned cvt_pk_bf16(float lo, float hi) { unsigned r; asm volatile("v_cvt_pk_bf16_f32 %0, %1, %2" : "=v"(r) : "v"(lo), "v"(hi)); return r; }
;     __device__ __forceinline__ void operator()(const f32x4 (&acc)[2][2][4][2], const Unit& u, int wr, int wc, int fr, int fq) const {
;     ...
;             for (int n = 0; n < 2; ++n) { const f32x4 q = *(const f32x4*)(ssq + col0 + bj * HALF + 4 * n);
; #pragma unroll
;                 for (int e = 0; e < 4; ++e) cs[bj][n][e] = __builtin_amdgcn_rsqf(q[e] * (1.0f / 1024.0f) + 1e-6f); }
; #pragma unroll
;         for (int ai = 0; ai < 2; ++ai)
; #pragma unroll
;             for (int m = 0; m < 4; ++m) { const int row = row0 + ai * HALF + m * 16, h = row >> 6, d = row & 63, dt = d >> 5, r = d & 31;
; #pragma unroll
;                 for (int bj = 0; bj < 2; ++bj) { const int col = col0 + bj * HALF, b = col >> 12, tl = col & 4095, kt = tl >> 5, k0 = tl & 31, s = k0 >> 4, half = (k0 >> 3) & 1, bh = b * 16 + h;
;                     const f32x4 v0 = acc[ai][bj][m][0] * cs[bj][0], v1 = acc[ai][bj][m][1] * cs[bj][1];
;                     bf16_t* p = VF + (((size_t)((((bh * 128 + kt) * 2 + dt) * 2 + s) * 64 + r)) << 3) + 4 * half;
;                     *(unsigned long long*)p = (unsigned long long)cvt_pk_bf16(v0[0], v0[1]) | ((unsigned long long)cvt_pk_bf16(v0[2], v0[3]) << 32);
;                     *(unsigned long long*)(p + 256) = (unsigned long long)cvt_pk_bf16(v1[0], v1[1]) | ((unsigned long long)cvt_pk_bf16(v1[2], v1[3]) << 32); }
	v_fmamk_f32 v146, v146, 0x3a800000, v170
	v_fmamk_f32 v147, v147, 0x3a800000, v170
	v_fmamk_f32 v148, v148, 0x3a800000, v170
	v_fmamk_f32 v149, v149, 0x3a800000, v170
	v_fmamk_f32 v150, v150, 0x3a800000, v170
	v_fmamk_f32 v151, v151, 0x3a800000, v170
	v_fmamk_f32 v179, v154, 0x3a800000, v170
	v_fmamk_f32 v180, v155, 0x3a800000, v170
	v_fmamk_f32 v183, v158, 0x3a800000, v170
	v_fmamk_f32 v185, v159, 0x3a800000, v170
	v_fmamk_f32 v152, v152, 0x3a800000, v170
	v_fmamk_f32 v153, v153, 0x3a800000, v170
	v_fmamk_f32 v181, v156, 0x3a800000, v170
	v_fmamk_f32 v182, v157, 0x3a800000, v170
	v_fmamk_f32 v187, v160, 0x3a800000, v170
	v_fmamk_f32 v188, v161, 0x3a800000, v170
	v_rsq_f32_e32 v156, v146
	v_rsq_f32_e32 v157, v147
	v_rsq_f32_e32 v160, v148
	v_rsq_f32_e32 v161, v149
	v_rsq_f32_e32 v154, v150
	v_rsq_f32_e32 v155, v151
	v_rsq_f32_e32 v148, v179
	v_rsq_f32_e32 v149, v180
	v_rsq_f32_e32 v146, v183
	v_rsq_f32_e32 v147, v185
	v_rsq_f32_e32 v158, v152
	v_rsq_f32_e32 v159, v153
	v_rsq_f32_e32 v152, v181
	v_rsq_f32_e32 v153, v182
	v_rsq_f32_e32 v150, v187
	v_rsq_f32_e32 v151, v188
	v_pk_mul_f32 v[124:125], v[124:125], v[156:157]
	v_pk_mul_f32 v[120:121], v[120:121], v[154:155]
	v_pk_mul_f32 v[108:109], v[108:109], v[148:149]
	v_pk_mul_f32 v[104:105], v[104:105], v[146:147]
	v_pk_mul_f32 v[126:127], v[126:127], v[160:161]
	v_pk_mul_f32 v[122:123], v[122:123], v[158:159]
	v_pk_mul_f32 v[110:111], v[110:111], v[152:153]
	v_pk_mul_f32 v[106:107], v[106:107], v[150:151]
	v_cvt_pk_bf16_f32 v124, v124, v125
	v_cvt_pk_bf16_f32 v125, v126, v127
	global_store_dwordx2 v[172:173], v[124:125], off
	v_cvt_pk_bf16_f32 v120, v120, v121
	v_cvt_pk_bf16_f32 v121, v122, v123
	global_store_dwordx2 v[172:173], v[120:121], off offset:512
	v_cvt_pk_bf16_f32 v108, v108, v109
	v_cvt_pk_bf16_f32 v109, v110, v111
	global_store_dwordx2 v[174:175], v[108:109], off
	v_cvt_pk_bf16_f32 v104, v104, v105
	v_cvt_pk_bf16_f32 v105, v106, v107
	global_store_dwordx2 v[174:175], v[104:105], off offset:512
	v_pk_mul_f32 v[118:119], v[118:119], v[160:161]
	v_pk_mul_f32 v[116:117], v[116:117], v[156:157]
	v_pk_mul_f32 v[114:115], v[114:115], v[158:159]
	v_cvt_pk_bf16_f32 v104, v116, v117
	v_cvt_pk_bf16_f32 v105, v118, v119
	v_pk_mul_f32 v[112:113], v[112:113], v[154:155]
	global_store_dwordx2 v[176:177], v[104:105], off
	v_cvt_pk_bf16_f32 v104, v112, v113
	v_cvt_pk_bf16_f32 v105, v114, v115
	v_ashrrev_i32_e32 v179, 31, v178
	v_pk_mul_f32 v[100:101], v[100:101], v[148:149]
	v_pk_mul_f32 v[98:99], v[98:99], v[150:151]
	v_pk_mul_f32 v[96:97], v[96:97], v[146:147]
	global_store_dwordx2 v[176:177], v[104:105], off offset:512
	v_lshl_add_u64 v[104:105], v[178:179], 4, v[136:137]
	v_pk_mul_f32 v[102:103], v[102:103], v[152:153]
	v_cvt_pk_bf16_f32 v100, v100, v101
	v_pk_mul_f32 v[92:93], v[92:93], v[156:157]
	v_cvt_pk_bf16_f32 v101, v102, v103
	global_store_dwordx2 v[104:105], v[100:101], off
	v_cvt_pk_bf16_f32 v96, v96, v97
	v_cvt_pk_bf16_f32 v97, v98, v99
	v_or_b32_e32 v98, 2, v171
	global_store_dwordx2 v[104:105], v[96:97], off offset:512
	v_or_b32_e32 v96, s11, v98
	v_lshlrev_b32_e32 v99, 6, v96
	v_or_b32_e32 v96, v99, v162
	v_ashrrev_i32_e32 v97, 31, v96
	v_pk_mul_f32 v[88:89], v[88:89], v[154:155]
	v_lshl_add_u64 v[96:97], v[96:97], 4, v[136:137]
	v_pk_mul_f32 v[94:95], v[94:95], v[160:161]
	v_cvt_pk_bf16_f32 v92, v92, v93
	v_pk_mul_f32 v[90:91], v[90:91], v[158:159]
	v_cvt_pk_bf16_f32 v93, v94, v95
	global_store_dwordx2 v[96:97], v[92:93], off
	v_cvt_pk_bf16_f32 v88, v88, v89
	v_cvt_pk_bf16_f32 v89, v90, v91
	global_store_dwordx2 v[96:97], v[88:89], off offset:512
	v_or_b32_e32 v88, s13, v98
	v_lshlrev_b32_e32 v90, 6, v88
	v_or_b32_e32 v88, v90, v162
	v_ashrrev_i32_e32 v89, 31, v88
	v_pk_mul_f32 v[84:85], v[84:85], v[148:149]
	v_pk_mul_f32 v[80:81], v[80:81], v[146:147]
	v_lshl_add_u64 v[88:89], v[88:89], 4, v[136:137]
	v_pk_mul_f32 v[86:87], v[86:87], v[152:153]
	v_cvt_pk_bf16_f32 v84, v84, v85
	v_pk_mul_f32 v[82:83], v[82:83], v[150:151]
	v_cvt_pk_bf16_f32 v85, v86, v87
	global_store_dwordx2 v[88:89], v[84:85], off
	v_cvt_pk_bf16_f32 v80, v80, v81
	v_cvt_pk_bf16_f32 v81, v82, v83
	global_store_dwordx2 v[88:89], v[80:81], off offset:512
	v_or_b32_e32 v80, v99, v166
	v_ashrrev_i32_e32 v81, 31, v80
	v_pk_mul_f32 v[76:77], v[76:77], v[156:157]
	v_pk_mul_f32 v[72:73], v[72:73], v[154:155]
	v_lshl_add_u64 v[80:81], v[80:81], 4, v[136:137]
	v_pk_mul_f32 v[78:79], v[78:79], v[160:161]
	v_cvt_pk_bf16_f32 v76, v76, v77
	v_pk_mul_f32 v[74:75], v[74:75], v[158:159]
	v_cvt_pk_bf16_f32 v77, v78, v79
	global_store_dwordx2 v[80:81], v[76:77], off
	v_cvt_pk_bf16_f32 v72, v72, v73
	v_cvt_pk_bf16_f32 v73, v74, v75
	global_store_dwordx2 v[80:81], v[72:73], off offset:512
	v_or_b32_e32 v72, v90, v166
	v_ashrrev_i32_e32 v73, 31, v72
	v_pk_mul_f32 v[68:69], v[68:69], v[148:149]
	v_pk_mul_f32 v[66:67], v[66:67], v[150:151]
	v_pk_mul_f32 v[64:65], v[64:65], v[146:147]
; __device__ __forceinline__ unsigned cvt_pk_bf16(float lo, float hi) { unsigned r; asm volatile("v_cvt_pk_bf16_f32 %0, %1, %2" : "=v"(r) : "v"(lo), "v"(hi)); return r; }
; #define PG8_WAIT_V(n) asm volatile("s_waitcnt vmcnt(" #n ")" ::: "memory")
; #define PG8_BAR __builtin_amdgcn_s_barrier()
;     __device__ __forceinline__ void operator()(const f32x4 (&acc)[2][2][4][2], const Unit& u, int wr, int wc, int fr, int fq) const {
;     ...
;         for (int ai = 0; ai < 2; ++ai)
; #pragma unroll
;             for (int m = 0; m < 4; ++m) { const int row = row0 + ai * HALF + m * 16, h = row >> 6, d = row & 63, dt = d >> 5, r = d & 31;
; #pragma unroll
;                 for (int bj = 0; bj < 2; ++bj) { const int col = col0 + bj * HALF, b = col >> 12, tl = col & 4095, kt = tl >> 5, k0 = tl & 31, s = k0 >> 4, half = (k0 >> 3) & 1, bh = b * 16 + h;
;                     const f32x4 v0 = acc[ai][bj][m][0] * cs[bj][0], v1 = acc[ai][bj][m][1] * cs[bj][1];
;                     bf16_t* p = VF + (((size_t)((((bh * 128 + kt) * 2 + dt) * 2 + s) * 64 + r)) << 3) + 4 * half;
;                     *(unsigned long long*)p = (unsigned long long)cvt_pk_bf16(v0[0], v0[1]) | ((unsigned long long)cvt_pk_bf16(v0[2], v0[3]) << 32);
;                     *(unsigned long long*)(p + 256) = (unsigned long long)cvt_pk_bf16(v1[0], v1[1]) | ((unsigned long long)cvt_pk_bf16(v1[2], v1[3]) << 32); }
; template <class Epi, class Sched, bool ALIGN_EPI = false, bool SP2 = false>
; __device__ __forceinline__ void gemm_phase(PG8_LAS unsigned char* lds, const Gemm g, const Sched& S, const Epi& E) {
;     ...
;     PG8_WAIT_V(0);
;     if constexpr (!ALIGN_EPI) { if (wr == 0) PG8_BAR; }
	v_lshl_add_u64 v[72:73], v[72:73], 4, v[136:137]
	v_pk_mul_f32 v[70:71], v[70:71], v[152:153]
	v_cvt_pk_bf16_f32 v68, v68, v69
	v_pk_mul_f32 v[60:61], v[60:61], v[156:157]
	v_cvt_pk_bf16_f32 v69, v70, v71
	global_store_dwordx2 v[72:73], v[68:69], off
	v_cvt_pk_bf16_f32 v64, v64, v65
	v_cvt_pk_bf16_f32 v65, v66, v67
	v_lshl_or_b32 v66, s20, 9, v165
	global_store_dwordx2 v[72:73], v[64:65], off offset:512
	v_or_b32_e32 v64, s11, v66
	v_lshlrev_b32_e32 v67, 6, v64
	v_or_b32_e32 v64, v67, v162
	v_ashrrev_i32_e32 v65, 31, v64
	v_pk_mul_f32 v[56:57], v[56:57], v[154:155]
	v_lshl_add_u64 v[64:65], v[64:65], 4, v[136:137]
	v_pk_mul_f32 v[62:63], v[62:63], v[160:161]
	v_cvt_pk_bf16_f32 v60, v60, v61
	v_pk_mul_f32 v[58:59], v[58:59], v[158:159]
	v_cvt_pk_bf16_f32 v61, v62, v63
	global_store_dwordx2 v[64:65], v[60:61], off
	v_cvt_pk_bf16_f32 v56, v56, v57
	v_cvt_pk_bf16_f32 v57, v58, v59
	global_store_dwordx2 v[64:65], v[56:57], off offset:512
	v_or_b32_e32 v56, s13, v66
	v_lshlrev_b32_e32 v58, 6, v56
	v_or_b32_e32 v56, v58, v162
	v_ashrrev_i32_e32 v57, 31, v56
	v_pk_mul_f32 v[52:53], v[52:53], v[148:149]
	v_pk_mul_f32 v[48:49], v[48:49], v[146:147]
	v_lshl_add_u64 v[56:57], v[56:57], 4, v[136:137]
	v_pk_mul_f32 v[54:55], v[54:55], v[152:153]
	v_cvt_pk_bf16_f32 v52, v52, v53
	v_pk_mul_f32 v[50:51], v[50:51], v[150:151]
	v_cvt_pk_bf16_f32 v53, v54, v55
	global_store_dwordx2 v[56:57], v[52:53], off
	v_cvt_pk_bf16_f32 v48, v48, v49
	v_cvt_pk_bf16_f32 v49, v50, v51
	global_store_dwordx2 v[56:57], v[48:49], off offset:512
	v_or_b32_e32 v48, v67, v166
	v_ashrrev_i32_e32 v49, 31, v48
	v_pk_mul_f32 v[44:45], v[44:45], v[156:157]
	v_pk_mul_f32 v[40:41], v[40:41], v[154:155]
	v_lshl_add_u64 v[48:49], v[48:49], 4, v[136:137]
	v_pk_mul_f32 v[46:47], v[46:47], v[160:161]
	v_cvt_pk_bf16_f32 v44, v44, v45
	v_pk_mul_f32 v[42:43], v[42:43], v[158:159]
	v_cvt_pk_bf16_f32 v45, v46, v47
	global_store_dwordx2 v[48:49], v[44:45], off
	v_cvt_pk_bf16_f32 v40, v40, v41
	v_cvt_pk_bf16_f32 v41, v42, v43
	global_store_dwordx2 v[48:49], v[40:41], off offset:512
	v_or_b32_e32 v40, v58, v166
	v_ashrrev_i32_e32 v41, 31, v40
	v_pk_mul_f32 v[36:37], v[36:37], v[148:149]
	v_pk_mul_f32 v[34:35], v[34:35], v[150:151]
	v_pk_mul_f32 v[32:33], v[32:33], v[146:147]
	v_lshl_add_u64 v[40:41], v[40:41], 4, v[136:137]
	v_pk_mul_f32 v[38:39], v[38:39], v[152:153]
	v_cvt_pk_bf16_f32 v36, v36, v37
	v_pk_mul_f32 v[28:29], v[28:29], v[156:157]
	v_cvt_pk_bf16_f32 v37, v38, v39
	global_store_dwordx2 v[40:41], v[36:37], off
	v_cvt_pk_bf16_f32 v32, v32, v33
	v_cvt_pk_bf16_f32 v33, v34, v35
	v_or_b32_e32 v34, 2, v66
	global_store_dwordx2 v[40:41], v[32:33], off offset:512
	v_or_b32_e32 v32, s11, v34
	v_lshlrev_b32_e32 v35, 6, v32
	v_or_b32_e32 v32, v35, v162
	v_ashrrev_i32_e32 v33, 31, v32
	v_pk_mul_f32 v[24:25], v[24:25], v[154:155]
	v_lshl_add_u64 v[32:33], v[32:33], 4, v[136:137]
	v_pk_mul_f32 v[30:31], v[30:31], v[160:161]
	v_cvt_pk_bf16_f32 v28, v28, v29
	v_pk_mul_f32 v[26:27], v[26:27], v[158:159]
	v_cvt_pk_bf16_f32 v29, v30, v31
	global_store_dwordx2 v[32:33], v[28:29], off
	v_cvt_pk_bf16_f32 v24, v24, v25
	v_cvt_pk_bf16_f32 v25, v26, v27
	global_store_dwordx2 v[32:33], v[24:25], off offset:512
	v_or_b32_e32 v24, s13, v34
	v_lshlrev_b32_e32 v26, 6, v24
	v_or_b32_e32 v24, v26, v162
	v_ashrrev_i32_e32 v25, 31, v24
	v_pk_mul_f32 v[20:21], v[20:21], v[148:149]
	v_pk_mul_f32 v[16:17], v[16:17], v[146:147]
	v_lshl_add_u64 v[24:25], v[24:25], 4, v[136:137]
	v_pk_mul_f32 v[22:23], v[22:23], v[152:153]
	v_cvt_pk_bf16_f32 v20, v20, v21
	v_pk_mul_f32 v[18:19], v[18:19], v[150:151]
	v_cvt_pk_bf16_f32 v21, v22, v23
	global_store_dwordx2 v[24:25], v[20:21], off
	v_cvt_pk_bf16_f32 v16, v16, v17
	v_cvt_pk_bf16_f32 v17, v18, v19
	global_store_dwordx2 v[24:25], v[16:17], off offset:512
	v_or_b32_e32 v16, v35, v166
	v_ashrrev_i32_e32 v17, 31, v16
	v_pk_mul_f32 v[12:13], v[12:13], v[156:157]
	v_pk_mul_f32 v[8:9], v[8:9], v[154:155]
	v_lshl_add_u64 v[16:17], v[16:17], 4, v[136:137]
	v_pk_mul_f32 v[14:15], v[14:15], v[160:161]
	v_cvt_pk_bf16_f32 v12, v12, v13
	v_pk_mul_f32 v[10:11], v[10:11], v[158:159]
	v_cvt_pk_bf16_f32 v13, v14, v15
	global_store_dwordx2 v[16:17], v[12:13], off
	v_cvt_pk_bf16_f32 v8, v8, v9
	v_cvt_pk_bf16_f32 v9, v10, v11
	global_store_dwordx2 v[16:17], v[8:9], off offset:512
	v_or_b32_e32 v8, v26, v166
	v_ashrrev_i32_e32 v9, 31, v8
	v_pk_mul_f32 v[4:5], v[4:5], v[148:149]
	v_pk_mul_f32 v[0:1], v[0:1], v[146:147]
	v_lshl_add_u64 v[8:9], v[8:9], 4, v[136:137]
	v_pk_mul_f32 v[6:7], v[6:7], v[152:153]
	v_pk_mul_f32 v[2:3], v[2:3], v[150:151]
	v_cvt_pk_bf16_f32 v4, v4, v5
	v_cvt_pk_bf16_f32 v5, v6, v7
	global_store_dwordx2 v[8:9], v[4:5], off
	v_cvt_pk_bf16_f32 v0, v0, v1
	v_cvt_pk_bf16_f32 v1, v2, v3
	global_store_dwordx2 v[8:9], v[0:1], off offset:512
	s_mov_b64 s[20:21], s[14:15]
	s_cbranch_vccz .LBB0_569
	s_waitcnt vmcnt(0)
	s_cmpk_gt_u32 s26, 0xff
	s_cbranch_scc1 .LBB0_580
	s_barrier

; #define PG8_STAGE(bufoff, gbase, voff) do { _Pragma("unroll") for (int _i = 0; _i < 2; ++_i) \
;         __builtin_amdgcn_global_load_lds((const unsigned*)((const char*)(gbase) + (voff)[_i]), (PG8_LAS unsigned*)(lds + (bufoff) + ldsw + _i * 8192), 16, 0, 0); } while (0)
; #define PG8_LDA(dst, b, h) do { _Pragma("unroll") for (int m = 0; m < 4; ++m) _Pragma("unroll") for (int k = 0; k < 2; ++k) dst[m][k] = *(const PG8_LAS bf16x8*)(lds + PG8_SA(b, h) + aoff + m * 2048 + k * 1024); } while (0)
; #define PG8_LDB(dst, b, h) do { _Pragma("unroll") for (int n = 0; n < 2; ++n) _Pragma("unroll") for (int k = 0; k < 2; ++k) dst[n][k] = *(const PG8_LAS bf16x8*)(lds + PG8_SB(b, h) + boff + n * 2048 + k * 1024); } while (0)
; #define PG8_MMA(ai, bj, At, Bt) do { __builtin_amdgcn_s_setprio(1); _Pragma("unroll") for (int m = 0; m < 4; ++m) _Pragma("unroll") for (int n = 0; n < 2; ++n) _Pragma("unroll") for (int k = 0; k < 2; ++k) \
;         acc[ai][bj][m][n] = __builtin_amdgcn_mfma_f32_16x16x32_bf16(Bt[n][k], At[m][k], acc[ai][bj][m][n], 0, 0, 0); __builtin_amdgcn_s_setprio(0); } while (0)
; #define PG8_BAR __builtin_amdgcn_s_barrier()
; template <class Epi, class Sched, bool ALIGN_EPI = false, bool SP2 = false>
; __device__ __forceinline__ void gemm_phase(PG8_LAS unsigned char* lds, const Gemm g, const Sched& S, const Epi& E) {
;     ...
;         const bool has_next = S.next(ui + 1, nxt);
;         const char* nA = has_next ? (const char*)g.A + (size_t)nxt.pm * tstep : cA; const char* nB = has_next ? (const char*)g.Bt + (size_t)nxt.pn * tstep : cB;
;         for (int t = 0; t < nt; t += 2) {
;             const bool last = (t == nt - 2);
;             const char* a1 = cA + (size_t)(t + 1) * kstep;
;             const char* a2 = last ? nA : cA + (size_t)(t + 2) * kstep; const char* b2 = last ? nB : cB + (size_t)(t + 2) * kstep;
;             const char* a3 = a2 + kstep; const char* b3 = b2 + kstep;
;             if (last && has_next) S.a_ready(nxt);
;             if constexpr (SP2) {
;             PG8_LDB(B0, 0, 0); PG8_LDB(B1, 0, 1); PG8_SCHED; PG8_LDA(At, 0, 0); PG8_STAGE(PG8_SA(1, 1), a1 + hstep, voffA);
;             PG8_WAIT_V(8); PG8_WAIT_L(0); PG8_BAR; PG8_MMA(0, 0, At, B0); PG8_MMA(0, 1, At, B1); PG8_BAR; PG8_SCHED;
;             PG8_LDA(At, 0, 1); PG8_STAGE(PG8_SB(0, 0), b2, voffB); PG8_STAGE(PG8_SB(0, 1), b2 + hstep, voffB); PG8_STAGE(PG8_SA(0, 0), a2, voffA);
.LBB0_716:
	ds_read_b128 v[140:143], v223
	ds_read_b128 v[144:147], v223 offset:1024
	ds_read_b128 v[148:151], v223 offset:2048
	ds_read_b128 v[152:155], v223 offset:3072
	ds_read_b128 v[156:159], v224
	ds_read_b128 v[160:163], v224 offset:1024
	ds_read_b128 v[164:167], v224 offset:2048
	ds_read_b128 v[168:171], v224 offset:3072
	s_add_u32 s26, s24, 0xfffc0080
	s_addc_u32 s27, s25, -1
	s_cmp_eq_u32 s58, 12
	s_cselect_b32 s29, s15, s27
	s_cselect_b32 s28, s21, s26
	s_cselect_b32 s27, s13, s57
	s_cselect_b32 s26, s51, s56
	v_lshl_add_u64 v[206:207], s[24:25], 0, v[132:133]
	s_add_i32 m0, s23, 0xc000
	ds_read_b128 v[172:175], v225
	ds_read_b128 v[176:179], v225 offset:1024
	ds_read_b128 v[180:183], v225 offset:2048
	ds_read_b128 v[186:189], v225 offset:3072
	ds_read_b128 v[190:193], v225 offset:4096
	ds_read_b128 v[194:197], v225 offset:5120
	ds_read_b128 v[198:201], v225 offset:6144
	ds_read_b128 v[202:205], v225 offset:7168
	global_load_lds_dwordx4 v[206:207], off
	v_lshl_add_u64 v[206:207], s[24:25], 0, v[134:135]
	s_add_i32 m0, s23, 0xe000
	s_nop 0
	global_load_lds_dwordx4 v[206:207], off
	s_waitcnt vmcnt(8)
	s_waitcnt lgkmcnt(0)
	s_barrier
	s_setprio 1
	s_waitcnt lgkmcnt(0)
	v_mfma_f32_16x16x32_bf16 v[124:127], v[140:143], v[172:175], v[124:127]
	v_mfma_f32_16x16x32_bf16 v[120:123], v[148:151], v[172:175], v[120:123]
	v_mfma_f32_16x16x32_bf16 v[108:111], v[140:143], v[180:183], v[108:111]
	v_mfma_f32_16x16x32_bf16 v[104:107], v[148:151], v[180:183], v[104:107]
	v_mfma_f32_16x16x32_bf16 v[92:95], v[140:143], v[190:193], v[92:95]
	v_mfma_f32_16x16x32_bf16 v[88:91], v[148:151], v[190:193], v[88:91]
	v_mfma_f32_16x16x32_bf16 v[76:79], v[140:143], v[198:201], v[76:79]
	v_mfma_f32_16x16x32_bf16 v[72:75], v[148:151], v[198:201], v[72:75]
	v_mfma_f32_16x16x32_bf16 v[124:127], v[144:147], v[176:179], v[124:127]
	v_mfma_f32_16x16x32_bf16 v[120:123], v[152:155], v[176:179], v[120:123]
	v_mfma_f32_16x16x32_bf16 v[108:111], v[144:147], v[186:189], v[108:111]
	v_mfma_f32_16x16x32_bf16 v[104:107], v[152:155], v[186:189], v[104:107]
	v_mfma_f32_16x16x32_bf16 v[92:95], v[144:147], v[194:197], v[92:95]
	v_mfma_f32_16x16x32_bf16 v[88:91], v[152:155], v[194:197], v[88:91]
	v_mfma_f32_16x16x32_bf16 v[76:79], v[144:147], v[202:205], v[76:79]
	v_mfma_f32_16x16x32_bf16 v[72:75], v[152:155], v[202:205], v[72:75]
	v_mfma_f32_16x16x32_bf16 v[116:119], v[156:159], v[172:175], v[116:119]
	v_mfma_f32_16x16x32_bf16 v[112:115], v[164:167], v[172:175], v[112:115]
	v_mfma_f32_16x16x32_bf16 v[100:103], v[156:159], v[180:183], v[100:103]
	v_mfma_f32_16x16x32_bf16 v[96:99], v[164:167], v[180:183], v[96:99]
	v_mfma_f32_16x16x32_bf16 v[84:87], v[156:159], v[190:193], v[84:87]
	v_mfma_f32_16x16x32_bf16 v[80:83], v[164:167], v[190:193], v[80:83]
	v_mfma_f32_16x16x32_bf16 v[68:71], v[156:159], v[198:201], v[68:71]
	v_mfma_f32_16x16x32_bf16 v[64:67], v[164:167], v[198:201], v[64:67]
	v_mfma_f32_16x16x32_bf16 v[116:119], v[160:163], v[176:179], v[116:119]
	v_mfma_f32_16x16x32_bf16 v[112:115], v[168:171], v[176:179], v[112:115]
	v_mfma_f32_16x16x32_bf16 v[100:103], v[160:163], v[186:189], v[100:103]
	v_mfma_f32_16x16x32_bf16 v[96:99], v[168:171], v[186:189], v[96:99]
	v_mfma_f32_16x16x32_bf16 v[84:87], v[160:163], v[194:197], v[84:87]
	v_mfma_f32_16x16x32_bf16 v[80:83], v[168:171], v[194:197], v[80:83]
	v_mfma_f32_16x16x32_bf16 v[68:71], v[160:163], v[202:205], v[68:71]
	v_mfma_f32_16x16x32_bf16 v[64:67], v[168:171], v[202:205], v[64:67]
	s_setprio 0
	s_barrier
	s_add_i32 s63, s49, s37
	v_lshl_add_u64 v[206:207], s[26:27], 0, v[128:129]
	s_mov_b32 m0, s63
	ds_read_b128 v[172:175], v225 offset:16384
	ds_read_b128 v[176:179], v225 offset:17408
	ds_read_b128 v[180:183], v225 offset:18432
	ds_read_b128 v[186:189], v225 offset:19456
	ds_read_b128 v[190:193], v225 offset:20480
	ds_read_b128 v[194:197], v225 offset:21504
	ds_read_b128 v[198:201], v225 offset:22528
	ds_read_b128 v[202:205], v225 offset:23552
	global_load_lds_dwordx4 v[206:207], off
	s_add_i32 m0, s63, 0x2000
	s_add_u32 s66, s26, 0x40000
	v_lshl_add_u64 v[208:209], s[26:27], 0, v[130:131]
	s_addc_u32 s67, s27, 0
	s_add_i32 s63, s50, s37
	global_load_lds_dwordx4 v[208:209], off
	v_lshl_add_u64 v[210:211], s[66:67], 0, v[128:129]
	s_mov_b32 m0, s63
	v_lshl_add_u64 v[212:213], s[28:29], 0, v[130:131]
	global_load_lds_dwordx4 v[210:211], off
	v_lshl_add_u64 v[210:211], s[66:67], 0, v[130:131]
	s_add_i32 m0, s63, 0x2000
	s_nop 0
	global_load_lds_dwordx4 v[210:211], off
	v_lshl_add_u64 v[210:211], s[28:29], 0, v[128:129]
	s_mov_b32 m0, s23
	s_nop 0
	global_load_lds_dwordx4 v[210:211], off
	s_mov_b32 m0, s38
	s_nop 0
	global_load_lds_dwordx4 v[212:213], off
	s_waitcnt vmcnt(8)
	s_waitcnt lgkmcnt(0)
	s_barrier
; #define PG8_STAGE(bufoff, gbase, voff) do { _Pragma("unroll") for (int _i = 0; _i < 2; ++_i) \
;         __builtin_amdgcn_global_load_lds((const unsigned*)((const char*)(gbase) + (voff)[_i]), (PG8_LAS unsigned*)(lds + (bufoff) + ldsw + _i * 8192), 16, 0, 0); } while (0)
; #define PG8_LDA(dst, b, h) do { _Pragma("unroll") for (int m = 0; m < 4; ++m) _Pragma("unroll") for (int k = 0; k < 2; ++k) dst[m][k] = *(const PG8_LAS bf16x8*)(lds + PG8_SA(b, h) + aoff + m * 2048 + k * 1024); } while (0)
; #define PG8_LDB(dst, b, h) do { _Pragma("unroll") for (int n = 0; n < 2; ++n) _Pragma("unroll") for (int k = 0; k < 2; ++k) dst[n][k] = *(const PG8_LAS bf16x8*)(lds + PG8_SB(b, h) + boff + n * 2048 + k * 1024); } while (0)
; #define PG8_MMA(ai, bj, At, Bt) do { __builtin_amdgcn_s_setprio(1); _Pragma("unroll") for (int m = 0; m < 4; ++m) _Pragma("unroll") for (int n = 0; n < 2; ++n) _Pragma("unroll") for (int k = 0; k < 2; ++k) \
;         acc[ai][bj][m][n] = __builtin_amdgcn_mfma_f32_16x16x32_bf16(Bt[n][k], At[m][k], acc[ai][bj][m][n], 0, 0, 0); __builtin_amdgcn_s_setprio(0); } while (0)
; #define PG8_WAIT_V(n) asm volatile("s_waitcnt vmcnt(" #n ")" ::: "memory")
; #define PG8_WAIT_L(n) asm volatile("s_waitcnt lgkmcnt(" #n ")" ::: "memory")
; #define PG8_BAR __builtin_amdgcn_s_barrier()
; #define PG8_SCHED __builtin_amdgcn_sched_barrier(0)
; template <class Epi, class Sched, bool ALIGN_EPI = false, bool SP2 = false>
; __device__ __forceinline__ void gemm_phase(PG8_LAS unsigned char* lds, const Gemm g, const Sched& S, const Epi& E) {
;     ...
;             PG8_WAIT_V(8); PG8_WAIT_L(0); PG8_BAR; PG8_MMA(1, 0, At, B0); PG8_MMA(1, 1, At, B1); PG8_BAR; PG8_SCHED;
;             PG8_LDB(B0, 1, 0); PG8_LDB(B1, 1, 1); PG8_SCHED; PG8_LDA(At, 1, 0); PG8_STAGE(PG8_SA(0, 1), a2 + hstep, voffA);
;             PG8_WAIT_V(8); PG8_WAIT_L(0); PG8_BAR; PG8_MMA(0, 0, At, B0); PG8_MMA(0, 1, At, B1); PG8_BAR; PG8_SCHED;
	s_setprio 1
	s_waitcnt lgkmcnt(0)
	v_mfma_f32_16x16x32_bf16 v[60:63], v[140:143], v[172:175], v[60:63]
	v_mfma_f32_16x16x32_bf16 v[56:59], v[148:151], v[172:175], v[56:59]
	v_mfma_f32_16x16x32_bf16 v[44:47], v[140:143], v[180:183], v[44:47]
	v_mfma_f32_16x16x32_bf16 v[40:43], v[148:151], v[180:183], v[40:43]
	v_mfma_f32_16x16x32_bf16 v[28:31], v[140:143], v[190:193], v[28:31]
	v_mfma_f32_16x16x32_bf16 v[24:27], v[148:151], v[190:193], v[24:27]
	v_mfma_f32_16x16x32_bf16 v[12:15], v[140:143], v[198:201], v[12:15]
	v_mfma_f32_16x16x32_bf16 v[8:11], v[148:151], v[198:201], v[8:11]
	v_mfma_f32_16x16x32_bf16 v[60:63], v[144:147], v[176:179], v[60:63]
	v_mfma_f32_16x16x32_bf16 v[56:59], v[152:155], v[176:179], v[56:59]
	v_mfma_f32_16x16x32_bf16 v[44:47], v[144:147], v[186:189], v[44:47]
	v_mfma_f32_16x16x32_bf16 v[40:43], v[152:155], v[186:189], v[40:43]
	v_mfma_f32_16x16x32_bf16 v[28:31], v[144:147], v[194:197], v[28:31]
	v_mfma_f32_16x16x32_bf16 v[24:27], v[152:155], v[194:197], v[24:27]
	v_mfma_f32_16x16x32_bf16 v[12:15], v[144:147], v[202:205], v[12:15]
	v_mfma_f32_16x16x32_bf16 v[8:11], v[152:155], v[202:205], v[8:11]
	v_mfma_f32_16x16x32_bf16 v[52:55], v[156:159], v[172:175], v[52:55]
	v_mfma_f32_16x16x32_bf16 v[48:51], v[164:167], v[172:175], v[48:51]
	v_mfma_f32_16x16x32_bf16 v[36:39], v[156:159], v[180:183], v[36:39]
	v_mfma_f32_16x16x32_bf16 v[32:35], v[164:167], v[180:183], v[32:35]
	v_mfma_f32_16x16x32_bf16 v[20:23], v[156:159], v[190:193], v[20:23]
	v_mfma_f32_16x16x32_bf16 v[16:19], v[164:167], v[190:193], v[16:19]
	v_mfma_f32_16x16x32_bf16 v[4:7], v[156:159], v[198:201], v[4:7]
	v_mfma_f32_16x16x32_bf16 v[0:3], v[164:167], v[198:201], v[0:3]
	v_mfma_f32_16x16x32_bf16 v[52:55], v[160:163], v[176:179], v[52:55]
	v_mfma_f32_16x16x32_bf16 v[48:51], v[168:171], v[176:179], v[48:51]
	v_mfma_f32_16x16x32_bf16 v[36:39], v[160:163], v[186:189], v[36:39]
	v_mfma_f32_16x16x32_bf16 v[32:35], v[168:171], v[186:189], v[32:35]
	v_mfma_f32_16x16x32_bf16 v[20:23], v[160:163], v[194:197], v[20:23]
	v_mfma_f32_16x16x32_bf16 v[16:19], v[168:171], v[194:197], v[16:19]
	v_mfma_f32_16x16x32_bf16 v[4:7], v[160:163], v[202:205], v[4:7]
	v_mfma_f32_16x16x32_bf16 v[0:3], v[168:171], v[202:205], v[0:3]
	s_setprio 0
	s_barrier
	s_add_i32 s63, 0, 0x18000
	s_add_i32 s66, 0, 0x1c000
	v_add_u32_e32 v152, s63, v221
	v_add_u32_e32 v168, s66, v221
	ds_read_b128 v[140:143], v152
	ds_read_b128 v[144:147], v152 offset:1024
	ds_read_b128 v[148:151], v152 offset:2048
	ds_read_b128 v[152:155], v152 offset:3072
	ds_read_b128 v[156:159], v168
	ds_read_b128 v[160:163], v168 offset:1024
	ds_read_b128 v[164:167], v168 offset:2048
	ds_read_b128 v[168:171], v168 offset:3072
	s_add_u32 s28, s28, 0x40000
	s_addc_u32 s29, s29, 0
	s_mov_b32 m0, s39
	v_lshl_add_u64 v[214:215], s[28:29], 0, v[128:129]
	ds_read_b128 v[172:175], v225 offset:32768
	ds_read_b128 v[176:179], v225 offset:33792
	ds_read_b128 v[180:183], v225 offset:34816
	ds_read_b128 v[186:189], v225 offset:35840
	ds_read_b128 v[190:193], v225 offset:36864
	ds_read_b128 v[194:197], v225 offset:37888
	ds_read_b128 v[198:201], v225 offset:38912
	ds_read_b128 v[202:205], v225 offset:39936
	global_load_lds_dwordx4 v[214:215], off
	v_lshl_add_u64 v[214:215], s[28:29], 0, v[130:131]
	s_mov_b32 m0, s42
	s_nop 0
	global_load_lds_dwordx4 v[214:215], off
	s_waitcnt vmcnt(8)
	s_waitcnt lgkmcnt(0)
	s_barrier
	s_setprio 1
	s_waitcnt lgkmcnt(0)
	v_mfma_f32_16x16x32_bf16 v[124:127], v[140:143], v[172:175], v[124:127]
	v_mfma_f32_16x16x32_bf16 v[120:123], v[148:151], v[172:175], v[120:123]
	v_mfma_f32_16x16x32_bf16 v[108:111], v[140:143], v[180:183], v[108:111]
	v_mfma_f32_16x16x32_bf16 v[104:107], v[148:151], v[180:183], v[104:107]
	v_mfma_f32_16x16x32_bf16 v[92:95], v[140:143], v[190:193], v[92:95]
	v_mfma_f32_16x16x32_bf16 v[88:91], v[148:151], v[190:193], v[88:91]
	v_mfma_f32_16x16x32_bf16 v[76:79], v[140:143], v[198:201], v[76:79]
	v_mfma_f32_16x16x32_bf16 v[72:75], v[148:151], v[198:201], v[72:75]
	v_mfma_f32_16x16x32_bf16 v[124:127], v[144:147], v[176:179], v[124:127]
	v_mfma_f32_16x16x32_bf16 v[120:123], v[152:155], v[176:179], v[120:123]
	v_mfma_f32_16x16x32_bf16 v[108:111], v[144:147], v[186:189], v[108:111]
	v_mfma_f32_16x16x32_bf16 v[104:107], v[152:155], v[186:189], v[104:107]
	v_mfma_f32_16x16x32_bf16 v[92:95], v[144:147], v[194:197], v[92:95]
	v_mfma_f32_16x16x32_bf16 v[88:91], v[152:155], v[194:197], v[88:91]
	v_mfma_f32_16x16x32_bf16 v[76:79], v[144:147], v[202:205], v[76:79]
	v_mfma_f32_16x16x32_bf16 v[72:75], v[152:155], v[202:205], v[72:75]
	v_mfma_f32_16x16x32_bf16 v[116:119], v[156:159], v[172:175], v[116:119]
	v_mfma_f32_16x16x32_bf16 v[112:115], v[164:167], v[172:175], v[112:115]
	v_mfma_f32_16x16x32_bf16 v[100:103], v[156:159], v[180:183], v[100:103]
	v_mfma_f32_16x16x32_bf16 v[96:99], v[164:167], v[180:183], v[96:99]
	v_mfma_f32_16x16x32_bf16 v[84:87], v[156:159], v[190:193], v[84:87]
	v_mfma_f32_16x16x32_bf16 v[80:83], v[164:167], v[190:193], v[80:83]
	v_mfma_f32_16x16x32_bf16 v[68:71], v[156:159], v[198:201], v[68:71]
	v_mfma_f32_16x16x32_bf16 v[64:67], v[164:167], v[198:201], v[64:67]
	v_mfma_f32_16x16x32_bf16 v[116:119], v[160:163], v[176:179], v[116:119]
	v_mfma_f32_16x16x32_bf16 v[112:115], v[168:171], v[176:179], v[112:115]
	v_mfma_f32_16x16x32_bf16 v[100:103], v[160:163], v[186:189], v[100:103]
	v_mfma_f32_16x16x32_bf16 v[96:99], v[168:171], v[186:189], v[96:99]
	v_mfma_f32_16x16x32_bf16 v[84:87], v[160:163], v[194:197], v[84:87]
	v_mfma_f32_16x16x32_bf16 v[80:83], v[168:171], v[194:197], v[80:83]
	v_mfma_f32_16x16x32_bf16 v[68:71], v[160:163], v[202:205], v[68:71]
	v_mfma_f32_16x16x32_bf16 v[64:67], v[168:171], v[202:205], v[64:67]
	s_setprio 0
	s_barrier
; #define PG8_STAGE(bufoff, gbase, voff) do { _Pragma("unroll") for (int _i = 0; _i < 2; ++_i) \
;         __builtin_amdgcn_global_load_lds((const unsigned*)((const char*)(gbase) + (voff)[_i]), (PG8_LAS unsigned*)(lds + (bufoff) + ldsw + _i * 8192), 16, 0, 0); } while (0)
; #define PG8_LDA(dst, b, h) do { _Pragma("unroll") for (int m = 0; m < 4; ++m) _Pragma("unroll") for (int k = 0; k < 2; ++k) dst[m][k] = *(const PG8_LAS bf16x8*)(lds + PG8_SA(b, h) + aoff + m * 2048 + k * 1024); } while (0)
; #define PG8_MMA(ai, bj, At, Bt) do { __builtin_amdgcn_s_setprio(1); _Pragma("unroll") for (int m = 0; m < 4; ++m) _Pragma("unroll") for (int n = 0; n < 2; ++n) _Pragma("unroll") for (int k = 0; k < 2; ++k) \
;         acc[ai][bj][m][n] = __builtin_amdgcn_mfma_f32_16x16x32_bf16(Bt[n][k], At[m][k], acc[ai][bj][m][n], 0, 0, 0); __builtin_amdgcn_s_setprio(0); } while (0)
; #define PG8_WAIT_V(n) asm volatile("s_waitcnt vmcnt(" #n ")" ::: "memory")
; #define PG8_WAIT_L(n) asm volatile("s_waitcnt lgkmcnt(" #n ")" ::: "memory")
; #define PG8_BAR __builtin_amdgcn_s_barrier()
; #define PG8_SCHED __builtin_amdgcn_sched_barrier(0)
; template <class Epi, class Sched, bool ALIGN_EPI = false, bool SP2 = false>
; __device__ __forceinline__ void gemm_phase(PG8_LAS unsigned char* lds, const Gemm g, const Sched& S, const Epi& E) {
;     ...
;             PG8_LDA(At, 1, 1); PG8_STAGE(PG8_SB(1, 0), b3, voffB); PG8_STAGE(PG8_SB(1, 1), b3 + hstep, voffB); PG8_STAGE(PG8_SA(1, 0), a3, voffA);
;             PG8_WAIT_V(8); PG8_WAIT_L(0); PG8_BAR; PG8_MMA(1, 0, At, B0); PG8_MMA(1, 1, At, B1); PG8_BAR; PG8_SCHED;
	s_add_i32 s28, s63, s37
	v_lshl_add_u64 v[206:207], v[206:207], 0, s[10:11]
	s_mov_b32 m0, s28
	ds_read_b128 v[172:175], v225 offset:49152
	ds_read_b128 v[176:179], v225 offset:50176
	ds_read_b128 v[180:183], v225 offset:51200
	ds_read_b128 v[186:189], v225 offset:52224
	ds_read_b128 v[190:193], v225 offset:53248
	ds_read_b128 v[194:197], v225 offset:54272
	ds_read_b128 v[198:201], v225 offset:55296
	ds_read_b128 v[202:205], v225 offset:56320
	global_load_lds_dwordx4 v[206:207], off
	s_add_i32 m0, s28, 0x2000
	s_add_u32 s26, s26, 0x40080
	v_lshl_add_u64 v[206:207], v[208:209], 0, s[10:11]
	s_addc_u32 s27, s27, 0
	s_add_i32 s28, s66, s37
	global_load_lds_dwordx4 v[206:207], off
	v_lshl_add_u64 v[206:207], s[26:27], 0, v[128:129]
	s_mov_b32 m0, s28
	s_nop 0
	global_load_lds_dwordx4 v[206:207], off
	v_lshl_add_u64 v[206:207], s[26:27], 0, v[130:131]
	s_add_i32 m0, s28, 0x2000
	s_nop 0
	global_load_lds_dwordx4 v[206:207], off
	v_lshl_add_u64 v[206:207], v[210:211], 0, s[10:11]
	s_mov_b32 m0, s44
	s_nop 0
	global_load_lds_dwordx4 v[206:207], off
	v_lshl_add_u64 v[206:207], v[212:213], 0, s[10:11]
	s_mov_b32 m0, s45
	s_nop 0
	global_load_lds_dwordx4 v[206:207], off
	s_waitcnt vmcnt(8)
	s_waitcnt lgkmcnt(0)
	s_barrier
	s_setprio 1
	s_waitcnt lgkmcnt(0)
	v_mfma_f32_16x16x32_bf16 v[60:63], v[140:143], v[172:175], v[60:63]
	v_mfma_f32_16x16x32_bf16 v[56:59], v[148:151], v[172:175], v[56:59]
	v_mfma_f32_16x16x32_bf16 v[44:47], v[140:143], v[180:183], v[44:47]
	v_mfma_f32_16x16x32_bf16 v[40:43], v[148:151], v[180:183], v[40:43]
	v_mfma_f32_16x16x32_bf16 v[28:31], v[140:143], v[190:193], v[28:31]
	v_mfma_f32_16x16x32_bf16 v[24:27], v[148:151], v[190:193], v[24:27]
	v_mfma_f32_16x16x32_bf16 v[12:15], v[140:143], v[198:201], v[12:15]
	v_mfma_f32_16x16x32_bf16 v[8:11], v[148:151], v[198:201], v[8:11]
	v_mfma_f32_16x16x32_bf16 v[60:63], v[144:147], v[176:179], v[60:63]
	v_mfma_f32_16x16x32_bf16 v[56:59], v[152:155], v[176:179], v[56:59]
	v_mfma_f32_16x16x32_bf16 v[44:47], v[144:147], v[186:189], v[44:47]
	v_mfma_f32_16x16x32_bf16 v[40:43], v[152:155], v[186:189], v[40:43]
	v_mfma_f32_16x16x32_bf16 v[28:31], v[144:147], v[194:197], v[28:31]
	v_mfma_f32_16x16x32_bf16 v[24:27], v[152:155], v[194:197], v[24:27]
	v_mfma_f32_16x16x32_bf16 v[12:15], v[144:147], v[202:205], v[12:15]
	v_mfma_f32_16x16x32_bf16 v[8:11], v[152:155], v[202:205], v[8:11]
	v_mfma_f32_16x16x32_bf16 v[52:55], v[156:159], v[172:175], v[52:55]
	v_mfma_f32_16x16x32_bf16 v[48:51], v[164:167], v[172:175], v[48:51]
	v_mfma_f32_16x16x32_bf16 v[36:39], v[156:159], v[180:183], v[36:39]
	v_mfma_f32_16x16x32_bf16 v[32:35], v[164:167], v[180:183], v[32:35]
	v_mfma_f32_16x16x32_bf16 v[20:23], v[156:159], v[190:193], v[20:23]
	v_mfma_f32_16x16x32_bf16 v[16:19], v[164:167], v[190:193], v[16:19]
	v_mfma_f32_16x16x32_bf16 v[4:7], v[156:159], v[198:201], v[4:7]
	v_mfma_f32_16x16x32_bf16 v[0:3], v[164:167], v[198:201], v[0:3]
	v_mfma_f32_16x16x32_bf16 v[52:55], v[160:163], v[176:179], v[52:55]
	v_mfma_f32_16x16x32_bf16 v[48:51], v[168:171], v[176:179], v[48:51]
	v_mfma_f32_16x16x32_bf16 v[36:39], v[160:163], v[186:189], v[36:39]
	v_mfma_f32_16x16x32_bf16 v[32:35], v[168:171], v[186:189], v[32:35]
	v_mfma_f32_16x16x32_bf16 v[20:23], v[160:163], v[194:197], v[20:23]
	v_mfma_f32_16x16x32_bf16 v[16:19], v[168:171], v[194:197], v[16:19]
	v_mfma_f32_16x16x32_bf16 v[4:7], v[160:163], v[202:205], v[4:7]
	v_mfma_f32_16x16x32_bf16 v[0:3], v[168:171], v[202:205], v[0:3]
	s_setprio 0
	s_barrier
	s_add_i32 s58, s58, 2
	s_add_u32 s24, s24, 0x100
	s_addc_u32 s25, s25, 0
	s_add_u32 s56, s56, 0x100
	s_addc_u32 s57, s57, 0
	s_cmp_gt_u32 s58, 13
	s_cbranch_scc0 .LBB0_716
; __device__ __forceinline__ unsigned cvt_pk_bf16(float lo, float hi) { unsigned r; asm volatile("v_cvt_pk_bf16_f32 %0, %1, %2" : "=v"(r) : "v"(lo), "v"(hi)); return r; }
;     __device__ __forceinline__ void operator()(const f32x4 (&acc)[2][2][4][2], const Unit& u, int wr, int wc, int fr, int fq) const {
;         const int row0 = u.pm * BM + wr * 64 + fr, col0 = u.pn * BM + wc * 32 + 4 * fq;
;         unsigned long long rb[2][4][2][2];
;         if (BB) {
; #pragma unroll
;             for (int ai = 0; ai < 2; ++ai)
; #pragma unroll
;                 for (int m = 0; m < 4; ++m)
; #pragma unroll
;                     for (int bj = 0; bj < 2; ++bj)
; #pragma unroll
;                         for (int n = 0; n < 2; ++n) rb[ai][m][bj][n] = *(const unsigned long long*)((const bf16_t*)base + (size_t)(row0 + ai * HALF + m * 16) * ldc + col0 + bj * HALF + n * 16);
;             asm volatile("" ::: "memory"); }
; #pragma unroll
;         for (int ai = 0; ai < 2; ++ai)
; #pragma unroll
;             for (int m = 0; m < 4; ++m) { const int row = row0 + ai * HALF + m * 16; const size_t off = (size_t)row * ldc + col0; float s = 0.f;
; #pragma unroll
;                 for (int bj = 0; bj < 2; ++bj)
; #pragma unroll
;                     for (int n = 0; n < 2; ++n) { f32x4 bs;
;                         if (BB) { const unsigned long long rw = rb[ai][m][bj][n]; const unsigned lo = (unsigned)rw, hi = (unsigned)(rw >> 32);
;                             bs = (f32x4){__uint_as_float(lo << 16), __uint_as_float(lo & 0xffff0000u), __uint_as_float(hi << 16), __uint_as_float(hi & 0xffff0000u)}; }
;                         else bs = *(const f32x4*)((const float*)base + off + bj * HALF + n * 16);
;                         const f32x4 v = bs + acc[ai][bj][m][n];
;                         if (WF) *(f32x4*)(out + off + bj * HALF + n * 16) = v;
;                         s += (v[0] * v[0] + v[1] * v[1]) + (v[2] * v[2] + v[3] * v[3]);
;                         if (WB) { unsigned lo = cvt_pk_bf16(v[0], v[1]), hi = cvt_pk_bf16(v[2], v[3]); *(unsigned long long*)(outb + off + bj * HALF + n * 16) = (unsigned long long)lo | ((unsigned long long)hi << 32); } }
;                 s += __shfl_xor(s, 16); s += __shfl_xor(s, 32);
;                 if (fq == 0) atomicAdd(ssq + row, s);
	v_lshl_add_u32 v212, s20, 8, v220
	v_lshl_or_b32 v140, s22, 8, v222
	v_ashrrev_i32_e32 v141, 31, v140
	v_ashrrev_i32_e32 v213, 31, v212
	v_lshl_add_u64 v[144:145], v[140:141], 1, s[6:7]
	v_lshlrev_b64 v[142:143], 11, v[212:213]
	v_lshl_add_u64 v[142:143], v[144:145], 0, v[142:143]
	global_load_dwordx2 v[228:229], v[142:143], off
	global_load_dwordx2 v[230:231], v[142:143], off offset:32
	global_load_dwordx2 v[234:235], v[142:143], off offset:256
	global_load_dwordx2 v[236:237], v[142:143], off offset:288
	v_or_b32_e32 v202, 16, v212
	v_ashrrev_i32_e32 v203, 31, v202
	v_lshlrev_b64 v[142:143], 11, v[202:203]
	v_or_b32_e32 v192, 32, v212
	v_lshl_add_u64 v[142:143], v[144:145], 0, v[142:143]
	v_ashrrev_i32_e32 v193, 31, v192
	global_load_dwordx2 v[214:215], v[142:143], off
	global_load_dwordx2 v[210:211], v[142:143], off offset:32
	global_load_dwordx2 v[208:209], v[142:143], off offset:256
	global_load_dwordx2 v[206:207], v[142:143], off offset:288
	v_lshlrev_b64 v[142:143], 11, v[192:193]
	v_or_b32_e32 v180, 48, v212
	v_lshl_add_u64 v[142:143], v[144:145], 0, v[142:143]
	v_ashrrev_i32_e32 v181, 31, v180
	global_load_dwordx2 v[204:205], v[142:143], off
	global_load_dwordx2 v[200:201], v[142:143], off offset:32
	global_load_dwordx2 v[198:199], v[142:143], off offset:256
	global_load_dwordx2 v[196:197], v[142:143], off offset:288
	v_lshlrev_b64 v[142:143], 11, v[180:181]
	v_add_u32_e32 v170, 0x80, v212
	v_lshl_add_u64 v[142:143], v[144:145], 0, v[142:143]
	v_ashrrev_i32_e32 v171, 31, v170
	global_load_dwordx2 v[194:195], v[142:143], off
	global_load_dwordx2 v[190:191], v[142:143], off offset:32
	global_load_dwordx2 v[188:189], v[142:143], off offset:256
	global_load_dwordx2 v[186:187], v[142:143], off offset:288
	v_lshlrev_b64 v[142:143], 11, v[170:171]
	v_add_u32_e32 v160, 0x90, v212
	v_lshl_add_u64 v[142:143], v[144:145], 0, v[142:143]
	v_ashrrev_i32_e32 v161, 31, v160
	global_load_dwordx2 v[182:183], v[142:143], off
	global_load_dwordx2 v[178:179], v[142:143], off offset:32
	global_load_dwordx2 v[176:177], v[142:143], off offset:256
	global_load_dwordx2 v[174:175], v[142:143], off offset:288
	v_lshlrev_b64 v[142:143], 11, v[160:161]
	v_add_u32_e32 v150, 0xa0, v212
	v_lshl_add_u64 v[142:143], v[144:145], 0, v[142:143]
	v_ashrrev_i32_e32 v151, 31, v150
	global_load_dwordx2 v[172:173], v[142:143], off
	global_load_dwordx2 v[168:169], v[142:143], off offset:32
	global_load_dwordx2 v[166:167], v[142:143], off offset:256
	global_load_dwordx2 v[164:165], v[142:143], off offset:288
	v_lshlrev_b64 v[142:143], 11, v[150:151]
	v_lshl_add_u64 v[142:143], v[144:145], 0, v[142:143]
	global_load_dwordx2 v[162:163], v[142:143], off
	global_load_dwordx2 v[158:159], v[142:143], off offset:32
	global_load_dwordx2 v[156:157], v[142:143], off offset:256
	global_load_dwordx2 v[154:155], v[142:143], off offset:288
	v_add_u32_e32 v142, 0xb0, v212
	v_ashrrev_i32_e32 v143, 31, v142
	v_lshlrev_b64 v[146:147], 11, v[142:143]
	v_lshl_add_u64 v[144:145], v[144:145], 0, v[146:147]
	global_load_dwordx2 v[152:153], v[144:145], off
	global_load_dwordx2 v[148:149], v[144:145], off offset:32
	global_load_dwordx2 v[146:147], v[144:145], off offset:256
	s_nop 0
	global_load_dwordx2 v[144:145], v[144:145], off offset:288
	v_and_b32_e32 v233, 64, v226
	v_xor_b32_e32 v227, 16, v226
	v_add_u32_e32 v233, 64, v233
	v_xor_b32_e32 v238, 32, v226
	v_cmp_lt_i32_e32 vcc, v227, v233
	s_waitcnt vmcnt(0)
	v_and_b32_e32 v239, 0xffff0000, v228
	v_cndmask_b32_e32 v227, v226, v227, vcc
	v_cmp_lt_i32_e32 vcc, v238, v233
	v_lshlrev_b32_e32 v240, 16, v230
	v_and_b32_e32 v241, 0xffff0000, v230
	v_cndmask_b32_e32 v233, v226, v238, vcc
	v_lshlrev_b32_e32 v238, 16, v228
	v_lshlrev_b32_e32 v228, 16, v229
	v_and_b32_e32 v229, 0xffff0000, v229
	v_pk_add_f32 v[126:127], v[126:127], v[228:229]
	v_pk_add_f32 v[124:125], v[124:125], v[238:239]
	v_mul_f32_e32 v229, v127, v127
	v_mul_f32_e32 v228, v125, v125
	v_fmac_f32_e32 v228, v124, v124
	v_fmac_f32_e32 v229, v126, v126
	v_add_f32_e32 v238, v228, v229
	v_lshlrev_b32_e32 v228, 16, v231
	v_and_b32_e32 v229, 0xffff0000, v231
	v_pk_add_f32 v[122:123], v[122:123], v[228:229]
	v_pk_add_f32 v[120:121], v[120:121], v[240:241]
	v_mul_f32_e32 v229, v123, v123
	v_mul_f32_e32 v228, v121, v121
	v_fmac_f32_e32 v228, v120, v120
	v_fmac_f32_e32 v229, v122, v122
	v_add_f32_e32 v228, v228, v229
	v_add_f32_e32 v238, v238, v228
	v_lshlrev_b32_e32 v228, 16, v234
	v_and_b32_e32 v229, 0xffff0000, v234
	v_lshlrev_b32_e32 v230, 16, v235
	v_and_b32_e32 v231, 0xffff0000, v235
	v_pk_add_f32 v[118:119], v[118:119], v[230:231]
	v_pk_add_f32 v[116:117], v[116:117], v[228:229]
	v_mul_f32_e32 v229, v119, v119
	v_mul_f32_e32 v228, v117, v117
	v_fmac_f32_e32 v228, v116, v116
	v_fmac_f32_e32 v229, v118, v118
	v_add_f32_e32 v228, v228, v229
	v_add_f32_e32 v234, v238, v228
	v_lshlrev_b32_e32 v228, 16, v236
	v_and_b32_e32 v229, 0xffff0000, v236
	v_lshlrev_b32_e32 v230, 16, v237
	v_and_b32_e32 v231, 0xffff0000, v237
	v_pk_add_f32 v[230:231], v[114:115], v[230:231]
	v_pk_add_f32 v[228:229], v[112:113], v[228:229]
	v_mul_f32_e32 v113, v231, v231
	v_mul_f32_e32 v112, v229, v229
	v_fmac_f32_e32 v112, v228, v228
	v_fmac_f32_e32 v113, v230, v230
	v_add_f32_e32 v112, v112, v113
	v_lshlrev_b32_e32 v227, 2, v227
	v_add_f32_e32 v113, v234, v112
	ds_bpermute_b32 v236, v227, v113
	v_lshlrev_b64 v[114:115], 12, v[212:213]
	v_lshlrev_b32_e32 v112, 2, v233
	v_lshl_add_u64 v[114:115], s[52:53], 0, v[114:115]
	v_lshl_add_u64 v[234:235], v[140:141], 2, v[114:115]
	s_waitcnt lgkmcnt(0)
	v_add_f32_e32 v113, v113, v236
	ds_bpermute_b32 v114, v112, v113
	global_store_dwordx4 v[234:235], v[124:127], off
	global_store_dwordx4 v[234:235], v[120:123], off offset:64
	global_store_dwordx4 v[234:235], v[116:119], off offset:512
	global_store_dwordx4 v[234:235], v[228:231], off offset:576
	s_and_saveexec_b64 s[20:21], s[2:3]
	s_cbranch_execz .LBB0_719
	v_lshl_add_u64 v[116:117], v[212:213], 2, s[8:9]
	s_waitcnt lgkmcnt(0)
	v_add_f32_e32 v113, v113, v114
	global_atomic_add_f32 v[116:117], v113, off

; #define PG8_STAGE(bufoff, gbase, voff) do { _Pragma("unroll") for (int _i = 0; _i < 2; ++_i) \
;         __builtin_amdgcn_global_load_lds((const unsigned*)((const char*)(gbase) + (voff)[_i]), (PG8_LAS unsigned*)(lds + (bufoff) + ldsw + _i * 8192), 16, 0, 0); } while (0)
; #define PG8_LDA(dst, b, h) do { _Pragma("unroll") for (int m = 0; m < 4; ++m) _Pragma("unroll") for (int k = 0; k < 2; ++k) dst[m][k] = *(const PG8_LAS bf16x8*)(lds + PG8_SA(b, h) + aoff + m * 2048 + k * 1024); } while (0)
; #define PG8_LDB(dst, b, h) do { _Pragma("unroll") for (int n = 0; n < 2; ++n) _Pragma("unroll") for (int k = 0; k < 2; ++k) dst[n][k] = *(const PG8_LAS bf16x8*)(lds + PG8_SB(b, h) + boff + n * 2048 + k * 1024); } while (0)
; #define PG8_MMA(ai, bj, At, Bt) do { __builtin_amdgcn_s_setprio(1); _Pragma("unroll") for (int m = 0; m < 4; ++m) _Pragma("unroll") for (int n = 0; n < 2; ++n) _Pragma("unroll") for (int k = 0; k < 2; ++k) \
;         acc[ai][bj][m][n] = __builtin_amdgcn_mfma_f32_16x16x32_bf16(Bt[n][k], At[m][k], acc[ai][bj][m][n], 0, 0, 0); __builtin_amdgcn_s_setprio(0); } while (0)
; #define PG8_WAIT_V(n) asm volatile("s_waitcnt vmcnt(" #n ")" ::: "memory")
; #define PG8_WAIT_L(n) asm volatile("s_waitcnt lgkmcnt(" #n ")" ::: "memory")
; #define PG8_BAR __builtin_amdgcn_s_barrier()
; #define PG8_SCHED __builtin_amdgcn_sched_barrier(0)
; template <class Epi, class Sched, bool ALIGN_EPI = false, bool SP2 = false>
; __device__ __forceinline__ void gemm_phase(PG8_LAS unsigned char* lds, const Gemm g, const Sched& S, const Epi& E) {
;     ...
;             PG8_LDB(B0, 0, 0); PG8_LDB(B1, 0, 1); PG8_SCHED; PG8_LDA(At, 0, 0); PG8_STAGE(PG8_SA(1, 1), a1 + hstep, voffA);
;             PG8_WAIT_V(8); PG8_WAIT_L(0); PG8_BAR; PG8_MMA(0, 0, At, B0); PG8_MMA(0, 1, At, B1); PG8_BAR; PG8_SCHED;
;             PG8_LDA(At, 0, 1); PG8_STAGE(PG8_SB(0, 0), b2, voffB); PG8_STAGE(PG8_SB(0, 1), b2 + hstep, voffB); PG8_STAGE(PG8_SA(0, 0), a2, voffA);
;             PG8_WAIT_V(8); PG8_WAIT_L(0); PG8_BAR; PG8_MMA(1, 0, At, B0); PG8_MMA(1, 1, At, B1); PG8_BAR; PG8_SCHED;
.LBB0_809:
	v_add_u32_e32 v147, s49, v145
	ds_read_b128 v[148:151], v147
	ds_read_b128 v[152:155], v147 offset:1024
	ds_read_b128 v[156:159], v147 offset:2048
	ds_read_b128 v[160:163], v147 offset:3072
	v_add_u32_e32 v147, s50, v145
	s_add_u32 s26, s10, s24
	ds_read_b128 v[164:167], v147
	ds_read_b128 v[168:171], v147 offset:1024
	ds_read_b128 v[172:175], v147 offset:2048
	ds_read_b128 v[176:179], v147 offset:3072
	s_addc_u32 s27, s11, s25
	s_add_u32 s26, s26, 0x100
	s_addc_u32 s27, s27, 0
	s_add_u32 s59, s21, s24
	s_addc_u32 s60, s51, s25
	s_cmpk_eq_i32 s24, 0x700
	s_cselect_b32 s29, s17, s27
	s_cselect_b32 s28, s56, s26
	s_cselect_b32 s27, s15, s60
	s_cselect_b32 s26, s57, s59
	v_lshl_add_u64 v[184:185], v[140:141], 0, s[24:25]
	s_add_i32 m0, s39, 0xc000
	ds_read_b128 v[180:183], v146
	ds_read_b128 v[188:191], v146 offset:1024
	ds_read_b128 v[192:195], v146 offset:2048
	ds_read_b128 v[196:199], v146 offset:3072
	ds_read_b128 v[200:203], v146 offset:4096
	ds_read_b128 v[204:207], v146 offset:5120
	ds_read_b128 v[208:211], v146 offset:6144
	ds_read_b128 v[212:215], v146 offset:7168
	global_load_lds_dwordx4 v[184:185], off
	v_lshl_add_u64 v[184:185], v[142:143], 0, s[24:25]
	s_add_i32 m0, s39, 0xe000
	s_nop 0
	global_load_lds_dwordx4 v[184:185], off
	s_waitcnt vmcnt(8)
	s_waitcnt lgkmcnt(0)
	s_barrier
	s_setprio 1
	s_waitcnt lgkmcnt(0)
	v_mfma_f32_16x16x32_bf16 v[124:127], v[148:151], v[180:183], v[124:127]
	v_mfma_f32_16x16x32_bf16 v[120:123], v[156:159], v[180:183], v[120:123]
	v_mfma_f32_16x16x32_bf16 v[108:111], v[148:151], v[192:195], v[108:111]
	v_mfma_f32_16x16x32_bf16 v[104:107], v[156:159], v[192:195], v[104:107]
	v_mfma_f32_16x16x32_bf16 v[92:95], v[148:151], v[200:203], v[92:95]
	v_mfma_f32_16x16x32_bf16 v[88:91], v[156:159], v[200:203], v[88:91]
	v_mfma_f32_16x16x32_bf16 v[76:79], v[148:151], v[208:211], v[76:79]
	v_mfma_f32_16x16x32_bf16 v[72:75], v[156:159], v[208:211], v[72:75]
	v_mfma_f32_16x16x32_bf16 v[124:127], v[152:155], v[188:191], v[124:127]
	v_mfma_f32_16x16x32_bf16 v[120:123], v[160:163], v[188:191], v[120:123]
	v_mfma_f32_16x16x32_bf16 v[108:111], v[152:155], v[196:199], v[108:111]
	v_mfma_f32_16x16x32_bf16 v[104:107], v[160:163], v[196:199], v[104:107]
	v_mfma_f32_16x16x32_bf16 v[92:95], v[152:155], v[204:207], v[92:95]
	v_mfma_f32_16x16x32_bf16 v[88:91], v[160:163], v[204:207], v[88:91]
	v_mfma_f32_16x16x32_bf16 v[76:79], v[152:155], v[212:215], v[76:79]
	v_mfma_f32_16x16x32_bf16 v[72:75], v[160:163], v[212:215], v[72:75]
	v_mfma_f32_16x16x32_bf16 v[116:119], v[164:167], v[180:183], v[116:119]
	v_mfma_f32_16x16x32_bf16 v[112:115], v[172:175], v[180:183], v[112:115]
	v_mfma_f32_16x16x32_bf16 v[100:103], v[164:167], v[192:195], v[100:103]
	v_mfma_f32_16x16x32_bf16 v[96:99], v[172:175], v[192:195], v[96:99]
	v_mfma_f32_16x16x32_bf16 v[84:87], v[164:167], v[200:203], v[84:87]
	v_mfma_f32_16x16x32_bf16 v[80:83], v[172:175], v[200:203], v[80:83]
	v_mfma_f32_16x16x32_bf16 v[68:71], v[164:167], v[208:211], v[68:71]
	v_mfma_f32_16x16x32_bf16 v[64:67], v[172:175], v[208:211], v[64:67]
	v_mfma_f32_16x16x32_bf16 v[116:119], v[168:171], v[188:191], v[116:119]
	v_mfma_f32_16x16x32_bf16 v[112:115], v[176:179], v[188:191], v[112:115]
	v_mfma_f32_16x16x32_bf16 v[100:103], v[168:171], v[196:199], v[100:103]
	v_mfma_f32_16x16x32_bf16 v[96:99], v[176:179], v[196:199], v[96:99]
	v_mfma_f32_16x16x32_bf16 v[84:87], v[168:171], v[204:207], v[84:87]
	v_mfma_f32_16x16x32_bf16 v[80:83], v[176:179], v[204:207], v[80:83]
	v_mfma_f32_16x16x32_bf16 v[68:71], v[168:171], v[212:215], v[68:71]
	v_mfma_f32_16x16x32_bf16 v[64:67], v[176:179], v[212:215], v[64:67]
	s_setprio 0
	s_barrier
	s_add_i32 s59, s49, s38
	v_lshl_add_u64 v[184:185], s[26:27], 0, v[128:129]
	s_mov_b32 m0, s59
	ds_read_b128 v[180:183], v146 offset:16384
	ds_read_b128 v[188:191], v146 offset:17408
	ds_read_b128 v[192:195], v146 offset:18432
	ds_read_b128 v[196:199], v146 offset:19456
	ds_read_b128 v[200:203], v146 offset:20480
	ds_read_b128 v[204:207], v146 offset:21504
	ds_read_b128 v[208:211], v146 offset:22528
	ds_read_b128 v[212:215], v146 offset:23552
	global_load_lds_dwordx4 v[184:185], off
	s_add_i32 m0, s59, 0x2000
	s_add_u32 s60, s26, 0x40000
	v_lshl_add_u64 v[218:219], s[26:27], 0, v[130:131]
	s_addc_u32 s61, s27, 0
	s_add_i32 s59, s50, s38
	global_load_lds_dwordx4 v[218:219], off
	v_lshl_add_u64 v[220:221], s[60:61], 0, v[128:129]
	s_mov_b32 m0, s59
	v_lshl_add_u64 v[222:223], s[28:29], 0, v[130:131]
	global_load_lds_dwordx4 v[220:221], off
	v_lshl_add_u64 v[220:221], s[60:61], 0, v[130:131]
	s_add_i32 m0, s59, 0x2000
	s_nop 0
	global_load_lds_dwordx4 v[220:221], off
	v_lshl_add_u64 v[220:221], s[28:29], 0, v[128:129]
	s_mov_b32 m0, s39
	s_nop 0
	global_load_lds_dwordx4 v[220:221], off
	s_mov_b32 m0, s42
	s_nop 0
	global_load_lds_dwordx4 v[222:223], off
	s_waitcnt vmcnt(8)
	s_waitcnt lgkmcnt(0)
	s_barrier
; #define PG8_STAGE(bufoff, gbase, voff) do { _Pragma("unroll") for (int _i = 0; _i < 2; ++_i) \
;         __builtin_amdgcn_global_load_lds((const unsigned*)((const char*)(gbase) + (voff)[_i]), (PG8_LAS unsigned*)(lds + (bufoff) + ldsw + _i * 8192), 16, 0, 0); } while (0)
; #define PG8_LDA(dst, b, h) do { _Pragma("unroll") for (int m = 0; m < 4; ++m) _Pragma("unroll") for (int k = 0; k < 2; ++k) dst[m][k] = *(const PG8_LAS bf16x8*)(lds + PG8_SA(b, h) + aoff + m * 2048 + k * 1024); } while (0)
; #define PG8_LDB(dst, b, h) do { _Pragma("unroll") for (int n = 0; n < 2; ++n) _Pragma("unroll") for (int k = 0; k < 2; ++k) dst[n][k] = *(const PG8_LAS bf16x8*)(lds + PG8_SB(b, h) + boff + n * 2048 + k * 1024); } while (0)
; #define PG8_MMA(ai, bj, At, Bt) do { __builtin_amdgcn_s_setprio(1); _Pragma("unroll") for (int m = 0; m < 4; ++m) _Pragma("unroll") for (int n = 0; n < 2; ++n) _Pragma("unroll") for (int k = 0; k < 2; ++k) \
;         acc[ai][bj][m][n] = __builtin_amdgcn_mfma_f32_16x16x32_bf16(Bt[n][k], At[m][k], acc[ai][bj][m][n], 0, 0, 0); __builtin_amdgcn_s_setprio(0); } while (0)
; #define PG8_WAIT_V(n) asm volatile("s_waitcnt vmcnt(" #n ")" ::: "memory")
; #define PG8_WAIT_L(n) asm volatile("s_waitcnt lgkmcnt(" #n ")" ::: "memory")
; #define PG8_BAR __builtin_amdgcn_s_barrier()
; #define PG8_SCHED __builtin_amdgcn_sched_barrier(0)
; template <class Epi, class Sched, bool ALIGN_EPI = false, bool SP2 = false>
; __device__ __forceinline__ void gemm_phase(PG8_LAS unsigned char* lds, const Gemm g, const Sched& S, const Epi& E) {
;     ...
;             PG8_WAIT_V(8); PG8_WAIT_L(0); PG8_BAR; PG8_MMA(1, 0, At, B0); PG8_MMA(1, 1, At, B1); PG8_BAR; PG8_SCHED;
;             PG8_LDB(B0, 1, 0); PG8_LDB(B1, 1, 1); PG8_SCHED; PG8_LDA(At, 1, 0); PG8_STAGE(PG8_SA(0, 1), a2 + hstep, voffA);
;             PG8_WAIT_V(8); PG8_WAIT_L(0); PG8_BAR; PG8_MMA(0, 0, At, B0); PG8_MMA(0, 1, At, B1); PG8_BAR; PG8_SCHED;
	s_setprio 1
	s_waitcnt lgkmcnt(0)
	v_mfma_f32_16x16x32_bf16 v[60:63], v[148:151], v[180:183], v[60:63]
	v_mfma_f32_16x16x32_bf16 v[56:59], v[156:159], v[180:183], v[56:59]
	v_mfma_f32_16x16x32_bf16 v[44:47], v[148:151], v[192:195], v[44:47]
	v_mfma_f32_16x16x32_bf16 v[40:43], v[156:159], v[192:195], v[40:43]
	v_mfma_f32_16x16x32_bf16 v[28:31], v[148:151], v[200:203], v[28:31]
	v_mfma_f32_16x16x32_bf16 v[24:27], v[156:159], v[200:203], v[24:27]
	v_mfma_f32_16x16x32_bf16 v[12:15], v[148:151], v[208:211], v[12:15]
	v_mfma_f32_16x16x32_bf16 v[8:11], v[156:159], v[208:211], v[8:11]
	v_mfma_f32_16x16x32_bf16 v[60:63], v[152:155], v[188:191], v[60:63]
	v_mfma_f32_16x16x32_bf16 v[56:59], v[160:163], v[188:191], v[56:59]
	v_mfma_f32_16x16x32_bf16 v[44:47], v[152:155], v[196:199], v[44:47]
	v_mfma_f32_16x16x32_bf16 v[40:43], v[160:163], v[196:199], v[40:43]
	v_mfma_f32_16x16x32_bf16 v[28:31], v[152:155], v[204:207], v[28:31]
	v_mfma_f32_16x16x32_bf16 v[24:27], v[160:163], v[204:207], v[24:27]
	v_mfma_f32_16x16x32_bf16 v[12:15], v[152:155], v[212:215], v[12:15]
	v_mfma_f32_16x16x32_bf16 v[8:11], v[160:163], v[212:215], v[8:11]
	v_mfma_f32_16x16x32_bf16 v[52:55], v[164:167], v[180:183], v[52:55]
	v_mfma_f32_16x16x32_bf16 v[48:51], v[172:175], v[180:183], v[48:51]
	v_mfma_f32_16x16x32_bf16 v[36:39], v[164:167], v[192:195], v[36:39]
	v_mfma_f32_16x16x32_bf16 v[32:35], v[172:175], v[192:195], v[32:35]
	v_mfma_f32_16x16x32_bf16 v[20:23], v[164:167], v[200:203], v[20:23]
	v_mfma_f32_16x16x32_bf16 v[16:19], v[172:175], v[200:203], v[16:19]
	v_mfma_f32_16x16x32_bf16 v[4:7], v[164:167], v[208:211], v[4:7]
	v_mfma_f32_16x16x32_bf16 v[0:3], v[172:175], v[208:211], v[0:3]
	v_mfma_f32_16x16x32_bf16 v[52:55], v[168:171], v[188:191], v[52:55]
	v_mfma_f32_16x16x32_bf16 v[48:51], v[176:179], v[188:191], v[48:51]
	v_mfma_f32_16x16x32_bf16 v[36:39], v[168:171], v[196:199], v[36:39]
	v_mfma_f32_16x16x32_bf16 v[32:35], v[176:179], v[196:199], v[32:35]
	v_mfma_f32_16x16x32_bf16 v[20:23], v[168:171], v[204:207], v[20:23]
	v_mfma_f32_16x16x32_bf16 v[16:19], v[176:179], v[204:207], v[16:19]
	v_mfma_f32_16x16x32_bf16 v[4:7], v[168:171], v[212:215], v[4:7]
	v_mfma_f32_16x16x32_bf16 v[0:3], v[176:179], v[212:215], v[0:3]
	s_setprio 0
	s_barrier
	s_add_i32 s59, 0, 0x18000
	v_add_u32_e32 v147, s59, v145
	s_add_i32 s60, 0, 0x1c000
	ds_read_b128 v[148:151], v147
	ds_read_b128 v[152:155], v147 offset:1024
	ds_read_b128 v[156:159], v147 offset:2048
	ds_read_b128 v[160:163], v147 offset:3072
	v_add_u32_e32 v147, s60, v145
	ds_read_b128 v[164:167], v147
	ds_read_b128 v[168:171], v147 offset:1024
	ds_read_b128 v[172:175], v147 offset:2048
	ds_read_b128 v[176:179], v147 offset:3072
	s_add_u32 s28, s28, 0x40000
	s_addc_u32 s29, s29, 0
	s_mov_b32 m0, s43
	v_lshl_add_u64 v[224:225], s[28:29], 0, v[128:129]
	ds_read_b128 v[180:183], v146 offset:32768
	ds_read_b128 v[188:191], v146 offset:33792
	ds_read_b128 v[192:195], v146 offset:34816
	ds_read_b128 v[196:199], v146 offset:35840
	ds_read_b128 v[200:203], v146 offset:36864
	ds_read_b128 v[204:207], v146 offset:37888
	ds_read_b128 v[208:211], v146 offset:38912
	ds_read_b128 v[212:215], v146 offset:39936
	global_load_lds_dwordx4 v[224:225], off
	v_lshl_add_u64 v[224:225], s[28:29], 0, v[130:131]
	s_mov_b32 m0, s44
	s_nop 0
	global_load_lds_dwordx4 v[224:225], off
	s_waitcnt vmcnt(8)
	s_waitcnt lgkmcnt(0)
	s_barrier
	s_setprio 1
	s_waitcnt lgkmcnt(0)
	v_mfma_f32_16x16x32_bf16 v[124:127], v[148:151], v[180:183], v[124:127]
	v_mfma_f32_16x16x32_bf16 v[120:123], v[156:159], v[180:183], v[120:123]
	v_mfma_f32_16x16x32_bf16 v[108:111], v[148:151], v[192:195], v[108:111]
	v_mfma_f32_16x16x32_bf16 v[104:107], v[156:159], v[192:195], v[104:107]
	v_mfma_f32_16x16x32_bf16 v[92:95], v[148:151], v[200:203], v[92:95]
	v_mfma_f32_16x16x32_bf16 v[88:91], v[156:159], v[200:203], v[88:91]
	v_mfma_f32_16x16x32_bf16 v[76:79], v[148:151], v[208:211], v[76:79]
	v_mfma_f32_16x16x32_bf16 v[72:75], v[156:159], v[208:211], v[72:75]
	v_mfma_f32_16x16x32_bf16 v[124:127], v[152:155], v[188:191], v[124:127]
	v_mfma_f32_16x16x32_bf16 v[120:123], v[160:163], v[188:191], v[120:123]
	v_mfma_f32_16x16x32_bf16 v[108:111], v[152:155], v[196:199], v[108:111]
	v_mfma_f32_16x16x32_bf16 v[104:107], v[160:163], v[196:199], v[104:107]
	v_mfma_f32_16x16x32_bf16 v[92:95], v[152:155], v[204:207], v[92:95]
	v_mfma_f32_16x16x32_bf16 v[88:91], v[160:163], v[204:207], v[88:91]
	v_mfma_f32_16x16x32_bf16 v[76:79], v[152:155], v[212:215], v[76:79]
	v_mfma_f32_16x16x32_bf16 v[72:75], v[160:163], v[212:215], v[72:75]
	v_mfma_f32_16x16x32_bf16 v[116:119], v[164:167], v[180:183], v[116:119]
	v_mfma_f32_16x16x32_bf16 v[112:115], v[172:175], v[180:183], v[112:115]
	v_mfma_f32_16x16x32_bf16 v[100:103], v[164:167], v[192:195], v[100:103]
	v_mfma_f32_16x16x32_bf16 v[96:99], v[172:175], v[192:195], v[96:99]
	v_mfma_f32_16x16x32_bf16 v[84:87], v[164:167], v[200:203], v[84:87]
	v_mfma_f32_16x16x32_bf16 v[80:83], v[172:175], v[200:203], v[80:83]
	v_mfma_f32_16x16x32_bf16 v[68:71], v[164:167], v[208:211], v[68:71]
	v_mfma_f32_16x16x32_bf16 v[64:67], v[172:175], v[208:211], v[64:67]
	v_mfma_f32_16x16x32_bf16 v[116:119], v[168:171], v[188:191], v[116:119]
	v_mfma_f32_16x16x32_bf16 v[112:115], v[176:179], v[188:191], v[112:115]
	v_mfma_f32_16x16x32_bf16 v[100:103], v[168:171], v[196:199], v[100:103]
	v_mfma_f32_16x16x32_bf16 v[96:99], v[176:179], v[196:199], v[96:99]
	v_mfma_f32_16x16x32_bf16 v[84:87], v[168:171], v[204:207], v[84:87]
	v_mfma_f32_16x16x32_bf16 v[80:83], v[176:179], v[204:207], v[80:83]
	v_mfma_f32_16x16x32_bf16 v[68:71], v[168:171], v[212:215], v[68:71]
	v_mfma_f32_16x16x32_bf16 v[64:67], v[176:179], v[212:215], v[64:67]
	s_setprio 0
	s_barrier
; #define PG8_WAIT_V(n) asm volatile("s_waitcnt vmcnt(" #n ")" ::: "memory")
; #define PG8_BAR __builtin_amdgcn_s_barrier()
; template <class Epi, class Sched, bool ALIGN_EPI = false, bool SP2 = false>
; __device__ __forceinline__ void gemm_phase(PG8_LAS unsigned char* lds, const Gemm g, const Sched& S, const Epi& E) {
;     ...
;             PG8_LDA(At, 1, 1); PG8_STAGE(PG8_SB(1, 0), b3, voffB); PG8_STAGE(PG8_SB(1, 1), b3 + hstep, voffB); PG8_STAGE(PG8_SA(1, 0), a3, voffA);
;             PG8_WAIT_V(8); PG8_WAIT_L(0); PG8_BAR; PG8_MMA(1, 0, At, B0); PG8_MMA(1, 1, At, B1); PG8_BAR; PG8_SCHED;
;             } else {
;             PG8_LDB(B0, 0, 0); PG8_SCHED; PG8_LDA(At, 0, 0); PG8_STAGE(PG8_SA(1, 1), a1 + hstep, voffA);
;             PG8_WAIT_L(8); PG8_BAR; PG8_WAIT_L(0); PG8_MMA(0, 0, At, B0); PG8_BAR; PG8_SCHED;
;             PG8_LDB(B1, 0, 1); PG8_STAGE(PG8_SB(0, 0), b2, voffB);
;             PG8_BAR; PG8_WAIT_L(0); PG8_MMA(0, 1, At, B1); PG8_BAR;
;             PG8_LDA(At, 0, 1); PG8_STAGE(PG8_SA(0, 0), a2, voffA);
;             PG8_BAR; PG8_WAIT_L(0); PG8_MMA(1, 0, At, B0); PG8_BAR; PG8_SCHED;
;             PG8_STAGE(PG8_SB(0, 1), b2 + hstep, voffB);
;             PG8_WAIT_V(6); PG8_BAR; PG8_MMA(1, 1, At, B1); PG8_BAR;
;             PG8_LDB(B0, 1, 0); PG8_SCHED; PG8_LDA(At, 1, 0); PG8_STAGE(PG8_SA(0, 1), a2 + hstep, voffA);
;             PG8_WAIT_L(8); PG8_BAR; PG8_WAIT_L(0); PG8_MMA(0, 0, At, B0); PG8_BAR; PG8_SCHED;
;             PG8_LDB(B1, 1, 1); PG8_STAGE(PG8_SB(1, 0), b3, voffB);
;             PG8_BAR; PG8_WAIT_L(0); PG8_MMA(0, 1, At, B1); PG8_BAR;
;             PG8_LDA(At, 1, 1); PG8_STAGE(PG8_SA(1, 0), a3, voffA);
;             PG8_BAR; PG8_WAIT_L(0); PG8_MMA(1, 0, At, B0); PG8_BAR; PG8_SCHED;
;             PG8_STAGE(PG8_SB(1, 1), b3 + hstep, voffB);
;             PG8_WAIT_V(6); PG8_BAR; PG8_MMA(1, 1, At, B1); PG8_BAR;
;             }
;         }
;         if constexpr (ALIGN_EPI) { if (wr == 0) PG8_BAR; }
;         if constexpr (!Epi::AFTER_DRAIN) { E(acc, cur, wr, wc, fr, fq); S.done(cur); }
;         if (!has_next) break;
; #pragma unroll
;         for (int a = 0; a < 2; ++a)
; #pragma unroll
;             for (int b = 0; b < 2; ++b)
; #pragma unroll
;                 for (int m = 0; m < 4; ++m)
; #pragma unroll
;                     for (int n = 0; n < 2; ++n) acc[a][b][m][n] = (f32x4){0.f, 0.f, 0.f, 0.f};
;         cur = nxt; cA = nA; cB = nB; ++ui;
	s_add_i32 s28, s59, s38
	v_lshl_add_u64 v[184:185], v[184:185], 0, s[12:13]
	s_mov_b32 m0, s28
	ds_read_b128 v[180:183], v146 offset:49152
	ds_read_b128 v[188:191], v146 offset:50176
	ds_read_b128 v[192:195], v146 offset:51200
	ds_read_b128 v[196:199], v146 offset:52224
	ds_read_b128 v[200:203], v146 offset:53248
	ds_read_b128 v[204:207], v146 offset:54272
	ds_read_b128 v[208:211], v146 offset:55296
	ds_read_b128 v[212:215], v146 offset:56320
	global_load_lds_dwordx4 v[184:185], off
	s_add_i32 m0, s28, 0x2000
	s_add_u32 s26, s26, 0x40080
	v_lshl_add_u64 v[184:185], v[218:219], 0, s[12:13]
	s_addc_u32 s27, s27, 0
	s_add_i32 s28, s60, s38
	global_load_lds_dwordx4 v[184:185], off
	v_lshl_add_u64 v[184:185], s[26:27], 0, v[128:129]
	s_mov_b32 m0, s28
	s_nop 0
	global_load_lds_dwordx4 v[184:185], off
	v_lshl_add_u64 v[184:185], s[26:27], 0, v[130:131]
	s_add_i32 m0, s28, 0x2000
	s_nop 0
	global_load_lds_dwordx4 v[184:185], off
	v_lshl_add_u64 v[184:185], v[220:221], 0, s[12:13]
	s_mov_b32 m0, s46
	s_nop 0
	global_load_lds_dwordx4 v[184:185], off
	v_lshl_add_u64 v[184:185], v[222:223], 0, s[12:13]
	s_mov_b32 m0, s47
	s_nop 0
	global_load_lds_dwordx4 v[184:185], off
	s_waitcnt vmcnt(8)
	s_waitcnt lgkmcnt(0)
	s_barrier
	s_setprio 1
	s_waitcnt lgkmcnt(0)
	v_mfma_f32_16x16x32_bf16 v[60:63], v[148:151], v[180:183], v[60:63]
	v_mfma_f32_16x16x32_bf16 v[56:59], v[156:159], v[180:183], v[56:59]
	v_mfma_f32_16x16x32_bf16 v[44:47], v[148:151], v[192:195], v[44:47]
	v_mfma_f32_16x16x32_bf16 v[40:43], v[156:159], v[192:195], v[40:43]
	v_mfma_f32_16x16x32_bf16 v[28:31], v[148:151], v[200:203], v[28:31]
	v_mfma_f32_16x16x32_bf16 v[24:27], v[156:159], v[200:203], v[24:27]
	v_mfma_f32_16x16x32_bf16 v[12:15], v[148:151], v[208:211], v[12:15]
	v_mfma_f32_16x16x32_bf16 v[8:11], v[156:159], v[208:211], v[8:11]
	v_mfma_f32_16x16x32_bf16 v[60:63], v[152:155], v[188:191], v[60:63]
	v_mfma_f32_16x16x32_bf16 v[56:59], v[160:163], v[188:191], v[56:59]
	v_mfma_f32_16x16x32_bf16 v[44:47], v[152:155], v[196:199], v[44:47]
	v_mfma_f32_16x16x32_bf16 v[40:43], v[160:163], v[196:199], v[40:43]
	v_mfma_f32_16x16x32_bf16 v[28:31], v[152:155], v[204:207], v[28:31]
	v_mfma_f32_16x16x32_bf16 v[24:27], v[160:163], v[204:207], v[24:27]
	v_mfma_f32_16x16x32_bf16 v[12:15], v[152:155], v[212:215], v[12:15]
	v_mfma_f32_16x16x32_bf16 v[8:11], v[160:163], v[212:215], v[8:11]
	v_mfma_f32_16x16x32_bf16 v[52:55], v[164:167], v[180:183], v[52:55]
	v_mfma_f32_16x16x32_bf16 v[48:51], v[172:175], v[180:183], v[48:51]
	v_mfma_f32_16x16x32_bf16 v[36:39], v[164:167], v[192:195], v[36:39]
	v_mfma_f32_16x16x32_bf16 v[32:35], v[172:175], v[192:195], v[32:35]
	v_mfma_f32_16x16x32_bf16 v[20:23], v[164:167], v[200:203], v[20:23]
	v_mfma_f32_16x16x32_bf16 v[16:19], v[172:175], v[200:203], v[16:19]
	v_mfma_f32_16x16x32_bf16 v[4:7], v[164:167], v[208:211], v[4:7]
	v_mfma_f32_16x16x32_bf16 v[0:3], v[172:175], v[208:211], v[0:3]
	v_mfma_f32_16x16x32_bf16 v[52:55], v[168:171], v[188:191], v[52:55]
	v_mfma_f32_16x16x32_bf16 v[48:51], v[176:179], v[188:191], v[48:51]
	v_mfma_f32_16x16x32_bf16 v[36:39], v[168:171], v[196:199], v[36:39]
	v_mfma_f32_16x16x32_bf16 v[32:35], v[176:179], v[196:199], v[32:35]
	v_mfma_f32_16x16x32_bf16 v[20:23], v[168:171], v[204:207], v[20:23]
	v_mfma_f32_16x16x32_bf16 v[16:19], v[176:179], v[204:207], v[16:19]
	v_mfma_f32_16x16x32_bf16 v[4:7], v[168:171], v[212:215], v[4:7]
	v_mfma_f32_16x16x32_bf16 v[0:3], v[176:179], v[212:215], v[0:3]
	s_setprio 0
	s_barrier
	s_add_i32 s58, s58, 2
	s_add_u32 s24, s24, 0x100
	s_addc_u32 s25, s25, 0
	s_cmp_gt_u32 s58, 13
	s_cbranch_scc0 .LBB0_809
	s_add_u32 s24, s21, 0xffffff00
	s_addc_u32 s25, s51, -1
	s_andn2_b64 vcc, exec, s[2:3]
	s_cbranch_vccnz .LBB0_812
	v_mov_b32_e32 v0, 0
	s_mov_b32 s4, s14
	s_mov_b32 s8, s16
	s_mov_b64 s[10:11], s[22:23]
	s_mov_b32 s48, s20
	v_mov_b32_e32 v1, v0
	v_mov_b32_e32 v2, v0
	v_mov_b32_e32 v3, v0
	v_mov_b32_e32 v4, v0
	v_mov_b32_e32 v5, v0
	v_mov_b32_e32 v6, v0
	v_mov_b32_e32 v7, v0
	v_mov_b32_e32 v16, v0
	v_mov_b32_e32 v17, v0
	v_mov_b32_e32 v18, v0
	v_mov_b32_e32 v19, v0
	v_mov_b32_e32 v20, v0
	v_mov_b32_e32 v21, v0
	v_mov_b32_e32 v22, v0
	v_mov_b32_e32 v23, v0
	v_mov_b32_e32 v32, v0
	v_mov_b32_e32 v33, v0
	v_mov_b32_e32 v34, v0
	v_mov_b32_e32 v35, v0
	v_mov_b32_e32 v36, v0
	v_mov_b32_e32 v37, v0
	v_mov_b32_e32 v38, v0
	v_mov_b32_e32 v39, v0
	v_mov_b32_e32 v48, v0
	v_mov_b32_e32 v49, v0
	v_mov_b32_e32 v50, v0
	v_mov_b32_e32 v51, v0
	v_mov_b32_e32 v52, v0
	v_mov_b32_e32 v53, v0
	v_mov_b32_e32 v54, v0
	v_mov_b32_e32 v55, v0
	v_mov_b32_e32 v8, v0
	v_mov_b32_e32 v9, v0
	v_mov_b32_e32 v10, v0
	v_mov_b32_e32 v11, v0
	v_mov_b32_e32 v12, v0
	v_mov_b32_e32 v13, v0
	v_mov_b32_e32 v14, v0
	v_mov_b32_e32 v15, v0
	v_mov_b32_e32 v24, v0
	v_mov_b32_e32 v25, v0
	v_mov_b32_e32 v26, v0
	v_mov_b32_e32 v27, v0
	v_mov_b32_e32 v28, v0
	v_mov_b32_e32 v29, v0
	v_mov_b32_e32 v30, v0
	v_mov_b32_e32 v31, v0
	v_mov_b32_e32 v40, v0
	v_mov_b32_e32 v41, v0
	v_mov_b32_e32 v42, v0
	v_mov_b32_e32 v43, v0
	v_mov_b32_e32 v44, v0
	v_mov_b32_e32 v45, v0
	v_mov_b32_e32 v46, v0
	v_mov_b32_e32 v47, v0
	v_mov_b32_e32 v56, v0
	v_mov_b32_e32 v57, v0
	v_mov_b32_e32 v58, v0
	v_mov_b32_e32 v59, v0
	v_mov_b32_e32 v60, v0
	v_mov_b32_e32 v61, v0
	v_mov_b32_e32 v62, v0
	v_mov_b32_e32 v63, v0
	v_mov_b32_e32 v64, v0
	v_mov_b32_e32 v65, v0
	v_mov_b32_e32 v66, v0
	v_mov_b32_e32 v67, v0
	v_mov_b32_e32 v68, v0
	v_mov_b32_e32 v69, v0
	v_mov_b32_e32 v70, v0
	v_mov_b32_e32 v71, v0
	v_mov_b32_e32 v80, v0
	v_mov_b32_e32 v81, v0
	v_mov_b32_e32 v82, v0
	v_mov_b32_e32 v83, v0
	v_mov_b32_e32 v84, v0
	v_mov_b32_e32 v85, v0
	v_mov_b32_e32 v86, v0
	v_mov_b32_e32 v87, v0
	v_mov_b32_e32 v96, v0
	v_mov_b32_e32 v97, v0
	v_mov_b32_e32 v98, v0
	v_mov_b32_e32 v99, v0
	v_mov_b32_e32 v100, v0
	v_mov_b32_e32 v101, v0
	v_mov_b32_e32 v102, v0
	v_mov_b32_e32 v103, v0
	v_mov_b32_e32 v112, v0
	v_mov_b32_e32 v113, v0
	v_mov_b32_e32 v114, v0
	v_mov_b32_e32 v115, v0
	v_mov_b32_e32 v116, v0
	v_mov_b32_e32 v117, v0
	v_mov_b32_e32 v118, v0
	v_mov_b32_e32 v119, v0
	v_mov_b32_e32 v72, v0
	v_mov_b32_e32 v73, v0
	v_mov_b32_e32 v74, v0
	v_mov_b32_e32 v75, v0
	v_mov_b32_e32 v76, v0
	v_mov_b32_e32 v77, v0
	v_mov_b32_e32 v78, v0
	v_mov_b32_e32 v79, v0
	v_mov_b32_e32 v88, v0
	v_mov_b32_e32 v89, v0
	v_mov_b32_e32 v90, v0
	v_mov_b32_e32 v91, v0
	v_mov_b32_e32 v92, v0
	v_mov_b32_e32 v93, v0
	v_mov_b32_e32 v94, v0
	v_mov_b32_e32 v95, v0
	v_mov_b32_e32 v104, v0
	v_mov_b32_e32 v105, v0
	v_mov_b32_e32 v106, v0
	v_mov_b32_e32 v107, v0
	v_mov_b32_e32 v108, v0
	v_mov_b32_e32 v109, v0
	v_mov_b32_e32 v110, v0
	v_mov_b32_e32 v111, v0
	v_mov_b32_e32 v120, v0
	v_mov_b32_e32 v121, v0
	v_mov_b32_e32 v122, v0
	v_mov_b32_e32 v123, v0
	v_mov_b32_e32 v124, v0
	v_mov_b32_e32 v125, v0
	v_mov_b32_e32 v126, v0
	v_mov_b32_e32 v127, v0
	s_andn2_b64 vcc, exec, s[0:1]
	s_cbranch_vccnz .LBB0_813
	s_branch .LBB0_814
